# v24: v11 + score-reduction pair/group transposing steps done with bank-masked DPP adds (2 instructions instead of 2 selects + 1 add)
# speedup vs baseline: 1.0027x; 1.0027x over previous
; #define LAS __attribute__((address_space(3)))
; DI void attn_sample_item(const Params& p, int item, ldsp lds, int tid_) {
;     ...
;   const int b = item >> 2, h = item & 3;
;   bf16_t* qx = (bf16_t*)(p.ws + B_QX);
;   const float* ck = p.in[6] + ((size_t)b * 256 * 4 + h) * 256;
;   const float* cv = p.in[7] + ((size_t)b * 256 * 4 + h) * 256;
;   LAS float* SC = (LAS float*)lds;
;   LAS float* PART = (LAS float*)(lds + 4096);
;   float q[4][4];
; #pragma unroll
;   for (int t = 0; t < 4; ++t) { f32x4 a = {0.f, 0.f, 0.f, 0.f}; const float* pp = (const float*)(p.ws + B_PART) + (size_t)(b * 4 + t) * 1024 + h * 256 + lane * 4;
; #pragma unroll
;     for (int kp = 0; kp < 4; ++kp) a += *(const f32x4*)(pp + (size_t)kp * 512 * 1024);
;     q[t][0] = a[0] * 0.0625f; q[t][1] = a[1] * 0.0625f; q[t][2] = a[2] * 0.0625f; q[t][3] = a[3] * 0.0625f; }
;   const bool b0 = lane & 1, b1 = lane & 2;
;   f32x4 kvA[16], kvB[16];
; #pragma unroll
;   for (int j = 0; j < 16; ++j) kvA[j] = __builtin_nontemporal_load((const f32x4*)(ck + (size_t)(wid * 32 + j) * 1024 + lane * 4));
; #pragma unroll
;   for (int j = 0; j < 16; ++j) kvB[j] = __builtin_nontemporal_load((const f32x4*)(ck + (size_t)(wid * 32 + 16 + j) * 1024 + lane * 4));
.LBB0_1604:
	s_ashr_i32 s4, s40, 2
	s_ashr_i32 s5, s4, 31
	s_lshl_b64 s[4:5], s[4:5], 18
	s_and_b32 s26, s0, 0x300
	v_mov_b32_e32 v222, v212
	s_or_b32 s4, s4, s26
	s_and_b32 s28, s40, -4
	s_lshl_b32 s6, s26, 2
	s_add_u32 s6, s36, s6
	v_and_b32_e32 v223, 63, v222
	s_addc_u32 s7, s37, 0
	v_lshlrev_b32_e32 v144, 4, v223
	s_ashr_i32 s29, s28, 31
	v_lshl_add_u64 v[48:49], s[6:7], 0, v[144:145]
	s_lshl_b64 s[6:7], s[28:29], 12
	v_lshl_add_u64 v[8:9], v[48:49], 0, s[6:7]
	v_add_co_u32_e32 v4, vcc, s3, v8
	s_or_b32 s6, s28, 1
	s_nop 0
	v_addc_co_u32_e32 v5, vcc, 0, v9, vcc
	v_add_co_u32_e32 v10, vcc, s33, v8
	s_ashr_i32 s7, s6, 31
	s_nop 0
	v_addc_co_u32_e32 v11, vcc, 0, v9, vcc
	v_add_co_u32_e32 v12, vcc, s38, v8
	s_lshl_b64 s[6:7], s[6:7], 12
	s_nop 0
	v_addc_co_u32_e32 v13, vcc, 0, v9, vcc
	v_lshl_add_u64 v[24:25], v[48:49], 0, s[6:7]
	v_add_co_u32_e32 v20, vcc, s3, v24
	s_or_b32 s6, s28, 2
	s_nop 0
	v_addc_co_u32_e32 v21, vcc, 0, v25, vcc
	v_add_co_u32_e32 v26, vcc, s33, v24
	s_ashr_i32 s7, s6, 31
	s_nop 0
	v_addc_co_u32_e32 v27, vcc, 0, v25, vcc
	v_add_co_u32_e32 v28, vcc, s38, v24
	s_lshl_b64 s[6:7], s[6:7], 12
	global_load_dwordx4 v[0:3], v[8:9], off
	s_nop 0
	global_load_dwordx4 v[4:7], v[4:5], off
	v_addc_co_u32_e32 v29, vcc, 0, v25, vcc
	v_lshl_add_u64 v[44:45], v[48:49], 0, s[6:7]
	global_load_dwordx4 v[8:11], v[10:11], off
	s_nop 0
	global_load_dwordx4 v[12:15], v[12:13], off
	s_nop 0
	global_load_dwordx4 v[16:19], v[24:25], off
	s_nop 0
	global_load_dwordx4 v[20:23], v[20:21], off
	v_add_co_u32_e32 v36, vcc, s3, v44
	global_load_dwordx4 v[24:27], v[26:27], off
	s_nop 0
	global_load_dwordx4 v[28:31], v[28:29], off
	v_addc_co_u32_e32 v37, vcc, 0, v45, vcc
	v_add_co_u32_e32 v40, vcc, s33, v44
	global_load_dwordx4 v[32:35], v[44:45], off
	s_nop 0
	global_load_dwordx4 v[36:39], v[36:37], off
	v_addc_co_u32_e32 v41, vcc, 0, v45, vcc
	v_add_co_u32_e32 v44, vcc, s38, v44
	global_load_dwordx4 v[40:43], v[40:41], off
	s_nop 0
	v_addc_co_u32_e32 v45, vcc, 0, v45, vcc
	global_load_dwordx4 v[44:47], v[44:45], off
	s_or_b32 s6, s40, 3
	s_ashr_i32 s7, s6, 31
	s_lshl_b64 s[6:7], s[6:7], 12
	s_lshl_b64 s[30:31], s[4:5], 2
	s_add_u32 s4, s12, s30
	s_addc_u32 s5, s13, s31
	s_waitcnt vmcnt(11)
	v_pk_add_f32 v[2:3], v[2:3], 0 op_sel_hi:[1,0]
	v_pk_add_f32 v[0:1], v[0:1], 0 op_sel_hi:[1,0]
	s_waitcnt vmcnt(10)
	v_pk_add_f32 v[2:3], v[2:3], v[6:7]
	v_pk_add_f32 v[0:1], v[0:1], v[4:5]
	s_waitcnt vmcnt(9)
	v_pk_add_f32 v[2:3], v[2:3], v[10:11]
	s_waitcnt vmcnt(7)
	v_pk_add_f32 v[4:5], v[18:19], 0 op_sel_hi:[1,0]
	v_pk_add_f32 v[6:7], v[16:17], 0 op_sel_hi:[1,0]
	v_pk_add_f32 v[0:1], v[0:1], v[8:9]
	s_waitcnt vmcnt(6)
	v_pk_add_f32 v[4:5], v[4:5], v[22:23]
	v_pk_add_f32 v[6:7], v[6:7], v[20:21]
	v_pk_add_f32 v[2:3], v[2:3], v[14:15]
	v_pk_add_f32 v[0:1], v[0:1], v[12:13]
	s_waitcnt vmcnt(5)
	v_pk_add_f32 v[4:5], v[4:5], v[26:27]
	v_pk_add_f32 v[6:7], v[6:7], v[24:25]
	v_mul_f32_e32 v228, 0x3d800000, v0
	v_mul_f32_e32 v231, 0x3d800000, v1
	v_mul_f32_e32 v229, 0x3d800000, v2
	v_mul_f32_e32 v225, 0x3d800000, v3
	s_waitcnt vmcnt(4)
	v_pk_add_f32 v[0:1], v[4:5], v[30:31]
	v_pk_add_f32 v[2:3], v[6:7], v[28:29]
	v_mul_f32_e32 v227, 0x3d800000, v0
	v_mul_f32_e32 v226, 0x3d800000, v2
	v_mul_f32_e32 v230, 0x3d800000, v3
	v_mul_f32_e32 v224, 0x3d800000, v1
	s_waitcnt vmcnt(3)
	v_pk_add_f32 v[0:1], v[34:35], 0 op_sel_hi:[1,0]
	v_pk_add_f32 v[2:3], v[32:33], 0 op_sel_hi:[1,0]
	s_waitcnt vmcnt(2)
	v_pk_add_f32 v[0:1], v[0:1], v[38:39]
	v_pk_add_f32 v[2:3], v[2:3], v[36:37]
	s_waitcnt vmcnt(1)
	v_pk_add_f32 v[0:1], v[0:1], v[42:43]
	v_pk_add_f32 v[2:3], v[2:3], v[40:41]
	s_waitcnt vmcnt(0)
	v_pk_add_f32 v[210:211], v[0:1], v[46:47]
	v_pk_add_f32 v[0:1], v[2:3], v[44:45]
	v_mul_f32_e32 v233, 0x3d800000, v210
	v_mul_f32_e32 v232, 0x3d800000, v0
	v_mul_f32_e32 v234, 0x3d800000, v1
	v_lshl_add_u64 v[0:1], v[48:49], 0, s[6:7]
	v_add_co_u32_e32 v2, vcc, s3, v0
	v_ashrrev_i32_e32 v210, 6, v222
	s_nop 0
	v_addc_co_u32_e32 v3, vcc, 0, v1, vcc
	global_load_dwordx4 v[128:131], v[0:1], off
	global_load_dwordx4 v[132:135], v[2:3], off
	v_add_co_u32_e32 v2, vcc, s33, v0
	v_mul_f32_e32 v211, 0x3d800000, v211
	s_nop 0
	v_addc_co_u32_e32 v3, vcc, 0, v1, vcc
	v_add_co_u32_e32 v0, vcc, s38, v0
	v_cmp_lt_i32_e64 s[6:7], v218, v216
	s_nop 0
	v_addc_co_u32_e32 v1, vcc, 0, v1, vcc
	global_load_dwordx4 v[136:139], v[2:3], off
	global_load_dwordx4 v[140:143], v[0:1], off
	v_lshlrev_b32_e32 v0, 5, v210
	v_ashrrev_i32_e32 v1, 31, v0
	v_or_b32_e32 v6, 1, v0
	v_lshl_add_u64 v[2:3], s[4:5], 0, v[144:145]
	v_lshlrev_b64 v[162:163], 12, v[0:1]
	v_ashrrev_i32_e32 v7, 31, v6
	v_lshl_add_u64 v[4:5], v[2:3], 0, v[162:163]
	v_lshlrev_b64 v[166:167], 12, v[6:7]
	v_lshl_add_u64 v[6:7], v[2:3], 0, v[166:167]
	global_load_dwordx4 v[124:127], v[4:5], off nt
	global_load_dwordx4 v[120:123], v[6:7], off nt
	v_or_b32_e32 v4, 2, v0
	v_ashrrev_i32_e32 v5, 31, v4
	v_or_b32_e32 v6, 3, v0
	v_lshlrev_b64 v[168:169], 12, v[4:5]
	v_ashrrev_i32_e32 v7, 31, v6
	v_lshl_add_u64 v[4:5], v[2:3], 0, v[168:169]
	v_lshlrev_b64 v[172:173], 12, v[6:7]
	v_lshl_add_u64 v[6:7], v[2:3], 0, v[172:173]
	global_load_dwordx4 v[116:119], v[4:5], off nt
	global_load_dwordx4 v[112:115], v[6:7], off nt
	v_or_b32_e32 v4, 4, v0
	v_ashrrev_i32_e32 v5, 31, v4
	v_or_b32_e32 v6, 5, v0
	v_lshlrev_b64 v[176:177], 12, v[4:5]
	v_ashrrev_i32_e32 v7, 31, v6
	v_lshl_add_u64 v[4:5], v[2:3], 0, v[176:177]
	v_lshlrev_b64 v[180:181], 12, v[6:7]
	v_lshl_add_u64 v[6:7], v[2:3], 0, v[180:181]
	global_load_dwordx4 v[108:111], v[4:5], off nt
	global_load_dwordx4 v[104:107], v[6:7], off nt
	v_or_b32_e32 v4, 6, v0
	v_ashrrev_i32_e32 v5, 31, v4
	v_or_b32_e32 v6, 7, v0
; DI void attn_sample_item(const Params& p, int item, ldsp lds, int tid_) {
;     ...
;   for (int t = 0; t < 4; ++t) { f32x4 a = {0.f, 0.f, 0.f, 0.f}; const float* pp = (const float*)(p.ws + B_PART) + (size_t)(b * 4 + t) * 1024 + h * 256 + lane * 4;
; #pragma unroll
;     for (int kp = 0; kp < 4; ++kp) a += *(const f32x4*)(pp + (size_t)kp * 512 * 1024);
;     q[t][0] = a[0] * 0.0625f; q[t][1] = a[1] * 0.0625f; q[t][2] = a[2] * 0.0625f; q[t][3] = a[3] * 0.0625f; }
;   const bool b0 = lane & 1, b1 = lane & 2;
;   f32x4 kvA[16], kvB[16];
; #pragma unroll
;   for (int j = 0; j < 16; ++j) kvA[j] = __builtin_nontemporal_load((const f32x4*)(ck + (size_t)(wid * 32 + j) * 1024 + lane * 4));
; #pragma unroll
;   for (int j = 0; j < 16; ++j) kvB[j] = __builtin_nontemporal_load((const f32x4*)(ck + (size_t)(wid * 32 + 16 + j) * 1024 + lane * 4));
	v_lshlrev_b64 v[182:183], 12, v[4:5]
	v_ashrrev_i32_e32 v7, 31, v6
	v_lshl_add_u64 v[4:5], v[2:3], 0, v[182:183]
	v_lshlrev_b64 v[186:187], 12, v[6:7]
	v_lshl_add_u64 v[6:7], v[2:3], 0, v[186:187]
	global_load_dwordx4 v[100:103], v[4:5], off nt
	global_load_dwordx4 v[96:99], v[6:7], off nt
	v_or_b32_e32 v4, 8, v0
	v_ashrrev_i32_e32 v5, 31, v4
	v_or_b32_e32 v6, 9, v0
	v_lshlrev_b64 v[190:191], 12, v[4:5]
	v_ashrrev_i32_e32 v7, 31, v6
	v_lshl_add_u64 v[4:5], v[2:3], 0, v[190:191]
	v_lshlrev_b64 v[194:195], 12, v[6:7]
	v_lshl_add_u64 v[6:7], v[2:3], 0, v[194:195]
	global_load_dwordx4 v[92:95], v[4:5], off nt
	global_load_dwordx4 v[88:91], v[6:7], off nt
	v_or_b32_e32 v4, 10, v0
	v_ashrrev_i32_e32 v5, 31, v4
	v_or_b32_e32 v6, 11, v0
	v_lshlrev_b64 v[198:199], 12, v[4:5]
	v_ashrrev_i32_e32 v7, 31, v6
	v_lshl_add_u64 v[4:5], v[2:3], 0, v[198:199]
	v_lshlrev_b64 v[200:201], 12, v[6:7]
	v_lshl_add_u64 v[6:7], v[2:3], 0, v[200:201]
	global_load_dwordx4 v[84:87], v[4:5], off nt
	global_load_dwordx4 v[80:83], v[6:7], off nt
	v_or_b32_e32 v4, 12, v0
	v_ashrrev_i32_e32 v5, 31, v4
	v_or_b32_e32 v6, 13, v0
	v_lshlrev_b64 v[202:203], 12, v[4:5]
	v_ashrrev_i32_e32 v7, 31, v6
	v_lshl_add_u64 v[4:5], v[2:3], 0, v[202:203]
	v_lshlrev_b64 v[204:205], 12, v[6:7]
	v_lshl_add_u64 v[6:7], v[2:3], 0, v[204:205]
	global_load_dwordx4 v[76:79], v[4:5], off nt
	global_load_dwordx4 v[72:75], v[6:7], off nt
	v_or_b32_e32 v4, 14, v0
	v_ashrrev_i32_e32 v5, 31, v4
	v_or_b32_e32 v6, 15, v0
	v_lshlrev_b64 v[206:207], 12, v[4:5]
	v_ashrrev_i32_e32 v7, 31, v6
	v_lshl_add_u64 v[4:5], v[2:3], 0, v[206:207]
	v_lshlrev_b64 v[208:209], 12, v[6:7]
	v_lshl_add_u64 v[6:7], v[2:3], 0, v[208:209]
	global_load_dwordx4 v[68:71], v[4:5], off nt
	global_load_dwordx4 v[64:67], v[6:7], off nt
	v_or_b32_e32 v4, 16, v0
	v_ashrrev_i32_e32 v5, 31, v4
	v_or_b32_e32 v6, 17, v0
	v_lshlrev_b64 v[146:147], 12, v[4:5]
	v_ashrrev_i32_e32 v7, 31, v6
	v_lshl_add_u64 v[4:5], v[2:3], 0, v[146:147]
	v_lshlrev_b64 v[148:149], 12, v[6:7]
	v_lshl_add_u64 v[6:7], v[2:3], 0, v[148:149]
	global_load_dwordx4 v[60:63], v[4:5], off nt
	global_load_dwordx4 v[56:59], v[6:7], off nt
	v_or_b32_e32 v4, 18, v0
	v_ashrrev_i32_e32 v5, 31, v4
	v_or_b32_e32 v6, 19, v0
	v_lshlrev_b64 v[150:151], 12, v[4:5]
	v_ashrrev_i32_e32 v7, 31, v6
	v_lshl_add_u64 v[4:5], v[2:3], 0, v[150:151]
	v_lshlrev_b64 v[152:153], 12, v[6:7]
	v_lshl_add_u64 v[6:7], v[2:3], 0, v[152:153]
	global_load_dwordx4 v[52:55], v[4:5], off nt
	global_load_dwordx4 v[48:51], v[6:7], off nt
	v_or_b32_e32 v4, 20, v0
	v_ashrrev_i32_e32 v5, 31, v4
	v_or_b32_e32 v6, 21, v0
	v_lshlrev_b64 v[154:155], 12, v[4:5]
	v_ashrrev_i32_e32 v7, 31, v6
	v_lshl_add_u64 v[4:5], v[2:3], 0, v[154:155]
	v_lshlrev_b64 v[156:157], 12, v[6:7]
	v_lshl_add_u64 v[6:7], v[2:3], 0, v[156:157]
	global_load_dwordx4 v[44:47], v[4:5], off nt
	global_load_dwordx4 v[40:43], v[6:7], off nt
	v_or_b32_e32 v4, 22, v0
	v_ashrrev_i32_e32 v5, 31, v4
	v_or_b32_e32 v6, 23, v0
	v_lshlrev_b64 v[158:159], 12, v[4:5]
	v_ashrrev_i32_e32 v7, 31, v6
	v_lshl_add_u64 v[4:5], v[2:3], 0, v[158:159]
	v_lshlrev_b64 v[160:161], 12, v[6:7]
	v_lshl_add_u64 v[6:7], v[2:3], 0, v[160:161]
	global_load_dwordx4 v[36:39], v[4:5], off nt
	global_load_dwordx4 v[32:35], v[6:7], off nt
	v_or_b32_e32 v4, 24, v0
	v_ashrrev_i32_e32 v5, 31, v4
	v_or_b32_e32 v6, 25, v0
	v_lshlrev_b64 v[164:165], 12, v[4:5]
	v_ashrrev_i32_e32 v7, 31, v6
	v_lshl_add_u64 v[4:5], v[2:3], 0, v[164:165]
	v_lshlrev_b64 v[170:171], 12, v[6:7]
	v_lshl_add_u64 v[6:7], v[2:3], 0, v[170:171]
	global_load_dwordx4 v[28:31], v[4:5], off nt
	global_load_dwordx4 v[24:27], v[6:7], off nt
	v_or_b32_e32 v4, 26, v0
	v_ashrrev_i32_e32 v5, 31, v4
	v_or_b32_e32 v6, 27, v0
	v_lshlrev_b64 v[174:175], 12, v[4:5]
	v_ashrrev_i32_e32 v7, 31, v6
	v_lshl_add_u64 v[4:5], v[2:3], 0, v[174:175]
	v_lshlrev_b64 v[178:179], 12, v[6:7]
	v_lshl_add_u64 v[6:7], v[2:3], 0, v[178:179]
	global_load_dwordx4 v[20:23], v[4:5], off nt
	global_load_dwordx4 v[16:19], v[6:7], off nt
	v_or_b32_e32 v4, 28, v0
	v_ashrrev_i32_e32 v5, 31, v4
	v_or_b32_e32 v6, 29, v0
	v_lshlrev_b64 v[184:185], 12, v[4:5]
	v_ashrrev_i32_e32 v7, 31, v6
	v_lshl_add_u64 v[4:5], v[2:3], 0, v[184:185]
	v_lshlrev_b64 v[188:189], 12, v[6:7]
	v_lshl_add_u64 v[6:7], v[2:3], 0, v[188:189]
	global_load_dwordx4 v[12:15], v[4:5], off nt
	global_load_dwordx4 v[8:11], v[6:7], off nt
	v_or_b32_e32 v4, 30, v0
	v_or_b32_e32 v0, 31, v0
	v_ashrrev_i32_e32 v5, 31, v4
	v_ashrrev_i32_e32 v1, 31, v0
	v_lshlrev_b64 v[192:193], 12, v[4:5]
	v_lshlrev_b64 v[196:197], 12, v[0:1]
	v_lshl_add_u64 v[4:5], v[2:3], 0, v[192:193]
	v_lshl_add_u64 v[0:1], v[2:3], 0, v[196:197]
	global_load_dwordx4 v[4:7], v[4:5], off nt
	s_nop 0
	global_load_dwordx4 v[0:3], v[0:1], off nt
	s_waitcnt vmcnt(35)
	v_pk_add_f32 v[128:129], v[128:129], 0 op_sel_hi:[1,0]
	v_pk_add_f32 v[130:131], v[130:131], 0 op_sel_hi:[1,0]
	s_waitcnt vmcnt(34)
	v_pk_add_f32 v[128:129], v[128:129], v[132:133]
	v_pk_add_f32 v[130:131], v[130:131], v[134:135]
	s_waitcnt vmcnt(33)
	v_pk_add_f32 v[128:129], v[128:129], v[136:137]
	v_pk_add_f32 v[130:131], v[130:131], v[138:139]
	s_waitcnt vmcnt(32)
; DI void attn_sample_item(const Params& p, int item, ldsp lds, int tid_) {
;     ...
;     for (int kp = 0; kp < 4; ++kp) a += *(const f32x4*)(pp + (size_t)kp * 512 * 1024);
;     q[t][0] = a[0] * 0.0625f; q[t][1] = a[1] * 0.0625f; q[t][2] = a[2] * 0.0625f; q[t][3] = a[3] * 0.0625f; }
;   const bool b0 = lane & 1, b1 = lane & 2;
;   f32x4 kvA[16], kvB[16];
; #pragma unroll
;   for (int j = 0; j < 16; ++j) kvA[j] = __builtin_nontemporal_load((const f32x4*)(ck + (size_t)(wid * 32 + j) * 1024 + lane * 4));
; #pragma unroll
;   for (int j = 0; j < 16; ++j) kvB[j] = __builtin_nontemporal_load((const f32x4*)(ck + (size_t)(wid * 32 + 16 + j) * 1024 + lane * 4));
;     ...
;   SC_SCORE(kvA, 0)
;   SC_SCORE(kvB, 1)
	v_pk_add_f32 v[128:129], v[128:129], v[140:141]
	v_pk_add_f32 v[130:131], v[130:131], v[142:143]
	v_mul_f32_e32 v138, 0x3d800000, v129
	v_mul_f32_e32 v135, 0x3d800000, v128
	v_mul_f32_e32 v134, 0x3d800000, v131
	v_mul_f32_e32 v137, 0x3d800000, v130
	v_lshlrev_b32_e32 v128, 2, v215
	v_lshlrev_b32_e32 v129, 2, v217
	v_lshlrev_b32_e32 v130, 2, v218
	v_lshlrev_b32_e32 v131, 2, v219
	v_lshlrev_b32_e32 v132, 2, v220
	v_lshlrev_b32_e32 v133, 2, v221
	v_lshl_add_u32 v136, v210, 7, 16
	v_and_b32_e32 v139, 3, v223
	v_bfrev_b32_e32 v139, v139
	v_lshrrev_b32_e32 v139, 20, v139
	v_and_b32_e32 v235, -4, v223
	v_add3_u32 v235, v136, v139, v235
	v_mov_b32_e32 v236, v228
	v_mov_b32_e32 v237, v226
	v_mov_b32_e32 v238, v231
	v_mov_b32_e32 v239, v230
	v_mov_b32_e32 v240, v229
	v_mov_b32_e32 v241, v227
	v_mov_b32_e32 v242, v225
	v_mov_b32_e32 v243, v224
	v_mov_b32_e32 v244, v232
	v_mov_b32_e32 v245, v135
	v_mov_b32_e32 v246, v234
	v_mov_b32_e32 v247, v138
	v_mov_b32_e32 v248, v233
	v_mov_b32_e32 v249, v137
	v_mov_b32_e32 v250, v211
	v_mov_b32_e32 v251, v134
	s_mov_b32 vcc_lo, 0x55555555
	s_mov_b32 vcc_hi, 0x55555555
	s_mov_b32 s4, 0x33333333
	s_mov_b32 s5, 0x33333333
	s_mov_b32 s6, 0x0f0f0f0f
	s_mov_b32 s7, 0x0f0f0f0f
	s_mov_b32 s64, 0x00ff00ff
	s_mov_b32 s65, 0x00ff00ff
	s_waitcnt vmcnt(31)
	v_pk_mul_f32 v[252:253], v[236:237], v[124:125] op_sel_hi:[1,0]
	v_pk_mul_f32 v[254:255], v[244:245], v[124:125] op_sel_hi:[1,0]
	v_pk_fma_f32 v[252:253], v[238:239], v[124:125], v[252:253] op_sel:[0,1,0]
	v_pk_fma_f32 v[254:255], v[246:247], v[124:125], v[254:255] op_sel:[0,1,0]
	v_pk_fma_f32 v[252:253], v[240:241], v[126:127], v[252:253] op_sel_hi:[1,0,1]
	v_pk_fma_f32 v[254:255], v[248:249], v[126:127], v[254:255] op_sel_hi:[1,0,1]
	v_pk_fma_f32 v[252:253], v[242:243], v[126:127], v[252:253] op_sel:[0,1,0]
	v_pk_fma_f32 v[254:255], v[250:251], v[126:127], v[254:255] op_sel:[0,1,0]
	s_waitcnt vmcnt(30)
	v_pk_mul_f32 v[140:141], v[236:237], v[120:121] op_sel_hi:[1,0]
	v_pk_mul_f32 v[142:143], v[244:245], v[120:121] op_sel_hi:[1,0]
	v_pk_fma_f32 v[140:141], v[238:239], v[120:121], v[140:141] op_sel:[0,1,0]
	v_pk_fma_f32 v[142:143], v[246:247], v[120:121], v[142:143] op_sel:[0,1,0]
	v_pk_fma_f32 v[140:141], v[240:241], v[122:123], v[140:141] op_sel_hi:[1,0,1]
	v_pk_fma_f32 v[142:143], v[248:249], v[122:123], v[142:143] op_sel_hi:[1,0,1]
	v_pk_fma_f32 v[140:141], v[242:243], v[122:123], v[140:141] op_sel:[0,1,0]
	v_pk_fma_f32 v[142:143], v[250:251], v[122:123], v[142:143] op_sel:[0,1,0]
	v_add_f32_dpp v124, v252, v252 quad_perm:[1,0,3,2] row_mask:0xf bank_mask:0xf
	v_add_f32_dpp v125, v253, v253 quad_perm:[1,0,3,2] row_mask:0xf bank_mask:0xf
	v_add_f32_dpp v126, v254, v254 quad_perm:[1,0,3,2] row_mask:0xf bank_mask:0xf
	v_add_f32_dpp v127, v255, v255 quad_perm:[1,0,3,2] row_mask:0xf bank_mask:0xf
	v_cndmask_b32_e32 v124, v126, v124, vcc
	v_cndmask_b32_e32 v125, v127, v125, vcc
	s_waitcnt vmcnt(29)
	v_pk_mul_f32 v[252:253], v[236:237], v[116:117] op_sel_hi:[1,0]
	v_pk_mul_f32 v[254:255], v[244:245], v[116:117] op_sel_hi:[1,0]
	v_pk_fma_f32 v[252:253], v[238:239], v[116:117], v[252:253] op_sel:[0,1,0]
	v_pk_fma_f32 v[254:255], v[246:247], v[116:117], v[254:255] op_sel:[0,1,0]
	v_pk_fma_f32 v[252:253], v[240:241], v[118:119], v[252:253] op_sel_hi:[1,0,1]
	v_pk_fma_f32 v[254:255], v[248:249], v[118:119], v[254:255] op_sel_hi:[1,0,1]
	v_pk_fma_f32 v[252:253], v[242:243], v[118:119], v[252:253] op_sel:[0,1,0]
	v_pk_fma_f32 v[254:255], v[250:251], v[118:119], v[254:255] op_sel:[0,1,0]
	v_add_f32_dpp v120, v140, v140 quad_perm:[1,0,3,2] row_mask:0xf bank_mask:0xf
	v_add_f32_dpp v121, v141, v141 quad_perm:[1,0,3,2] row_mask:0xf bank_mask:0xf
	v_add_f32_dpp v122, v142, v142 quad_perm:[1,0,3,2] row_mask:0xf bank_mask:0xf
	v_add_f32_dpp v123, v143, v143 quad_perm:[1,0,3,2] row_mask:0xf bank_mask:0xf
	v_cndmask_b32_e32 v120, v122, v120, vcc
	v_cndmask_b32_e32 v121, v123, v121, vcc
	v_add_f32_dpp v126, v124, v124 quad_perm:[2,3,0,1] row_mask:0xf bank_mask:0xf
	v_add_f32_dpp v127, v125, v125 quad_perm:[2,3,0,1] row_mask:0xf bank_mask:0xf
	v_cndmask_b32_e64 v124, v127, v126, s[4:5]
	s_waitcnt vmcnt(28)
	v_pk_mul_f32 v[140:141], v[236:237], v[112:113] op_sel_hi:[1,0]
	v_pk_mul_f32 v[142:143], v[244:245], v[112:113] op_sel_hi:[1,0]
	v_pk_fma_f32 v[140:141], v[238:239], v[112:113], v[140:141] op_sel:[0,1,0]
	v_pk_fma_f32 v[142:143], v[246:247], v[112:113], v[142:143] op_sel:[0,1,0]
	v_pk_fma_f32 v[140:141], v[240:241], v[114:115], v[140:141] op_sel_hi:[1,0,1]
	v_pk_fma_f32 v[142:143], v[248:249], v[114:115], v[142:143] op_sel_hi:[1,0,1]
	v_pk_fma_f32 v[140:141], v[242:243], v[114:115], v[140:141] op_sel:[0,1,0]
	v_pk_fma_f32 v[142:143], v[250:251], v[114:115], v[142:143] op_sel:[0,1,0]
	v_add_f32_dpp v116, v252, v252 quad_perm:[1,0,3,2] row_mask:0xf bank_mask:0xf
	v_add_f32_dpp v117, v253, v253 quad_perm:[1,0,3,2] row_mask:0xf bank_mask:0xf
	v_add_f32_dpp v118, v254, v254 quad_perm:[1,0,3,2] row_mask:0xf bank_mask:0xf
	v_add_f32_dpp v119, v255, v255 quad_perm:[1,0,3,2] row_mask:0xf bank_mask:0xf
	v_cndmask_b32_e32 v116, v118, v116, vcc
	v_cndmask_b32_e32 v117, v119, v117, vcc
	v_add_f32_dpp v122, v120, v120 quad_perm:[2,3,0,1] row_mask:0xf bank_mask:0xf
	v_add_f32_dpp v123, v121, v121 quad_perm:[2,3,0,1] row_mask:0xf bank_mask:0xf
	v_cndmask_b32_e64 v120, v123, v122, s[4:5]
	s_waitcnt vmcnt(27)
; DI void attn_sample_item(const Params& p, int item, ldsp lds, int tid_) {
;     ...
;   SC_SCORE(kvA, 0)
;   SC_SCORE(kvB, 1)
	v_pk_mul_f32 v[252:253], v[236:237], v[108:109] op_sel_hi:[1,0]
	v_pk_mul_f32 v[254:255], v[244:245], v[108:109] op_sel_hi:[1,0]
	v_pk_fma_f32 v[252:253], v[238:239], v[108:109], v[252:253] op_sel:[0,1,0]
	v_pk_fma_f32 v[254:255], v[246:247], v[108:109], v[254:255] op_sel:[0,1,0]
	v_pk_fma_f32 v[252:253], v[240:241], v[110:111], v[252:253] op_sel_hi:[1,0,1]
	v_pk_fma_f32 v[254:255], v[248:249], v[110:111], v[254:255] op_sel_hi:[1,0,1]
	v_pk_fma_f32 v[252:253], v[242:243], v[110:111], v[252:253] op_sel:[0,1,0]
	v_pk_fma_f32 v[254:255], v[250:251], v[110:111], v[254:255] op_sel:[0,1,0]
	v_add_f32_dpp v124, v124, v124 row_ror:4 row_mask:0xf bank_mask:0x5
	v_add_f32_dpp v124, v120, v120 row_ror:4 row_mask:0xf bank_mask:0xa
	v_add_f32_dpp v112, v140, v140 quad_perm:[1,0,3,2] row_mask:0xf bank_mask:0xf
	v_add_f32_dpp v113, v141, v141 quad_perm:[1,0,3,2] row_mask:0xf bank_mask:0xf
	v_add_f32_dpp v114, v142, v142 quad_perm:[1,0,3,2] row_mask:0xf bank_mask:0xf
	v_add_f32_dpp v115, v143, v143 quad_perm:[1,0,3,2] row_mask:0xf bank_mask:0xf
	v_cndmask_b32_e32 v112, v114, v112, vcc
	v_cndmask_b32_e32 v113, v115, v113, vcc
	v_add_f32_dpp v118, v116, v116 quad_perm:[2,3,0,1] row_mask:0xf bank_mask:0xf
	v_add_f32_dpp v119, v117, v117 quad_perm:[2,3,0,1] row_mask:0xf bank_mask:0xf
	v_cndmask_b32_e64 v116, v119, v118, s[4:5]
	s_waitcnt vmcnt(26)
	v_pk_mul_f32 v[140:141], v[236:237], v[104:105] op_sel_hi:[1,0]
	v_pk_mul_f32 v[142:143], v[244:245], v[104:105] op_sel_hi:[1,0]
	v_pk_fma_f32 v[140:141], v[238:239], v[104:105], v[140:141] op_sel:[0,1,0]
	v_pk_fma_f32 v[142:143], v[246:247], v[104:105], v[142:143] op_sel:[0,1,0]
	v_pk_fma_f32 v[140:141], v[240:241], v[106:107], v[140:141] op_sel_hi:[1,0,1]
	v_pk_fma_f32 v[142:143], v[248:249], v[106:107], v[142:143] op_sel_hi:[1,0,1]
	v_pk_fma_f32 v[140:141], v[242:243], v[106:107], v[140:141] op_sel:[0,1,0]
	v_pk_fma_f32 v[142:143], v[250:251], v[106:107], v[142:143] op_sel:[0,1,0]
	v_add_f32_dpp v108, v252, v252 quad_perm:[1,0,3,2] row_mask:0xf bank_mask:0xf
	v_add_f32_dpp v109, v253, v253 quad_perm:[1,0,3,2] row_mask:0xf bank_mask:0xf
	v_add_f32_dpp v110, v254, v254 quad_perm:[1,0,3,2] row_mask:0xf bank_mask:0xf
	v_add_f32_dpp v111, v255, v255 quad_perm:[1,0,3,2] row_mask:0xf bank_mask:0xf
	v_cndmask_b32_e32 v108, v110, v108, vcc
	v_cndmask_b32_e32 v109, v111, v109, vcc
	v_add_f32_dpp v114, v112, v112 quad_perm:[2,3,0,1] row_mask:0xf bank_mask:0xf
	v_add_f32_dpp v115, v113, v113 quad_perm:[2,3,0,1] row_mask:0xf bank_mask:0xf
	v_cndmask_b32_e64 v112, v115, v114, s[4:5]
	s_waitcnt vmcnt(25)
	v_pk_mul_f32 v[252:253], v[236:237], v[100:101] op_sel_hi:[1,0]
	v_pk_mul_f32 v[254:255], v[244:245], v[100:101] op_sel_hi:[1,0]
	v_pk_fma_f32 v[252:253], v[238:239], v[100:101], v[252:253] op_sel:[0,1,0]
	v_pk_fma_f32 v[254:255], v[246:247], v[100:101], v[254:255] op_sel:[0,1,0]
	v_pk_fma_f32 v[252:253], v[240:241], v[102:103], v[252:253] op_sel_hi:[1,0,1]
	v_pk_fma_f32 v[254:255], v[248:249], v[102:103], v[254:255] op_sel_hi:[1,0,1]
	v_pk_fma_f32 v[252:253], v[242:243], v[102:103], v[252:253] op_sel:[0,1,0]
	v_pk_fma_f32 v[254:255], v[250:251], v[102:103], v[254:255] op_sel:[0,1,0]
	v_add_f32_dpp v116, v116, v116 row_ror:4 row_mask:0xf bank_mask:0x5
	v_add_f32_dpp v116, v112, v112 row_ror:4 row_mask:0xf bank_mask:0xa
	v_add_f32_dpp v104, v140, v140 quad_perm:[1,0,3,2] row_mask:0xf bank_mask:0xf
	v_add_f32_dpp v105, v141, v141 quad_perm:[1,0,3,2] row_mask:0xf bank_mask:0xf
	v_add_f32_dpp v106, v142, v142 quad_perm:[1,0,3,2] row_mask:0xf bank_mask:0xf
	v_add_f32_dpp v107, v143, v143 quad_perm:[1,0,3,2] row_mask:0xf bank_mask:0xf
	v_cndmask_b32_e32 v104, v106, v104, vcc
	v_cndmask_b32_e32 v105, v107, v105, vcc
	v_add_f32_dpp v110, v108, v108 quad_perm:[2,3,0,1] row_mask:0xf bank_mask:0xf
	v_add_f32_dpp v111, v109, v109 quad_perm:[2,3,0,1] row_mask:0xf bank_mask:0xf
	v_cndmask_b32_e64 v108, v111, v110, s[4:5]
	s_waitcnt vmcnt(24)
	v_pk_mul_f32 v[140:141], v[236:237], v[96:97] op_sel_hi:[1,0]
	v_pk_mul_f32 v[142:143], v[244:245], v[96:97] op_sel_hi:[1,0]
	v_pk_fma_f32 v[140:141], v[238:239], v[96:97], v[140:141] op_sel:[0,1,0]
	v_pk_fma_f32 v[142:143], v[246:247], v[96:97], v[142:143] op_sel:[0,1,0]
	v_pk_fma_f32 v[140:141], v[240:241], v[98:99], v[140:141] op_sel_hi:[1,0,1]
	v_pk_fma_f32 v[142:143], v[248:249], v[98:99], v[142:143] op_sel_hi:[1,0,1]
	v_pk_fma_f32 v[140:141], v[242:243], v[98:99], v[140:141] op_sel:[0,1,0]
	v_pk_fma_f32 v[142:143], v[250:251], v[98:99], v[142:143] op_sel:[0,1,0]
	v_add_f32_dpp v124, v124, v124 row_ror:8 row_mask:0xf bank_mask:0x3
	v_add_f32_dpp v124, v116, v116 row_ror:8 row_mask:0xf bank_mask:0xc
	v_add_f32_dpp v100, v252, v252 quad_perm:[1,0,3,2] row_mask:0xf bank_mask:0xf
	v_add_f32_dpp v101, v253, v253 quad_perm:[1,0,3,2] row_mask:0xf bank_mask:0xf
	v_add_f32_dpp v102, v254, v254 quad_perm:[1,0,3,2] row_mask:0xf bank_mask:0xf
	v_add_f32_dpp v103, v255, v255 quad_perm:[1,0,3,2] row_mask:0xf bank_mask:0xf
	v_cndmask_b32_e32 v100, v102, v100, vcc
	v_cndmask_b32_e32 v101, v103, v101, vcc
	v_add_f32_dpp v106, v104, v104 quad_perm:[2,3,0,1] row_mask:0xf bank_mask:0xf
	v_add_f32_dpp v107, v105, v105 quad_perm:[2,3,0,1] row_mask:0xf bank_mask:0xf
	v_cndmask_b32_e64 v104, v107, v106, s[4:5]
	s_waitcnt vmcnt(23)
; DI void attn_sample_item(const Params& p, int item, ldsp lds, int tid_) {
;     ...
;   SC_SCORE(kvA, 0)
;   SC_SCORE(kvB, 1)
	v_pk_mul_f32 v[252:253], v[236:237], v[92:93] op_sel_hi:[1,0]
	v_pk_mul_f32 v[254:255], v[244:245], v[92:93] op_sel_hi:[1,0]
	v_pk_fma_f32 v[252:253], v[238:239], v[92:93], v[252:253] op_sel:[0,1,0]
	v_pk_fma_f32 v[254:255], v[246:247], v[92:93], v[254:255] op_sel:[0,1,0]
	v_pk_fma_f32 v[252:253], v[240:241], v[94:95], v[252:253] op_sel_hi:[1,0,1]
	v_pk_fma_f32 v[254:255], v[248:249], v[94:95], v[254:255] op_sel_hi:[1,0,1]
	v_pk_fma_f32 v[252:253], v[242:243], v[94:95], v[252:253] op_sel:[0,1,0]
	v_pk_fma_f32 v[254:255], v[250:251], v[94:95], v[254:255] op_sel:[0,1,0]
	v_add_f32_dpp v108, v108, v108 row_ror:4 row_mask:0xf bank_mask:0x5
	v_add_f32_dpp v108, v104, v104 row_ror:4 row_mask:0xf bank_mask:0xa
	v_add_f32_dpp v96, v140, v140 quad_perm:[1,0,3,2] row_mask:0xf bank_mask:0xf
	v_add_f32_dpp v97, v141, v141 quad_perm:[1,0,3,2] row_mask:0xf bank_mask:0xf
	v_add_f32_dpp v98, v142, v142 quad_perm:[1,0,3,2] row_mask:0xf bank_mask:0xf
	v_add_f32_dpp v99, v143, v143 quad_perm:[1,0,3,2] row_mask:0xf bank_mask:0xf
	v_cndmask_b32_e32 v96, v98, v96, vcc
	v_cndmask_b32_e32 v97, v99, v97, vcc
	v_add_f32_dpp v102, v100, v100 quad_perm:[2,3,0,1] row_mask:0xf bank_mask:0xf
	v_add_f32_dpp v103, v101, v101 quad_perm:[2,3,0,1] row_mask:0xf bank_mask:0xf
	v_cndmask_b32_e64 v100, v103, v102, s[4:5]
	s_waitcnt vmcnt(22)
	v_pk_mul_f32 v[140:141], v[236:237], v[88:89] op_sel_hi:[1,0]
	v_pk_mul_f32 v[142:143], v[244:245], v[88:89] op_sel_hi:[1,0]
	v_pk_fma_f32 v[140:141], v[238:239], v[88:89], v[140:141] op_sel:[0,1,0]
	v_pk_fma_f32 v[142:143], v[246:247], v[88:89], v[142:143] op_sel:[0,1,0]
	v_pk_fma_f32 v[140:141], v[240:241], v[90:91], v[140:141] op_sel_hi:[1,0,1]
	v_pk_fma_f32 v[142:143], v[248:249], v[90:91], v[142:143] op_sel_hi:[1,0,1]
	v_pk_fma_f32 v[140:141], v[242:243], v[90:91], v[140:141] op_sel:[0,1,0]
	v_pk_fma_f32 v[142:143], v[250:251], v[90:91], v[142:143] op_sel:[0,1,0]
	v_add_f32_dpp v92, v252, v252 quad_perm:[1,0,3,2] row_mask:0xf bank_mask:0xf
	v_add_f32_dpp v93, v253, v253 quad_perm:[1,0,3,2] row_mask:0xf bank_mask:0xf
	v_add_f32_dpp v94, v254, v254 quad_perm:[1,0,3,2] row_mask:0xf bank_mask:0xf
	v_add_f32_dpp v95, v255, v255 quad_perm:[1,0,3,2] row_mask:0xf bank_mask:0xf
	v_cndmask_b32_e32 v92, v94, v92, vcc
	v_cndmask_b32_e32 v93, v95, v93, vcc
	v_add_f32_dpp v98, v96, v96 quad_perm:[2,3,0,1] row_mask:0xf bank_mask:0xf
	v_add_f32_dpp v99, v97, v97 quad_perm:[2,3,0,1] row_mask:0xf bank_mask:0xf
	v_cndmask_b32_e64 v96, v99, v98, s[4:5]
	s_waitcnt vmcnt(21)
	v_pk_mul_f32 v[252:253], v[236:237], v[84:85] op_sel_hi:[1,0]
	v_pk_mul_f32 v[254:255], v[244:245], v[84:85] op_sel_hi:[1,0]
	v_pk_fma_f32 v[252:253], v[238:239], v[84:85], v[252:253] op_sel:[0,1,0]
	v_pk_fma_f32 v[254:255], v[246:247], v[84:85], v[254:255] op_sel:[0,1,0]
	v_pk_fma_f32 v[252:253], v[240:241], v[86:87], v[252:253] op_sel_hi:[1,0,1]
	v_pk_fma_f32 v[254:255], v[248:249], v[86:87], v[254:255] op_sel_hi:[1,0,1]
	v_pk_fma_f32 v[252:253], v[242:243], v[86:87], v[252:253] op_sel:[0,1,0]
	v_pk_fma_f32 v[254:255], v[250:251], v[86:87], v[254:255] op_sel:[0,1,0]
	v_add_f32_dpp v100, v100, v100 row_ror:4 row_mask:0xf bank_mask:0x5
	v_add_f32_dpp v100, v96, v96 row_ror:4 row_mask:0xf bank_mask:0xa
	v_add_f32_dpp v88, v140, v140 quad_perm:[1,0,3,2] row_mask:0xf bank_mask:0xf
	v_add_f32_dpp v89, v141, v141 quad_perm:[1,0,3,2] row_mask:0xf bank_mask:0xf
	v_add_f32_dpp v90, v142, v142 quad_perm:[1,0,3,2] row_mask:0xf bank_mask:0xf
	v_add_f32_dpp v91, v143, v143 quad_perm:[1,0,3,2] row_mask:0xf bank_mask:0xf
	v_cndmask_b32_e32 v88, v90, v88, vcc
	v_cndmask_b32_e32 v89, v91, v89, vcc
	v_add_f32_dpp v94, v92, v92 quad_perm:[2,3,0,1] row_mask:0xf bank_mask:0xf
	v_add_f32_dpp v95, v93, v93 quad_perm:[2,3,0,1] row_mask:0xf bank_mask:0xf
	v_cndmask_b32_e64 v92, v95, v94, s[4:5]
	s_waitcnt vmcnt(20)
	v_pk_mul_f32 v[140:141], v[236:237], v[80:81] op_sel_hi:[1,0]
	v_pk_mul_f32 v[142:143], v[244:245], v[80:81] op_sel_hi:[1,0]
	v_pk_fma_f32 v[140:141], v[238:239], v[80:81], v[140:141] op_sel:[0,1,0]
	v_pk_fma_f32 v[142:143], v[246:247], v[80:81], v[142:143] op_sel:[0,1,0]
	v_pk_fma_f32 v[140:141], v[240:241], v[82:83], v[140:141] op_sel_hi:[1,0,1]
	v_pk_fma_f32 v[142:143], v[248:249], v[82:83], v[142:143] op_sel_hi:[1,0,1]
	v_pk_fma_f32 v[140:141], v[242:243], v[82:83], v[140:141] op_sel:[0,1,0]
	v_pk_fma_f32 v[142:143], v[250:251], v[82:83], v[142:143] op_sel:[0,1,0]
	v_add_f32_dpp v108, v108, v108 row_ror:8 row_mask:0xf bank_mask:0x3
	v_add_f32_dpp v108, v100, v100 row_ror:8 row_mask:0xf bank_mask:0xc
	v_add_f32_dpp v84, v252, v252 quad_perm:[1,0,3,2] row_mask:0xf bank_mask:0xf
	v_add_f32_dpp v85, v253, v253 quad_perm:[1,0,3,2] row_mask:0xf bank_mask:0xf
	v_add_f32_dpp v86, v254, v254 quad_perm:[1,0,3,2] row_mask:0xf bank_mask:0xf
	v_add_f32_dpp v87, v255, v255 quad_perm:[1,0,3,2] row_mask:0xf bank_mask:0xf
	v_cndmask_b32_e32 v84, v86, v84, vcc
	v_cndmask_b32_e32 v85, v87, v85, vcc
	v_add_f32_dpp v90, v88, v88 quad_perm:[2,3,0,1] row_mask:0xf bank_mask:0xf
	v_add_f32_dpp v91, v89, v89 quad_perm:[2,3,0,1] row_mask:0xf bank_mask:0xf
	v_cndmask_b32_e64 v88, v91, v90, s[4:5]
	s_waitcnt vmcnt(19)
; DI void attn_sample_item(const Params& p, int item, ldsp lds, int tid_) {
;     ...
;   SC_SCORE(kvA, 0)
;   SC_SCORE(kvB, 1)
	v_pk_mul_f32 v[252:253], v[236:237], v[76:77] op_sel_hi:[1,0]
	v_pk_mul_f32 v[254:255], v[244:245], v[76:77] op_sel_hi:[1,0]
	v_pk_fma_f32 v[252:253], v[238:239], v[76:77], v[252:253] op_sel:[0,1,0]
	v_pk_fma_f32 v[254:255], v[246:247], v[76:77], v[254:255] op_sel:[0,1,0]
	v_pk_fma_f32 v[252:253], v[240:241], v[78:79], v[252:253] op_sel_hi:[1,0,1]
	v_pk_fma_f32 v[254:255], v[248:249], v[78:79], v[254:255] op_sel_hi:[1,0,1]
	v_pk_fma_f32 v[252:253], v[242:243], v[78:79], v[252:253] op_sel:[0,1,0]
	v_pk_fma_f32 v[254:255], v[250:251], v[78:79], v[254:255] op_sel:[0,1,0]
	v_permlane16_swap_b32_e32 v124, v108
	v_add_f32_e32 v124, v124, v108
	v_add_f32_dpp v92, v92, v92 row_ror:4 row_mask:0xf bank_mask:0x5
	v_add_f32_dpp v92, v88, v88 row_ror:4 row_mask:0xf bank_mask:0xa
	v_add_f32_dpp v80, v140, v140 quad_perm:[1,0,3,2] row_mask:0xf bank_mask:0xf
	v_add_f32_dpp v81, v141, v141 quad_perm:[1,0,3,2] row_mask:0xf bank_mask:0xf
	v_add_f32_dpp v82, v142, v142 quad_perm:[1,0,3,2] row_mask:0xf bank_mask:0xf
	v_add_f32_dpp v83, v143, v143 quad_perm:[1,0,3,2] row_mask:0xf bank_mask:0xf
	v_cndmask_b32_e32 v80, v82, v80, vcc
	v_cndmask_b32_e32 v81, v83, v81, vcc
	v_add_f32_dpp v86, v84, v84 quad_perm:[2,3,0,1] row_mask:0xf bank_mask:0xf
	v_add_f32_dpp v87, v85, v85 quad_perm:[2,3,0,1] row_mask:0xf bank_mask:0xf
	v_cndmask_b32_e64 v84, v87, v86, s[4:5]
	s_waitcnt vmcnt(18)
	v_pk_mul_f32 v[140:141], v[236:237], v[72:73] op_sel_hi:[1,0]
	v_pk_mul_f32 v[142:143], v[244:245], v[72:73] op_sel_hi:[1,0]
	v_pk_fma_f32 v[140:141], v[238:239], v[72:73], v[140:141] op_sel:[0,1,0]
	v_pk_fma_f32 v[142:143], v[246:247], v[72:73], v[142:143] op_sel:[0,1,0]
	v_pk_fma_f32 v[140:141], v[240:241], v[74:75], v[140:141] op_sel_hi:[1,0,1]
	v_pk_fma_f32 v[142:143], v[248:249], v[74:75], v[142:143] op_sel_hi:[1,0,1]
	v_pk_fma_f32 v[140:141], v[242:243], v[74:75], v[140:141] op_sel:[0,1,0]
	v_pk_fma_f32 v[142:143], v[250:251], v[74:75], v[142:143] op_sel:[0,1,0]
	v_add_f32_dpp v76, v252, v252 quad_perm:[1,0,3,2] row_mask:0xf bank_mask:0xf
	v_add_f32_dpp v77, v253, v253 quad_perm:[1,0,3,2] row_mask:0xf bank_mask:0xf
	v_add_f32_dpp v78, v254, v254 quad_perm:[1,0,3,2] row_mask:0xf bank_mask:0xf
	v_add_f32_dpp v79, v255, v255 quad_perm:[1,0,3,2] row_mask:0xf bank_mask:0xf
	v_cndmask_b32_e32 v76, v78, v76, vcc
	v_cndmask_b32_e32 v77, v79, v77, vcc
	v_add_f32_dpp v82, v80, v80 quad_perm:[2,3,0,1] row_mask:0xf bank_mask:0xf
	v_add_f32_dpp v83, v81, v81 quad_perm:[2,3,0,1] row_mask:0xf bank_mask:0xf
	v_cndmask_b32_e64 v80, v83, v82, s[4:5]
	s_waitcnt vmcnt(17)
	v_pk_mul_f32 v[252:253], v[236:237], v[68:69] op_sel_hi:[1,0]
	v_pk_mul_f32 v[254:255], v[244:245], v[68:69] op_sel_hi:[1,0]
	v_pk_fma_f32 v[252:253], v[238:239], v[68:69], v[252:253] op_sel:[0,1,0]
	v_pk_fma_f32 v[254:255], v[246:247], v[68:69], v[254:255] op_sel:[0,1,0]
	v_pk_fma_f32 v[252:253], v[240:241], v[70:71], v[252:253] op_sel_hi:[1,0,1]
	v_pk_fma_f32 v[254:255], v[248:249], v[70:71], v[254:255] op_sel_hi:[1,0,1]
	v_pk_fma_f32 v[252:253], v[242:243], v[70:71], v[252:253] op_sel:[0,1,0]
	v_pk_fma_f32 v[254:255], v[250:251], v[70:71], v[254:255] op_sel:[0,1,0]
	v_add_f32_dpp v84, v84, v84 row_ror:4 row_mask:0xf bank_mask:0x5
	v_add_f32_dpp v84, v80, v80 row_ror:4 row_mask:0xf bank_mask:0xa
	v_add_f32_dpp v72, v140, v140 quad_perm:[1,0,3,2] row_mask:0xf bank_mask:0xf
	v_add_f32_dpp v73, v141, v141 quad_perm:[1,0,3,2] row_mask:0xf bank_mask:0xf
	v_add_f32_dpp v74, v142, v142 quad_perm:[1,0,3,2] row_mask:0xf bank_mask:0xf
	v_add_f32_dpp v75, v143, v143 quad_perm:[1,0,3,2] row_mask:0xf bank_mask:0xf
	v_cndmask_b32_e32 v72, v74, v72, vcc
	v_cndmask_b32_e32 v73, v75, v73, vcc
	v_add_f32_dpp v78, v76, v76 quad_perm:[2,3,0,1] row_mask:0xf bank_mask:0xf
	v_add_f32_dpp v79, v77, v77 quad_perm:[2,3,0,1] row_mask:0xf bank_mask:0xf
	v_cndmask_b32_e64 v76, v79, v78, s[4:5]
	s_waitcnt vmcnt(16)
	v_pk_mul_f32 v[140:141], v[236:237], v[64:65] op_sel_hi:[1,0]
	v_pk_mul_f32 v[142:143], v[244:245], v[64:65] op_sel_hi:[1,0]
	v_pk_fma_f32 v[140:141], v[238:239], v[64:65], v[140:141] op_sel:[0,1,0]
	v_pk_fma_f32 v[142:143], v[246:247], v[64:65], v[142:143] op_sel:[0,1,0]
	v_pk_fma_f32 v[140:141], v[240:241], v[66:67], v[140:141] op_sel_hi:[1,0,1]
	v_pk_fma_f32 v[142:143], v[248:249], v[66:67], v[142:143] op_sel_hi:[1,0,1]
	v_pk_fma_f32 v[140:141], v[242:243], v[66:67], v[140:141] op_sel:[0,1,0]
	v_pk_fma_f32 v[142:143], v[250:251], v[66:67], v[142:143] op_sel:[0,1,0]
	v_add_f32_dpp v92, v92, v92 row_ror:8 row_mask:0xf bank_mask:0x3
	v_add_f32_dpp v92, v84, v84 row_ror:8 row_mask:0xf bank_mask:0xc
	v_add_f32_dpp v68, v252, v252 quad_perm:[1,0,3,2] row_mask:0xf bank_mask:0xf
	v_add_f32_dpp v69, v253, v253 quad_perm:[1,0,3,2] row_mask:0xf bank_mask:0xf
	v_add_f32_dpp v70, v254, v254 quad_perm:[1,0,3,2] row_mask:0xf bank_mask:0xf
	v_add_f32_dpp v71, v255, v255 quad_perm:[1,0,3,2] row_mask:0xf bank_mask:0xf
	v_cndmask_b32_e32 v68, v70, v68, vcc
	v_cndmask_b32_e32 v69, v71, v69, vcc
	v_add_f32_dpp v74, v72, v72 quad_perm:[2,3,0,1] row_mask:0xf bank_mask:0xf
	v_add_f32_dpp v75, v73, v73 quad_perm:[2,3,0,1] row_mask:0xf bank_mask:0xf
	v_cndmask_b32_e64 v72, v75, v74, s[4:5]
	s_waitcnt vmcnt(15)
; DI void attn_sample_item(const Params& p, int item, ldsp lds, int tid_) {
;     ...
;   SC_SCORE(kvA, 0)
;   SC_SCORE(kvB, 1)
	v_pk_mul_f32 v[252:253], v[236:237], v[60:61] op_sel_hi:[1,0]
	v_pk_mul_f32 v[254:255], v[244:245], v[60:61] op_sel_hi:[1,0]
	v_pk_fma_f32 v[252:253], v[238:239], v[60:61], v[252:253] op_sel:[0,1,0]
	v_pk_fma_f32 v[254:255], v[246:247], v[60:61], v[254:255] op_sel:[0,1,0]
	v_pk_fma_f32 v[252:253], v[240:241], v[62:63], v[252:253] op_sel_hi:[1,0,1]
	v_pk_fma_f32 v[254:255], v[248:249], v[62:63], v[254:255] op_sel_hi:[1,0,1]
	v_pk_fma_f32 v[252:253], v[242:243], v[62:63], v[252:253] op_sel:[0,1,0]
	v_pk_fma_f32 v[254:255], v[250:251], v[62:63], v[254:255] op_sel:[0,1,0]
	v_add_f32_dpp v76, v76, v76 row_ror:4 row_mask:0xf bank_mask:0x5
	v_add_f32_dpp v76, v72, v72 row_ror:4 row_mask:0xf bank_mask:0xa
	v_add_f32_dpp v64, v140, v140 quad_perm:[1,0,3,2] row_mask:0xf bank_mask:0xf
	v_add_f32_dpp v65, v141, v141 quad_perm:[1,0,3,2] row_mask:0xf bank_mask:0xf
	v_add_f32_dpp v66, v142, v142 quad_perm:[1,0,3,2] row_mask:0xf bank_mask:0xf
	v_add_f32_dpp v67, v143, v143 quad_perm:[1,0,3,2] row_mask:0xf bank_mask:0xf
	v_cndmask_b32_e32 v64, v66, v64, vcc
	v_cndmask_b32_e32 v65, v67, v65, vcc
	v_add_f32_dpp v70, v68, v68 quad_perm:[2,3,0,1] row_mask:0xf bank_mask:0xf
	v_add_f32_dpp v71, v69, v69 quad_perm:[2,3,0,1] row_mask:0xf bank_mask:0xf
	v_cndmask_b32_e64 v68, v71, v70, s[4:5]
	s_waitcnt vmcnt(14)
	v_pk_mul_f32 v[140:141], v[236:237], v[56:57] op_sel_hi:[1,0]
	v_pk_mul_f32 v[142:143], v[244:245], v[56:57] op_sel_hi:[1,0]
	v_pk_fma_f32 v[140:141], v[238:239], v[56:57], v[140:141] op_sel:[0,1,0]
	v_pk_fma_f32 v[142:143], v[246:247], v[56:57], v[142:143] op_sel:[0,1,0]
	v_pk_fma_f32 v[140:141], v[240:241], v[58:59], v[140:141] op_sel_hi:[1,0,1]
	v_pk_fma_f32 v[142:143], v[248:249], v[58:59], v[142:143] op_sel_hi:[1,0,1]
	v_pk_fma_f32 v[140:141], v[242:243], v[58:59], v[140:141] op_sel:[0,1,0]
	v_pk_fma_f32 v[142:143], v[250:251], v[58:59], v[142:143] op_sel:[0,1,0]
	v_add_f32_dpp v60, v252, v252 quad_perm:[1,0,3,2] row_mask:0xf bank_mask:0xf
	v_add_f32_dpp v61, v253, v253 quad_perm:[1,0,3,2] row_mask:0xf bank_mask:0xf
	v_add_f32_dpp v62, v254, v254 quad_perm:[1,0,3,2] row_mask:0xf bank_mask:0xf
	v_add_f32_dpp v63, v255, v255 quad_perm:[1,0,3,2] row_mask:0xf bank_mask:0xf
	v_cndmask_b32_e32 v60, v62, v60, vcc
	v_cndmask_b32_e32 v61, v63, v61, vcc
	v_add_f32_dpp v66, v64, v64 quad_perm:[2,3,0,1] row_mask:0xf bank_mask:0xf
	v_add_f32_dpp v67, v65, v65 quad_perm:[2,3,0,1] row_mask:0xf bank_mask:0xf
	v_cndmask_b32_e64 v64, v67, v66, s[4:5]
	s_waitcnt vmcnt(13)
	v_pk_mul_f32 v[252:253], v[236:237], v[52:53] op_sel_hi:[1,0]
	v_pk_mul_f32 v[254:255], v[244:245], v[52:53] op_sel_hi:[1,0]
	v_pk_fma_f32 v[252:253], v[238:239], v[52:53], v[252:253] op_sel:[0,1,0]
	v_pk_fma_f32 v[254:255], v[246:247], v[52:53], v[254:255] op_sel:[0,1,0]
	v_pk_fma_f32 v[252:253], v[240:241], v[54:55], v[252:253] op_sel_hi:[1,0,1]
	v_pk_fma_f32 v[254:255], v[248:249], v[54:55], v[254:255] op_sel_hi:[1,0,1]
	v_pk_fma_f32 v[252:253], v[242:243], v[54:55], v[252:253] op_sel:[0,1,0]
	v_pk_fma_f32 v[254:255], v[250:251], v[54:55], v[254:255] op_sel:[0,1,0]
	v_add_f32_dpp v68, v68, v68 row_ror:4 row_mask:0xf bank_mask:0x5
	v_add_f32_dpp v68, v64, v64 row_ror:4 row_mask:0xf bank_mask:0xa
	v_add_f32_dpp v56, v140, v140 quad_perm:[1,0,3,2] row_mask:0xf bank_mask:0xf
	v_add_f32_dpp v57, v141, v141 quad_perm:[1,0,3,2] row_mask:0xf bank_mask:0xf
	v_add_f32_dpp v58, v142, v142 quad_perm:[1,0,3,2] row_mask:0xf bank_mask:0xf
	v_add_f32_dpp v59, v143, v143 quad_perm:[1,0,3,2] row_mask:0xf bank_mask:0xf
	v_cndmask_b32_e32 v56, v58, v56, vcc
	v_cndmask_b32_e32 v57, v59, v57, vcc
	v_add_f32_dpp v62, v60, v60 quad_perm:[2,3,0,1] row_mask:0xf bank_mask:0xf
	v_add_f32_dpp v63, v61, v61 quad_perm:[2,3,0,1] row_mask:0xf bank_mask:0xf
	v_cndmask_b32_e64 v60, v63, v62, s[4:5]
	s_waitcnt vmcnt(12)
	v_pk_mul_f32 v[140:141], v[236:237], v[48:49] op_sel_hi:[1,0]
	v_pk_mul_f32 v[142:143], v[244:245], v[48:49] op_sel_hi:[1,0]
	v_pk_fma_f32 v[140:141], v[238:239], v[48:49], v[140:141] op_sel:[0,1,0]
	v_pk_fma_f32 v[142:143], v[246:247], v[48:49], v[142:143] op_sel:[0,1,0]
	v_pk_fma_f32 v[140:141], v[240:241], v[50:51], v[140:141] op_sel_hi:[1,0,1]
	v_pk_fma_f32 v[142:143], v[248:249], v[50:51], v[142:143] op_sel_hi:[1,0,1]
	v_pk_fma_f32 v[140:141], v[242:243], v[50:51], v[140:141] op_sel:[0,1,0]
	v_pk_fma_f32 v[142:143], v[250:251], v[50:51], v[142:143] op_sel:[0,1,0]
	v_add_f32_dpp v76, v76, v76 row_ror:8 row_mask:0xf bank_mask:0x3
	v_add_f32_dpp v76, v68, v68 row_ror:8 row_mask:0xf bank_mask:0xc
	v_add_f32_dpp v52, v252, v252 quad_perm:[1,0,3,2] row_mask:0xf bank_mask:0xf
	v_add_f32_dpp v53, v253, v253 quad_perm:[1,0,3,2] row_mask:0xf bank_mask:0xf
	v_add_f32_dpp v54, v254, v254 quad_perm:[1,0,3,2] row_mask:0xf bank_mask:0xf
	v_add_f32_dpp v55, v255, v255 quad_perm:[1,0,3,2] row_mask:0xf bank_mask:0xf
	v_cndmask_b32_e32 v52, v54, v52, vcc
	v_cndmask_b32_e32 v53, v55, v53, vcc
	v_add_f32_dpp v58, v56, v56 quad_perm:[2,3,0,1] row_mask:0xf bank_mask:0xf
	v_add_f32_dpp v59, v57, v57 quad_perm:[2,3,0,1] row_mask:0xf bank_mask:0xf
	v_cndmask_b32_e64 v56, v59, v58, s[4:5]
	s_waitcnt vmcnt(11)
; DI void attn_sample_item(const Params& p, int item, ldsp lds, int tid_) {
;     ...
;   SC_SCORE(kvA, 0)
;   SC_SCORE(kvB, 1)
	v_pk_mul_f32 v[252:253], v[236:237], v[44:45] op_sel_hi:[1,0]
	v_pk_mul_f32 v[254:255], v[244:245], v[44:45] op_sel_hi:[1,0]
	v_pk_fma_f32 v[252:253], v[238:239], v[44:45], v[252:253] op_sel:[0,1,0]
	v_pk_fma_f32 v[254:255], v[246:247], v[44:45], v[254:255] op_sel:[0,1,0]
	v_pk_fma_f32 v[252:253], v[240:241], v[46:47], v[252:253] op_sel_hi:[1,0,1]
	v_pk_fma_f32 v[254:255], v[248:249], v[46:47], v[254:255] op_sel_hi:[1,0,1]
	v_pk_fma_f32 v[252:253], v[242:243], v[46:47], v[252:253] op_sel:[0,1,0]
	v_pk_fma_f32 v[254:255], v[250:251], v[46:47], v[254:255] op_sel:[0,1,0]
	v_permlane16_swap_b32_e32 v92, v76
	v_add_f32_e32 v92, v92, v76
	v_add_f32_dpp v60, v60, v60 row_ror:4 row_mask:0xf bank_mask:0x5
	v_add_f32_dpp v60, v56, v56 row_ror:4 row_mask:0xf bank_mask:0xa
	v_add_f32_dpp v48, v140, v140 quad_perm:[1,0,3,2] row_mask:0xf bank_mask:0xf
	v_add_f32_dpp v49, v141, v141 quad_perm:[1,0,3,2] row_mask:0xf bank_mask:0xf
	v_add_f32_dpp v50, v142, v142 quad_perm:[1,0,3,2] row_mask:0xf bank_mask:0xf
	v_add_f32_dpp v51, v143, v143 quad_perm:[1,0,3,2] row_mask:0xf bank_mask:0xf
	v_cndmask_b32_e32 v48, v50, v48, vcc
	v_cndmask_b32_e32 v49, v51, v49, vcc
	v_add_f32_dpp v54, v52, v52 quad_perm:[2,3,0,1] row_mask:0xf bank_mask:0xf
	v_add_f32_dpp v55, v53, v53 quad_perm:[2,3,0,1] row_mask:0xf bank_mask:0xf
	v_cndmask_b32_e64 v52, v55, v54, s[4:5]
	s_waitcnt vmcnt(10)
	v_pk_mul_f32 v[140:141], v[236:237], v[40:41] op_sel_hi:[1,0]
	v_pk_mul_f32 v[142:143], v[244:245], v[40:41] op_sel_hi:[1,0]
	v_pk_fma_f32 v[140:141], v[238:239], v[40:41], v[140:141] op_sel:[0,1,0]
	v_pk_fma_f32 v[142:143], v[246:247], v[40:41], v[142:143] op_sel:[0,1,0]
	v_pk_fma_f32 v[140:141], v[240:241], v[42:43], v[140:141] op_sel_hi:[1,0,1]
	v_pk_fma_f32 v[142:143], v[248:249], v[42:43], v[142:143] op_sel_hi:[1,0,1]
	v_pk_fma_f32 v[140:141], v[242:243], v[42:43], v[140:141] op_sel:[0,1,0]
	v_pk_fma_f32 v[142:143], v[250:251], v[42:43], v[142:143] op_sel:[0,1,0]
	v_permlane32_swap_b32_e32 v124, v92
	v_add_f32_e32 v124, v124, v92
	ds_write_b32 v235, v124
	v_add_f32_dpp v44, v252, v252 quad_perm:[1,0,3,2] row_mask:0xf bank_mask:0xf
	v_add_f32_dpp v45, v253, v253 quad_perm:[1,0,3,2] row_mask:0xf bank_mask:0xf
	v_add_f32_dpp v46, v254, v254 quad_perm:[1,0,3,2] row_mask:0xf bank_mask:0xf
	v_add_f32_dpp v47, v255, v255 quad_perm:[1,0,3,2] row_mask:0xf bank_mask:0xf
	v_cndmask_b32_e32 v44, v46, v44, vcc
	v_cndmask_b32_e32 v45, v47, v45, vcc
	v_add_f32_dpp v50, v48, v48 quad_perm:[2,3,0,1] row_mask:0xf bank_mask:0xf
	v_add_f32_dpp v51, v49, v49 quad_perm:[2,3,0,1] row_mask:0xf bank_mask:0xf
	v_cndmask_b32_e64 v48, v51, v50, s[4:5]
	s_waitcnt vmcnt(9)
	v_pk_mul_f32 v[252:253], v[236:237], v[36:37] op_sel_hi:[1,0]
	v_pk_mul_f32 v[254:255], v[244:245], v[36:37] op_sel_hi:[1,0]
	v_pk_fma_f32 v[252:253], v[238:239], v[36:37], v[252:253] op_sel:[0,1,0]
	v_pk_fma_f32 v[254:255], v[246:247], v[36:37], v[254:255] op_sel:[0,1,0]
	v_pk_fma_f32 v[252:253], v[240:241], v[38:39], v[252:253] op_sel_hi:[1,0,1]
	v_pk_fma_f32 v[254:255], v[248:249], v[38:39], v[254:255] op_sel_hi:[1,0,1]
	v_pk_fma_f32 v[252:253], v[242:243], v[38:39], v[252:253] op_sel:[0,1,0]
	v_pk_fma_f32 v[254:255], v[250:251], v[38:39], v[254:255] op_sel:[0,1,0]
	v_add_f32_dpp v52, v52, v52 row_ror:4 row_mask:0xf bank_mask:0x5
	v_add_f32_dpp v52, v48, v48 row_ror:4 row_mask:0xf bank_mask:0xa
	v_add_f32_dpp v40, v140, v140 quad_perm:[1,0,3,2] row_mask:0xf bank_mask:0xf
	v_add_f32_dpp v41, v141, v141 quad_perm:[1,0,3,2] row_mask:0xf bank_mask:0xf
	v_add_f32_dpp v42, v142, v142 quad_perm:[1,0,3,2] row_mask:0xf bank_mask:0xf
	v_add_f32_dpp v43, v143, v143 quad_perm:[1,0,3,2] row_mask:0xf bank_mask:0xf
	v_cndmask_b32_e32 v40, v42, v40, vcc
	v_cndmask_b32_e32 v41, v43, v41, vcc
	v_add_f32_dpp v46, v44, v44 quad_perm:[2,3,0,1] row_mask:0xf bank_mask:0xf
	v_add_f32_dpp v47, v45, v45 quad_perm:[2,3,0,1] row_mask:0xf bank_mask:0xf
	v_cndmask_b32_e64 v44, v47, v46, s[4:5]
	s_waitcnt vmcnt(8)
	v_pk_mul_f32 v[140:141], v[236:237], v[32:33] op_sel_hi:[1,0]
	v_pk_mul_f32 v[142:143], v[244:245], v[32:33] op_sel_hi:[1,0]
	v_pk_fma_f32 v[140:141], v[238:239], v[32:33], v[140:141] op_sel:[0,1,0]
	v_pk_fma_f32 v[142:143], v[246:247], v[32:33], v[142:143] op_sel:[0,1,0]
	v_pk_fma_f32 v[140:141], v[240:241], v[34:35], v[140:141] op_sel_hi:[1,0,1]
	v_pk_fma_f32 v[142:143], v[248:249], v[34:35], v[142:143] op_sel_hi:[1,0,1]
	v_pk_fma_f32 v[140:141], v[242:243], v[34:35], v[140:141] op_sel:[0,1,0]
	v_pk_fma_f32 v[142:143], v[250:251], v[34:35], v[142:143] op_sel:[0,1,0]
	v_add_f32_dpp v60, v60, v60 row_ror:8 row_mask:0xf bank_mask:0x3
	v_add_f32_dpp v60, v52, v52 row_ror:8 row_mask:0xf bank_mask:0xc
	v_add_f32_dpp v36, v252, v252 quad_perm:[1,0,3,2] row_mask:0xf bank_mask:0xf
	v_add_f32_dpp v37, v253, v253 quad_perm:[1,0,3,2] row_mask:0xf bank_mask:0xf
	v_add_f32_dpp v38, v254, v254 quad_perm:[1,0,3,2] row_mask:0xf bank_mask:0xf
	v_add_f32_dpp v39, v255, v255 quad_perm:[1,0,3,2] row_mask:0xf bank_mask:0xf
	v_cndmask_b32_e32 v36, v38, v36, vcc
	v_cndmask_b32_e32 v37, v39, v37, vcc
	v_add_f32_dpp v42, v40, v40 quad_perm:[2,3,0,1] row_mask:0xf bank_mask:0xf
	v_add_f32_dpp v43, v41, v41 quad_perm:[2,3,0,1] row_mask:0xf bank_mask:0xf
	v_cndmask_b32_e64 v40, v43, v42, s[4:5]
	s_waitcnt vmcnt(7)
; DI void attn_sample_item(const Params& p, int item, ldsp lds, int tid_) {
;     ...
;   SC_SCORE(kvA, 0)
;   SC_SCORE(kvB, 1)
	v_pk_mul_f32 v[252:253], v[236:237], v[28:29] op_sel_hi:[1,0]
	v_pk_mul_f32 v[254:255], v[244:245], v[28:29] op_sel_hi:[1,0]
	v_pk_fma_f32 v[252:253], v[238:239], v[28:29], v[252:253] op_sel:[0,1,0]
	v_pk_fma_f32 v[254:255], v[246:247], v[28:29], v[254:255] op_sel:[0,1,0]
	v_pk_fma_f32 v[252:253], v[240:241], v[30:31], v[252:253] op_sel_hi:[1,0,1]
	v_pk_fma_f32 v[254:255], v[248:249], v[30:31], v[254:255] op_sel_hi:[1,0,1]
	v_pk_fma_f32 v[252:253], v[242:243], v[30:31], v[252:253] op_sel:[0,1,0]
	v_pk_fma_f32 v[254:255], v[250:251], v[30:31], v[254:255] op_sel:[0,1,0]
	v_add_f32_dpp v44, v44, v44 row_ror:4 row_mask:0xf bank_mask:0x5
	v_add_f32_dpp v44, v40, v40 row_ror:4 row_mask:0xf bank_mask:0xa
	v_add_f32_dpp v32, v140, v140 quad_perm:[1,0,3,2] row_mask:0xf bank_mask:0xf
	v_add_f32_dpp v33, v141, v141 quad_perm:[1,0,3,2] row_mask:0xf bank_mask:0xf
	v_add_f32_dpp v34, v142, v142 quad_perm:[1,0,3,2] row_mask:0xf bank_mask:0xf
	v_add_f32_dpp v35, v143, v143 quad_perm:[1,0,3,2] row_mask:0xf bank_mask:0xf
	v_cndmask_b32_e32 v32, v34, v32, vcc
	v_cndmask_b32_e32 v33, v35, v33, vcc
	v_add_f32_dpp v38, v36, v36 quad_perm:[2,3,0,1] row_mask:0xf bank_mask:0xf
	v_add_f32_dpp v39, v37, v37 quad_perm:[2,3,0,1] row_mask:0xf bank_mask:0xf
	v_cndmask_b32_e64 v36, v39, v38, s[4:5]
	s_waitcnt vmcnt(6)
	v_pk_mul_f32 v[140:141], v[236:237], v[24:25] op_sel_hi:[1,0]
	v_pk_mul_f32 v[142:143], v[244:245], v[24:25] op_sel_hi:[1,0]
	v_pk_fma_f32 v[140:141], v[238:239], v[24:25], v[140:141] op_sel:[0,1,0]
	v_pk_fma_f32 v[142:143], v[246:247], v[24:25], v[142:143] op_sel:[0,1,0]
	v_pk_fma_f32 v[140:141], v[240:241], v[26:27], v[140:141] op_sel_hi:[1,0,1]
	v_pk_fma_f32 v[142:143], v[248:249], v[26:27], v[142:143] op_sel_hi:[1,0,1]
	v_pk_fma_f32 v[140:141], v[242:243], v[26:27], v[140:141] op_sel:[0,1,0]
	v_pk_fma_f32 v[142:143], v[250:251], v[26:27], v[142:143] op_sel:[0,1,0]
	v_add_f32_dpp v28, v252, v252 quad_perm:[1,0,3,2] row_mask:0xf bank_mask:0xf
	v_add_f32_dpp v29, v253, v253 quad_perm:[1,0,3,2] row_mask:0xf bank_mask:0xf
	v_add_f32_dpp v30, v254, v254 quad_perm:[1,0,3,2] row_mask:0xf bank_mask:0xf
	v_add_f32_dpp v31, v255, v255 quad_perm:[1,0,3,2] row_mask:0xf bank_mask:0xf
	v_cndmask_b32_e32 v28, v30, v28, vcc
	v_cndmask_b32_e32 v29, v31, v29, vcc
	v_add_f32_dpp v34, v32, v32 quad_perm:[2,3,0,1] row_mask:0xf bank_mask:0xf
	v_add_f32_dpp v35, v33, v33 quad_perm:[2,3,0,1] row_mask:0xf bank_mask:0xf
	v_cndmask_b32_e64 v32, v35, v34, s[4:5]
	s_waitcnt vmcnt(5)
	v_pk_mul_f32 v[252:253], v[236:237], v[20:21] op_sel_hi:[1,0]
	v_pk_mul_f32 v[254:255], v[244:245], v[20:21] op_sel_hi:[1,0]
	v_pk_fma_f32 v[252:253], v[238:239], v[20:21], v[252:253] op_sel:[0,1,0]
	v_pk_fma_f32 v[254:255], v[246:247], v[20:21], v[254:255] op_sel:[0,1,0]
	v_pk_fma_f32 v[252:253], v[240:241], v[22:23], v[252:253] op_sel_hi:[1,0,1]
	v_pk_fma_f32 v[254:255], v[248:249], v[22:23], v[254:255] op_sel_hi:[1,0,1]
	v_pk_fma_f32 v[252:253], v[242:243], v[22:23], v[252:253] op_sel:[0,1,0]
	v_pk_fma_f32 v[254:255], v[250:251], v[22:23], v[254:255] op_sel:[0,1,0]
	v_add_f32_dpp v36, v36, v36 row_ror:4 row_mask:0xf bank_mask:0x5
	v_add_f32_dpp v36, v32, v32 row_ror:4 row_mask:0xf bank_mask:0xa
	v_add_f32_dpp v24, v140, v140 quad_perm:[1,0,3,2] row_mask:0xf bank_mask:0xf
	v_add_f32_dpp v25, v141, v141 quad_perm:[1,0,3,2] row_mask:0xf bank_mask:0xf
	v_add_f32_dpp v26, v142, v142 quad_perm:[1,0,3,2] row_mask:0xf bank_mask:0xf
	v_add_f32_dpp v27, v143, v143 quad_perm:[1,0,3,2] row_mask:0xf bank_mask:0xf
	v_cndmask_b32_e32 v24, v26, v24, vcc
	v_cndmask_b32_e32 v25, v27, v25, vcc
	v_add_f32_dpp v30, v28, v28 quad_perm:[2,3,0,1] row_mask:0xf bank_mask:0xf
	v_add_f32_dpp v31, v29, v29 quad_perm:[2,3,0,1] row_mask:0xf bank_mask:0xf
	v_cndmask_b32_e64 v28, v31, v30, s[4:5]
	s_waitcnt vmcnt(4)
	v_pk_mul_f32 v[140:141], v[236:237], v[16:17] op_sel_hi:[1,0]
	v_pk_mul_f32 v[142:143], v[244:245], v[16:17] op_sel_hi:[1,0]
	v_pk_fma_f32 v[140:141], v[238:239], v[16:17], v[140:141] op_sel:[0,1,0]
	v_pk_fma_f32 v[142:143], v[246:247], v[16:17], v[142:143] op_sel:[0,1,0]
	v_pk_fma_f32 v[140:141], v[240:241], v[18:19], v[140:141] op_sel_hi:[1,0,1]
	v_pk_fma_f32 v[142:143], v[248:249], v[18:19], v[142:143] op_sel_hi:[1,0,1]
	v_pk_fma_f32 v[140:141], v[242:243], v[18:19], v[140:141] op_sel:[0,1,0]
	v_pk_fma_f32 v[142:143], v[250:251], v[18:19], v[142:143] op_sel:[0,1,0]
	v_add_f32_dpp v44, v44, v44 row_ror:8 row_mask:0xf bank_mask:0x3
	v_add_f32_dpp v44, v36, v36 row_ror:8 row_mask:0xf bank_mask:0xc
	v_add_f32_dpp v20, v252, v252 quad_perm:[1,0,3,2] row_mask:0xf bank_mask:0xf
	v_add_f32_dpp v21, v253, v253 quad_perm:[1,0,3,2] row_mask:0xf bank_mask:0xf
	v_add_f32_dpp v22, v254, v254 quad_perm:[1,0,3,2] row_mask:0xf bank_mask:0xf
	v_add_f32_dpp v23, v255, v255 quad_perm:[1,0,3,2] row_mask:0xf bank_mask:0xf
	v_cndmask_b32_e32 v20, v22, v20, vcc
	v_cndmask_b32_e32 v21, v23, v21, vcc
	v_add_f32_dpp v26, v24, v24 quad_perm:[2,3,0,1] row_mask:0xf bank_mask:0xf
	v_add_f32_dpp v27, v25, v25 quad_perm:[2,3,0,1] row_mask:0xf bank_mask:0xf
	v_cndmask_b32_e64 v24, v27, v26, s[4:5]
	s_waitcnt vmcnt(3)
; DI void attn_sample_item(const Params& p, int item, ldsp lds, int tid_) {
;     ...
;   SC_SCORE(kvA, 0)
;   SC_SCORE(kvB, 1)
;     ...
;   f32x4 vvA[16], vvB[16];
; #pragma unroll
;   for (int j = 0; j < 16; ++j) vvA[j] = __builtin_nontemporal_load((const f32x4*)(cv + (size_t)(wid * 32 + j) * 1024 + lane * 4));
	v_pk_mul_f32 v[252:253], v[236:237], v[12:13] op_sel_hi:[1,0]
	v_pk_mul_f32 v[254:255], v[244:245], v[12:13] op_sel_hi:[1,0]
	v_pk_fma_f32 v[252:253], v[238:239], v[12:13], v[252:253] op_sel:[0,1,0]
	v_pk_fma_f32 v[254:255], v[246:247], v[12:13], v[254:255] op_sel:[0,1,0]
	v_pk_fma_f32 v[252:253], v[240:241], v[14:15], v[252:253] op_sel_hi:[1,0,1]
	v_pk_fma_f32 v[254:255], v[248:249], v[14:15], v[254:255] op_sel_hi:[1,0,1]
	v_pk_fma_f32 v[252:253], v[242:243], v[14:15], v[252:253] op_sel:[0,1,0]
	v_pk_fma_f32 v[254:255], v[250:251], v[14:15], v[254:255] op_sel:[0,1,0]
	v_permlane16_swap_b32_e32 v60, v44
	v_add_f32_e32 v60, v60, v44
	v_add_f32_dpp v28, v28, v28 row_ror:4 row_mask:0xf bank_mask:0x5
	v_add_f32_dpp v28, v24, v24 row_ror:4 row_mask:0xf bank_mask:0xa
	v_add_f32_dpp v16, v140, v140 quad_perm:[1,0,3,2] row_mask:0xf bank_mask:0xf
	v_add_f32_dpp v17, v141, v141 quad_perm:[1,0,3,2] row_mask:0xf bank_mask:0xf
	v_add_f32_dpp v18, v142, v142 quad_perm:[1,0,3,2] row_mask:0xf bank_mask:0xf
	v_add_f32_dpp v19, v143, v143 quad_perm:[1,0,3,2] row_mask:0xf bank_mask:0xf
	v_cndmask_b32_e32 v16, v18, v16, vcc
	v_cndmask_b32_e32 v17, v19, v17, vcc
	v_add_f32_dpp v22, v20, v20 quad_perm:[2,3,0,1] row_mask:0xf bank_mask:0xf
	v_add_f32_dpp v23, v21, v21 quad_perm:[2,3,0,1] row_mask:0xf bank_mask:0xf
	v_cndmask_b32_e64 v20, v23, v22, s[4:5]
	s_waitcnt vmcnt(2)
	v_pk_mul_f32 v[140:141], v[236:237], v[8:9] op_sel_hi:[1,0]
	v_pk_mul_f32 v[142:143], v[244:245], v[8:9] op_sel_hi:[1,0]
	v_pk_fma_f32 v[140:141], v[238:239], v[8:9], v[140:141] op_sel:[0,1,0]
	v_pk_fma_f32 v[142:143], v[246:247], v[8:9], v[142:143] op_sel:[0,1,0]
	v_pk_fma_f32 v[140:141], v[240:241], v[10:11], v[140:141] op_sel_hi:[1,0,1]
	v_pk_fma_f32 v[142:143], v[248:249], v[10:11], v[142:143] op_sel_hi:[1,0,1]
	v_pk_fma_f32 v[140:141], v[242:243], v[10:11], v[140:141] op_sel:[0,1,0]
	v_pk_fma_f32 v[142:143], v[250:251], v[10:11], v[142:143] op_sel:[0,1,0]
	v_add_f32_dpp v12, v252, v252 quad_perm:[1,0,3,2] row_mask:0xf bank_mask:0xf
	v_add_f32_dpp v13, v253, v253 quad_perm:[1,0,3,2] row_mask:0xf bank_mask:0xf
	v_add_f32_dpp v14, v254, v254 quad_perm:[1,0,3,2] row_mask:0xf bank_mask:0xf
	v_add_f32_dpp v15, v255, v255 quad_perm:[1,0,3,2] row_mask:0xf bank_mask:0xf
	v_cndmask_b32_e32 v12, v14, v12, vcc
	v_cndmask_b32_e32 v13, v15, v13, vcc
	v_add_f32_dpp v18, v16, v16 quad_perm:[2,3,0,1] row_mask:0xf bank_mask:0xf
	v_add_f32_dpp v19, v17, v17 quad_perm:[2,3,0,1] row_mask:0xf bank_mask:0xf
	v_cndmask_b32_e64 v16, v19, v18, s[4:5]
	s_waitcnt vmcnt(1)
	v_pk_mul_f32 v[252:253], v[236:237], v[4:5] op_sel_hi:[1,0]
	v_pk_mul_f32 v[254:255], v[244:245], v[4:5] op_sel_hi:[1,0]
	v_pk_fma_f32 v[252:253], v[238:239], v[4:5], v[252:253] op_sel:[0,1,0]
	v_pk_fma_f32 v[254:255], v[246:247], v[4:5], v[254:255] op_sel:[0,1,0]
	v_pk_fma_f32 v[252:253], v[240:241], v[6:7], v[252:253] op_sel_hi:[1,0,1]
	v_pk_fma_f32 v[254:255], v[248:249], v[6:7], v[254:255] op_sel_hi:[1,0,1]
	v_pk_fma_f32 v[252:253], v[242:243], v[6:7], v[252:253] op_sel:[0,1,0]
	v_pk_fma_f32 v[254:255], v[250:251], v[6:7], v[254:255] op_sel:[0,1,0]
	v_add_f32_dpp v20, v20, v20 row_ror:4 row_mask:0xf bank_mask:0x5
	v_add_f32_dpp v20, v16, v16 row_ror:4 row_mask:0xf bank_mask:0xa
	v_add_f32_dpp v8, v140, v140 quad_perm:[1,0,3,2] row_mask:0xf bank_mask:0xf
	v_add_f32_dpp v9, v141, v141 quad_perm:[1,0,3,2] row_mask:0xf bank_mask:0xf
	v_add_f32_dpp v10, v142, v142 quad_perm:[1,0,3,2] row_mask:0xf bank_mask:0xf
	v_add_f32_dpp v11, v143, v143 quad_perm:[1,0,3,2] row_mask:0xf bank_mask:0xf
	v_cndmask_b32_e32 v8, v10, v8, vcc
	v_cndmask_b32_e32 v9, v11, v9, vcc
	v_add_f32_dpp v14, v12, v12 quad_perm:[2,3,0,1] row_mask:0xf bank_mask:0xf
	v_add_f32_dpp v15, v13, v13 quad_perm:[2,3,0,1] row_mask:0xf bank_mask:0xf
	v_cndmask_b32_e64 v12, v15, v14, s[4:5]
	s_waitcnt vmcnt(0)
	v_pk_mul_f32 v[140:141], v[236:237], v[0:1] op_sel_hi:[1,0]
	v_pk_mul_f32 v[142:143], v[244:245], v[0:1] op_sel_hi:[1,0]
	v_pk_fma_f32 v[140:141], v[238:239], v[0:1], v[140:141] op_sel:[0,1,0]
	v_pk_fma_f32 v[142:143], v[246:247], v[0:1], v[142:143] op_sel:[0,1,0]
	v_pk_fma_f32 v[140:141], v[240:241], v[2:3], v[140:141] op_sel_hi:[1,0,1]
	v_pk_fma_f32 v[142:143], v[248:249], v[2:3], v[142:143] op_sel_hi:[1,0,1]
	v_pk_fma_f32 v[140:141], v[242:243], v[2:3], v[140:141] op_sel:[0,1,0]
	v_pk_fma_f32 v[142:143], v[250:251], v[2:3], v[142:143] op_sel:[0,1,0]
	v_add_f32_dpp v28, v28, v28 row_ror:8 row_mask:0xf bank_mask:0x3
	v_add_f32_dpp v28, v20, v20 row_ror:8 row_mask:0xf bank_mask:0xc
	v_add_f32_dpp v4, v252, v252 quad_perm:[1,0,3,2] row_mask:0xf bank_mask:0xf
	v_add_f32_dpp v5, v253, v253 quad_perm:[1,0,3,2] row_mask:0xf bank_mask:0xf
	v_add_f32_dpp v6, v254, v254 quad_perm:[1,0,3,2] row_mask:0xf bank_mask:0xf
	v_add_f32_dpp v7, v255, v255 quad_perm:[1,0,3,2] row_mask:0xf bank_mask:0xf
	v_cndmask_b32_e32 v4, v6, v4, vcc
	v_cndmask_b32_e32 v5, v7, v5, vcc
	v_add_f32_dpp v10, v8, v8 quad_perm:[2,3,0,1] row_mask:0xf bank_mask:0xf
	v_add_f32_dpp v11, v9, v9 quad_perm:[2,3,0,1] row_mask:0xf bank_mask:0xf
	v_cndmask_b32_e64 v8, v11, v10, s[4:5]
	v_add_f32_dpp v12, v12, v12 row_ror:4 row_mask:0xf bank_mask:0x5
	s_nop 0
	v_add_f32_dpp v12, v8, v8 row_ror:4 row_mask:0xf bank_mask:0xa
	v_add_f32_dpp v0, v140, v140 quad_perm:[1,0,3,2] row_mask:0xf bank_mask:0xf
	v_add_f32_dpp v1, v141, v141 quad_perm:[1,0,3,2] row_mask:0xf bank_mask:0xf
	v_add_f32_dpp v2, v142, v142 quad_perm:[1,0,3,2] row_mask:0xf bank_mask:0xf
	v_add_f32_dpp v3, v143, v143 quad_perm:[1,0,3,2] row_mask:0xf bank_mask:0xf
	v_cndmask_b32_e32 v0, v2, v0, vcc
	v_cndmask_b32_e32 v1, v3, v1, vcc
	v_add_f32_dpp v6, v4, v4 quad_perm:[2,3,0,1] row_mask:0xf bank_mask:0xf
	v_add_f32_dpp v7, v5, v5 quad_perm:[2,3,0,1] row_mask:0xf bank_mask:0xf
	v_cndmask_b32_e64 v4, v7, v6, s[4:5]
	v_add_f32_dpp v2, v0, v0 quad_perm:[2,3,0,1] row_mask:0xf bank_mask:0xf
	v_add_f32_dpp v3, v1, v1 quad_perm:[2,3,0,1] row_mask:0xf bank_mask:0xf
	v_cndmask_b32_e64 v0, v3, v2, s[4:5]
	v_add_f32_dpp v4, v4, v4 row_ror:4 row_mask:0xf bank_mask:0x5
	s_nop 0
	v_add_f32_dpp v4, v0, v0 row_ror:4 row_mask:0xf bank_mask:0xa
	v_add_f32_dpp v12, v12, v12 row_ror:8 row_mask:0xf bank_mask:0x3
	s_nop 0
	v_add_f32_dpp v12, v4, v4 row_ror:8 row_mask:0xf bank_mask:0xc
	s_nop 1
	v_permlane16_swap_b32_e32 v28, v12
	v_add_f32_e32 v28, v28, v12
	s_nop 1
	v_permlane32_swap_b32_e32 v60, v28
	v_add_f32_e32 v60, v60, v28
	ds_write_b32 v235, v60 offset:64
	v_lshlrev_b32_e32 v2, 2, v223
	s_add_u32 s4, s14, s30
	s_addc_u32 s5, s15, s31
	v_lshlrev_b32_e32 v0, 2, v2
	s_waitcnt lgkmcnt(0)
; DI void lbar() { asm volatile("s_waitcnt lgkmcnt(0)" ::: "memory"); __builtin_amdgcn_s_barrier(); asm volatile("" ::: "memory"); }
; DI float wave_sum(float v) { for (int o = 32; o >= 1; o >>= 1) v += __shfl_xor(v, o); return v; }
; DI void attn_sample_item(const Params& p, int item, ldsp lds, int tid_) {
;     ...
;   for (int j = 0; j < 16; ++j) vvA[j] = __builtin_nontemporal_load((const f32x4*)(cv + (size_t)(wid * 32 + j) * 1024 + lane * 4));
;   lbar();
;   if (wid < 4) {
;     float v[4]; float mx = -1e30f;
; #pragma unroll
;     for (int j = 0; j < 4; ++j) { v[j] = SC[wid * 256 + j * 64 + lane]; mx = fmaxf(mx, v[j]); }
;     for (int o = 32; o >= 1; o >>= 1) mx = fmaxf(mx, __shfl_xor(mx, o));
;     float s = 0.f;
; #pragma unroll
;     for (int j = 0; j < 4; ++j) { v[j] = __expf(v[j] - mx); s += v[j]; }
;     s = wave_sum(s); const float inv = 1.f / s;
; #pragma unroll
;     for (int j = 0; j < 4; ++j) SC[wid * 256 + j * 64 + lane] = v[j] * inv;
;   }
	v_mov_b32_e32 v1, v145
	v_lshl_add_u64 v[0:1], s[4:5], 0, v[0:1]
	v_lshl_add_u64 v[4:5], v[0:1], 0, v[162:163]
	v_lshl_add_u64 v[6:7], v[0:1], 0, v[166:167]
	global_load_dwordx4 v[100:103], v[4:5], off nt
	global_load_dwordx4 v[92:95], v[6:7], off nt
	v_lshl_add_u64 v[4:5], v[0:1], 0, v[168:169]
	v_lshl_add_u64 v[6:7], v[0:1], 0, v[172:173]
	global_load_dwordx4 v[112:115], v[4:5], off nt
	global_load_dwordx4 v[108:111], v[6:7], off nt
	v_lshl_add_u64 v[4:5], v[0:1], 0, v[176:177]
	v_lshl_add_u64 v[6:7], v[0:1], 0, v[180:181]
	global_load_dwordx4 v[120:123], v[4:5], off nt
	global_load_dwordx4 v[116:119], v[6:7], off nt
	v_lshl_add_u64 v[4:5], v[0:1], 0, v[182:183]
	v_lshl_add_u64 v[6:7], v[0:1], 0, v[186:187]
	global_load_dwordx4 v[124:127], v[4:5], off nt
	global_load_dwordx4 v[104:107], v[6:7], off nt
	v_lshl_add_u64 v[4:5], v[0:1], 0, v[190:191]
	v_lshl_add_u64 v[6:7], v[0:1], 0, v[194:195]
	global_load_dwordx4 v[68:71], v[4:5], off nt
	global_load_dwordx4 v[64:67], v[6:7], off nt
	v_lshl_add_u64 v[4:5], v[0:1], 0, v[198:199]
	v_lshl_add_u64 v[6:7], v[0:1], 0, v[200:201]
	global_load_dwordx4 v[80:83], v[4:5], off nt
	global_load_dwordx4 v[76:79], v[6:7], off nt
	v_lshl_add_u64 v[4:5], v[0:1], 0, v[202:203]
	v_lshl_add_u64 v[6:7], v[0:1], 0, v[204:205]
	global_load_dwordx4 v[88:91], v[4:5], off nt
	global_load_dwordx4 v[84:87], v[6:7], off nt
	v_lshl_add_u64 v[4:5], v[0:1], 0, v[206:207]
	v_lshl_add_u64 v[6:7], v[0:1], 0, v[208:209]
	global_load_dwordx4 v[96:99], v[4:5], off nt
	global_load_dwordx4 v[72:75], v[6:7], off nt
	s_waitcnt lgkmcnt(0)
	s_barrier
	v_cmp_gt_i32_e32 vcc, 4, v210
	s_and_saveexec_b64 s[4:5], vcc
	s_cbranch_execz .LBB0_1603
	v_lshlrev_b32_e32 v3, 10, v210
	v_add3_u32 v6, 16, v3, v2
	ds_read2st64_b32 v[2:3], v6 offset1:1
	ds_read2st64_b32 v[4:5], v6 offset0:2 offset1:3
	s_waitcnt lgkmcnt(1)
	v_max3_f32 v7, v2, s39, v3
	s_waitcnt lgkmcnt(0)
	v_max3_f32 v7, v7, v4, v5
	ds_bpermute_b32 v8, v133, v7
	s_waitcnt lgkmcnt(0)
	v_max_f32_e32 v8, v8, v8
	v_max_f32_e32 v7, v7, v8
	ds_bpermute_b32 v8, v132, v7
	s_waitcnt lgkmcnt(0)
	v_max_f32_e32 v8, v8, v8
	v_max_f32_e32 v7, v7, v8
	ds_bpermute_b32 v8, v131, v7
	s_waitcnt lgkmcnt(0)
	v_max_f32_e32 v8, v8, v8
	v_max_f32_e32 v7, v7, v8
	ds_bpermute_b32 v8, v130, v7
	s_waitcnt lgkmcnt(0)
	v_max_f32_e32 v8, v8, v8
	v_max_f32_e32 v7, v7, v8
	ds_bpermute_b32 v8, v129, v7
	s_waitcnt lgkmcnt(0)
	v_max_f32_e32 v8, v8, v8
	v_max_f32_e32 v7, v7, v8
	ds_bpermute_b32 v8, v128, v7
	s_waitcnt lgkmcnt(0)
	v_max_f32_e32 v8, v8, v8
	v_max_f32_e32 v7, v7, v8
	v_sub_f32_e32 v2, v2, v7
	v_sub_f32_e32 v3, v3, v7
	v_mul_f32_e32 v2, 0x3fb8aa3b, v2
	v_sub_f32_e32 v4, v4, v7
	v_mul_f32_e32 v3, 0x3fb8aa3b, v3
	v_exp_f32_e32 v2, v2
	v_sub_f32_e32 v5, v5, v7
	v_mul_f32_e32 v4, 0x3fb8aa3b, v4
	v_exp_f32_e32 v3, v3
	v_mul_f32_e32 v5, 0x3fb8aa3b, v5
	v_exp_f32_e32 v4, v4
	v_exp_f32_e32 v5, v5
	v_add_f32_e32 v7, 0, v2
	v_add_f32_e32 v7, v3, v7
	v_add_f32_e32 v7, v4, v7
	v_add_f32_e32 v7, v5, v7
	ds_bpermute_b32 v8, v133, v7
	s_waitcnt lgkmcnt(0)
	v_add_f32_e32 v7, v7, v8
	ds_bpermute_b32 v8, v132, v7
	s_waitcnt lgkmcnt(0)
	v_add_f32_e32 v7, v7, v8
	ds_bpermute_b32 v8, v131, v7
	s_waitcnt lgkmcnt(0)
	v_add_f32_e32 v7, v7, v8
	ds_bpermute_b32 v8, v130, v7
	s_waitcnt lgkmcnt(0)
	v_add_f32_e32 v7, v7, v8
	ds_bpermute_b32 v8, v129, v7
	s_waitcnt lgkmcnt(0)
	v_add_f32_e32 v7, v7, v8
	ds_bpermute_b32 v8, v128, v7
	s_waitcnt lgkmcnt(0)
	v_add_f32_e32 v7, v7, v8
	v_div_scale_f32 v8, s[6:7], v7, v7, 1.0
	v_rcp_f32_e32 v9, v8
	v_div_scale_f32 v10, vcc, 1.0, v7, 1.0
	v_fma_f32 v11, -v8, v9, 1.0
	v_fmac_f32_e32 v9, v11, v9
	v_mul_f32_e32 v11, v10, v9
	v_fma_f32 v12, -v8, v11, v10
	v_fmac_f32_e32 v11, v12, v9
	v_fma_f32 v8, -v8, v11, v10
	v_div_fmas_f32 v8, v8, v9, v11
	v_div_fixup_f32 v7, v8, v7, 1.0
	v_mul_f32_e32 v2, v2, v7
	v_mul_f32_e32 v3, v3, v7
	v_mul_f32_e32 v4, v4, v7
	v_mul_f32_e32 v5, v5, v7
	ds_write2st64_b32 v6, v2, v3 offset1:1
	ds_write2st64_b32 v6, v4, v5 offset0:2 offset1:3
	s_branch .LBB0_1603

; #define LAS __attribute__((address_space(3)))
; DI void attn_sample_item(const Params& p, int item, ldsp lds, int tid_) {
;     ...
;   const int b = item >> 2, h = item & 3;
;   bf16_t* qx = (bf16_t*)(p.ws + B_QX);
;   const float* ck = p.in[6] + ((size_t)b * 256 * 4 + h) * 256;
;   const float* cv = p.in[7] + ((size_t)b * 256 * 4 + h) * 256;
;   LAS float* SC = (LAS float*)lds;
;   LAS float* PART = (LAS float*)(lds + 4096);
;   float q[4][4];
; #pragma unroll
;   for (int t = 0; t < 4; ++t) { f32x4 a = {0.f, 0.f, 0.f, 0.f}; const float* pp = (const float*)(p.ws + B_PART) + (size_t)(b * 4 + t) * 1024 + h * 256 + lane * 4;
; #pragma unroll
;     for (int kp = 0; kp < 4; ++kp) a += *(const f32x4*)(pp + (size_t)kp * 512 * 1024);
;     q[t][0] = a[0] * 0.0625f; q[t][1] = a[1] * 0.0625f; q[t][2] = a[2] * 0.0625f; q[t][3] = a[3] * 0.0625f; }
;   const bool b0 = lane & 1, b1 = lane & 2;
;   f32x4 kvA[16], kvB[16];
; #pragma unroll
;   for (int j = 0; j < 16; ++j) kvA[j] = __builtin_nontemporal_load((const f32x4*)(ck + (size_t)(wid * 32 + j) * 1024 + lane * 4));
; #pragma unroll
;   for (int j = 0; j < 16; ++j) kvB[j] = __builtin_nontemporal_load((const f32x4*)(ck + (size_t)(wid * 32 + 16 + j) * 1024 + lane * 4));
.LBB0_1676:
	s_ashr_i32 s4, s38, 2
	s_ashr_i32 s5, s4, 31
	s_lshl_b64 s[4:5], s[4:5], 18
	s_and_b32 s24, s0, 0x300
	v_mov_b32_e32 v222, v212
	s_or_b32 s4, s4, s24
	s_and_b32 s26, s38, -4
	s_lshl_b32 s6, s24, 2
	s_add_u32 s6, s36, s6
	v_and_b32_e32 v223, 63, v222
	s_addc_u32 s7, s37, 0
	v_lshlrev_b32_e32 v144, 4, v223
	s_ashr_i32 s27, s26, 31
	v_lshl_add_u64 v[48:49], s[6:7], 0, v[144:145]
	s_lshl_b64 s[6:7], s[26:27], 12
	v_lshl_add_u64 v[8:9], v[48:49], 0, s[6:7]
	v_add_co_u32_e32 v10, vcc, s3, v8
	s_or_b32 s6, s26, 1
	s_nop 0
	v_addc_co_u32_e32 v11, vcc, 0, v9, vcc
	global_load_dwordx4 v[0:3], v[8:9], off
	global_load_dwordx4 v[4:7], v[10:11], off
	v_add_co_u32_e32 v10, vcc, s33, v8
	s_ashr_i32 s7, s6, 31
	s_nop 0
	v_addc_co_u32_e32 v11, vcc, 0, v9, vcc
	v_add_co_u32_e32 v12, vcc, s34, v8
	s_lshl_b64 s[6:7], s[6:7], 12
	s_nop 0
	v_addc_co_u32_e32 v13, vcc, 0, v9, vcc
	v_lshl_add_u64 v[24:25], v[48:49], 0, s[6:7]
	v_add_co_u32_e32 v20, vcc, s3, v24
	s_or_b32 s6, s26, 2
	s_nop 0
	v_addc_co_u32_e32 v21, vcc, 0, v25, vcc
	v_add_co_u32_e32 v26, vcc, s33, v24
	s_ashr_i32 s7, s6, 31
	s_nop 0
	v_addc_co_u32_e32 v27, vcc, 0, v25, vcc
	v_add_co_u32_e32 v28, vcc, s34, v24
	s_lshl_b64 s[6:7], s[6:7], 12
	s_nop 0
	v_addc_co_u32_e32 v29, vcc, 0, v25, vcc
	v_lshl_add_u64 v[44:45], v[48:49], 0, s[6:7]
	global_load_dwordx4 v[8:11], v[10:11], off
	s_nop 0
	global_load_dwordx4 v[12:15], v[12:13], off
	s_nop 0
	global_load_dwordx4 v[16:19], v[24:25], off
	s_nop 0
	global_load_dwordx4 v[20:23], v[20:21], off
	v_add_co_u32_e32 v36, vcc, s3, v44
	global_load_dwordx4 v[24:27], v[26:27], off
	s_nop 0
	global_load_dwordx4 v[28:31], v[28:29], off
	v_addc_co_u32_e32 v37, vcc, 0, v45, vcc
	v_add_co_u32_e32 v40, vcc, s33, v44
	global_load_dwordx4 v[32:35], v[44:45], off
	s_nop 0
	global_load_dwordx4 v[36:39], v[36:37], off
	v_addc_co_u32_e32 v41, vcc, 0, v45, vcc
	v_add_co_u32_e32 v44, vcc, s34, v44
	global_load_dwordx4 v[40:43], v[40:41], off
	s_nop 0
	v_addc_co_u32_e32 v45, vcc, 0, v45, vcc
	global_load_dwordx4 v[44:47], v[44:45], off
	s_or_b32 s6, s38, 3
	s_ashr_i32 s7, s6, 31
	s_lshl_b64 s[6:7], s[6:7], 12
	s_lshl_b64 s[28:29], s[4:5], 2
	s_add_u32 s4, s12, s28
	s_addc_u32 s5, s13, s29
	s_waitcnt vmcnt(11)
	v_pk_add_f32 v[2:3], v[2:3], 0 op_sel_hi:[1,0]
	v_pk_add_f32 v[0:1], v[0:1], 0 op_sel_hi:[1,0]
	s_waitcnt vmcnt(10)
	v_pk_add_f32 v[2:3], v[2:3], v[6:7]
	v_pk_add_f32 v[0:1], v[0:1], v[4:5]
	s_waitcnt vmcnt(9)
	v_pk_add_f32 v[2:3], v[2:3], v[10:11]
	s_waitcnt vmcnt(7)
	v_pk_add_f32 v[4:5], v[18:19], 0 op_sel_hi:[1,0]
	v_pk_add_f32 v[6:7], v[16:17], 0 op_sel_hi:[1,0]
	v_pk_add_f32 v[0:1], v[0:1], v[8:9]
	s_waitcnt vmcnt(6)
	v_pk_add_f32 v[4:5], v[4:5], v[22:23]
	v_pk_add_f32 v[6:7], v[6:7], v[20:21]
	v_pk_add_f32 v[2:3], v[2:3], v[14:15]
	v_pk_add_f32 v[0:1], v[0:1], v[12:13]
	s_waitcnt vmcnt(5)
	v_pk_add_f32 v[4:5], v[4:5], v[26:27]
	v_pk_add_f32 v[6:7], v[6:7], v[24:25]
	v_mul_f32_e32 v228, 0x3d800000, v0
	v_mul_f32_e32 v231, 0x3d800000, v1
	v_mul_f32_e32 v229, 0x3d800000, v2
	v_mul_f32_e32 v225, 0x3d800000, v3
	s_waitcnt vmcnt(4)
	v_pk_add_f32 v[0:1], v[4:5], v[30:31]
	v_pk_add_f32 v[2:3], v[6:7], v[28:29]
	v_mul_f32_e32 v227, 0x3d800000, v0
	v_mul_f32_e32 v226, 0x3d800000, v2
	v_mul_f32_e32 v230, 0x3d800000, v3
	v_mul_f32_e32 v224, 0x3d800000, v1
	s_waitcnt vmcnt(3)
	v_pk_add_f32 v[0:1], v[34:35], 0 op_sel_hi:[1,0]
	v_pk_add_f32 v[2:3], v[32:33], 0 op_sel_hi:[1,0]
	s_waitcnt vmcnt(2)
	v_pk_add_f32 v[0:1], v[0:1], v[38:39]
	v_pk_add_f32 v[2:3], v[2:3], v[36:37]
	s_waitcnt vmcnt(1)
	v_pk_add_f32 v[0:1], v[0:1], v[42:43]
	v_pk_add_f32 v[2:3], v[2:3], v[40:41]
	s_waitcnt vmcnt(0)
	v_pk_add_f32 v[210:211], v[0:1], v[46:47]
	v_pk_add_f32 v[0:1], v[2:3], v[44:45]
	v_mul_f32_e32 v233, 0x3d800000, v210
	v_mul_f32_e32 v232, 0x3d800000, v0
	v_mul_f32_e32 v234, 0x3d800000, v1
	v_lshl_add_u64 v[0:1], v[48:49], 0, s[6:7]
	v_add_co_u32_e32 v2, vcc, s3, v0
	v_ashrrev_i32_e32 v210, 6, v222
	s_nop 0
	v_addc_co_u32_e32 v3, vcc, 0, v1, vcc
	global_load_dwordx4 v[128:131], v[0:1], off
	global_load_dwordx4 v[132:135], v[2:3], off
	v_add_co_u32_e32 v2, vcc, s33, v0
	v_mul_f32_e32 v211, 0x3d800000, v211
	s_nop 0
	v_addc_co_u32_e32 v3, vcc, 0, v1, vcc
	v_add_co_u32_e32 v0, vcc, s34, v0
	v_cmp_lt_i32_e64 s[6:7], v218, v216
	s_nop 0
	v_addc_co_u32_e32 v1, vcc, 0, v1, vcc
	global_load_dwordx4 v[136:139], v[2:3], off
	global_load_dwordx4 v[140:143], v[0:1], off
	v_lshlrev_b32_e32 v0, 5, v210
	v_ashrrev_i32_e32 v1, 31, v0
	v_or_b32_e32 v6, 1, v0
	v_lshl_add_u64 v[2:3], s[4:5], 0, v[144:145]
	v_lshlrev_b64 v[158:159], 12, v[0:1]
	v_ashrrev_i32_e32 v7, 31, v6
	v_lshl_add_u64 v[4:5], v[2:3], 0, v[158:159]
	v_lshlrev_b64 v[162:163], 12, v[6:7]
	v_lshl_add_u64 v[6:7], v[2:3], 0, v[162:163]
	global_load_dwordx4 v[124:127], v[4:5], off nt
	global_load_dwordx4 v[120:123], v[6:7], off nt
	v_or_b32_e32 v4, 2, v0
	v_ashrrev_i32_e32 v5, 31, v4
	v_or_b32_e32 v6, 3, v0
	v_lshlrev_b64 v[164:165], 12, v[4:5]
	v_ashrrev_i32_e32 v7, 31, v6
	v_lshl_add_u64 v[4:5], v[2:3], 0, v[164:165]
	v_lshlrev_b64 v[168:169], 12, v[6:7]
	v_lshl_add_u64 v[6:7], v[2:3], 0, v[168:169]
	global_load_dwordx4 v[116:119], v[4:5], off nt
	global_load_dwordx4 v[112:115], v[6:7], off nt
	v_or_b32_e32 v4, 4, v0
	v_ashrrev_i32_e32 v5, 31, v4
	v_or_b32_e32 v6, 5, v0
	v_lshlrev_b64 v[172:173], 12, v[4:5]
	v_ashrrev_i32_e32 v7, 31, v6
	v_lshl_add_u64 v[4:5], v[2:3], 0, v[172:173]
	v_lshlrev_b64 v[176:177], 12, v[6:7]
	v_lshl_add_u64 v[6:7], v[2:3], 0, v[176:177]
	global_load_dwordx4 v[108:111], v[4:5], off nt
	global_load_dwordx4 v[104:107], v[6:7], off nt
	v_or_b32_e32 v4, 6, v0
	v_ashrrev_i32_e32 v5, 31, v4
	v_or_b32_e32 v6, 7, v0
; DI void attn_sample_item(const Params& p, int item, ldsp lds, int tid_) {
;     ...
;   for (int t = 0; t < 4; ++t) { f32x4 a = {0.f, 0.f, 0.f, 0.f}; const float* pp = (const float*)(p.ws + B_PART) + (size_t)(b * 4 + t) * 1024 + h * 256 + lane * 4;
; #pragma unroll
;     for (int kp = 0; kp < 4; ++kp) a += *(const f32x4*)(pp + (size_t)kp * 512 * 1024);
;     q[t][0] = a[0] * 0.0625f; q[t][1] = a[1] * 0.0625f; q[t][2] = a[2] * 0.0625f; q[t][3] = a[3] * 0.0625f; }
;   const bool b0 = lane & 1, b1 = lane & 2;
;   f32x4 kvA[16], kvB[16];
; #pragma unroll
;   for (int j = 0; j < 16; ++j) kvA[j] = __builtin_nontemporal_load((const f32x4*)(ck + (size_t)(wid * 32 + j) * 1024 + lane * 4));
; #pragma unroll
;   for (int j = 0; j < 16; ++j) kvB[j] = __builtin_nontemporal_load((const f32x4*)(ck + (size_t)(wid * 32 + 16 + j) * 1024 + lane * 4));
	v_lshlrev_b64 v[180:181], 12, v[4:5]
	v_ashrrev_i32_e32 v7, 31, v6
	v_lshl_add_u64 v[4:5], v[2:3], 0, v[180:181]
	v_lshlrev_b64 v[184:185], 12, v[6:7]
	v_lshl_add_u64 v[6:7], v[2:3], 0, v[184:185]
	global_load_dwordx4 v[100:103], v[4:5], off nt
	global_load_dwordx4 v[96:99], v[6:7], off nt
	v_or_b32_e32 v4, 8, v0
	v_ashrrev_i32_e32 v5, 31, v4
	v_or_b32_e32 v6, 9, v0
	v_lshlrev_b64 v[188:189], 12, v[4:5]
	v_ashrrev_i32_e32 v7, 31, v6
	v_lshl_add_u64 v[4:5], v[2:3], 0, v[188:189]
	v_lshlrev_b64 v[192:193], 12, v[6:7]
	v_lshl_add_u64 v[6:7], v[2:3], 0, v[192:193]
	global_load_dwordx4 v[92:95], v[4:5], off nt
	global_load_dwordx4 v[88:91], v[6:7], off nt
	v_or_b32_e32 v4, 10, v0
	v_ashrrev_i32_e32 v5, 31, v4
	v_or_b32_e32 v6, 11, v0
	v_lshlrev_b64 v[196:197], 12, v[4:5]
	v_ashrrev_i32_e32 v7, 31, v6
	v_lshl_add_u64 v[4:5], v[2:3], 0, v[196:197]
	v_lshlrev_b64 v[200:201], 12, v[6:7]
	v_lshl_add_u64 v[6:7], v[2:3], 0, v[200:201]
	global_load_dwordx4 v[84:87], v[4:5], off nt
	global_load_dwordx4 v[80:83], v[6:7], off nt
	v_or_b32_e32 v4, 12, v0
	v_ashrrev_i32_e32 v5, 31, v4
	v_or_b32_e32 v6, 13, v0
	v_lshlrev_b64 v[202:203], 12, v[4:5]
	v_ashrrev_i32_e32 v7, 31, v6
	v_lshl_add_u64 v[4:5], v[2:3], 0, v[202:203]
	v_lshlrev_b64 v[204:205], 12, v[6:7]
	v_lshl_add_u64 v[6:7], v[2:3], 0, v[204:205]
	global_load_dwordx4 v[76:79], v[4:5], off nt
	global_load_dwordx4 v[72:75], v[6:7], off nt
	v_or_b32_e32 v4, 14, v0
	v_ashrrev_i32_e32 v5, 31, v4
	v_or_b32_e32 v6, 15, v0
	v_lshlrev_b64 v[206:207], 12, v[4:5]
	v_ashrrev_i32_e32 v7, 31, v6
	v_lshl_add_u64 v[4:5], v[2:3], 0, v[206:207]
	v_lshlrev_b64 v[208:209], 12, v[6:7]
	v_lshl_add_u64 v[6:7], v[2:3], 0, v[208:209]
	global_load_dwordx4 v[68:71], v[4:5], off nt
	global_load_dwordx4 v[64:67], v[6:7], off nt
	v_or_b32_e32 v4, 16, v0
	v_ashrrev_i32_e32 v5, 31, v4
	v_or_b32_e32 v6, 17, v0
	v_lshlrev_b64 v[146:147], 12, v[4:5]
	v_ashrrev_i32_e32 v7, 31, v6
	v_lshl_add_u64 v[4:5], v[2:3], 0, v[146:147]
	v_lshlrev_b64 v[148:149], 12, v[6:7]
	v_lshl_add_u64 v[6:7], v[2:3], 0, v[148:149]
	global_load_dwordx4 v[60:63], v[4:5], off nt
	global_load_dwordx4 v[56:59], v[6:7], off nt
	v_or_b32_e32 v4, 18, v0
	v_ashrrev_i32_e32 v5, 31, v4
	v_or_b32_e32 v6, 19, v0
	v_lshlrev_b64 v[150:151], 12, v[4:5]
	v_ashrrev_i32_e32 v7, 31, v6
	v_lshl_add_u64 v[4:5], v[2:3], 0, v[150:151]
	v_lshlrev_b64 v[152:153], 12, v[6:7]
	v_lshl_add_u64 v[6:7], v[2:3], 0, v[152:153]
	global_load_dwordx4 v[52:55], v[4:5], off nt
	global_load_dwordx4 v[48:51], v[6:7], off nt
	v_or_b32_e32 v4, 20, v0
	v_ashrrev_i32_e32 v5, 31, v4
	v_or_b32_e32 v6, 21, v0
	v_lshlrev_b64 v[154:155], 12, v[4:5]
	v_ashrrev_i32_e32 v7, 31, v6
	v_lshl_add_u64 v[4:5], v[2:3], 0, v[154:155]
	v_lshlrev_b64 v[156:157], 12, v[6:7]
	v_lshl_add_u64 v[6:7], v[2:3], 0, v[156:157]
	global_load_dwordx4 v[44:47], v[4:5], off nt
	global_load_dwordx4 v[40:43], v[6:7], off nt
	v_or_b32_e32 v4, 22, v0
	v_ashrrev_i32_e32 v5, 31, v4
	v_or_b32_e32 v6, 23, v0
	v_lshlrev_b64 v[160:161], 12, v[4:5]
	v_ashrrev_i32_e32 v7, 31, v6
	v_lshl_add_u64 v[4:5], v[2:3], 0, v[160:161]
	v_lshlrev_b64 v[166:167], 12, v[6:7]
	v_lshl_add_u64 v[6:7], v[2:3], 0, v[166:167]
	global_load_dwordx4 v[36:39], v[4:5], off nt
	global_load_dwordx4 v[32:35], v[6:7], off nt
	v_or_b32_e32 v4, 24, v0
	v_ashrrev_i32_e32 v5, 31, v4
	v_or_b32_e32 v6, 25, v0
	v_lshlrev_b64 v[170:171], 12, v[4:5]
	v_ashrrev_i32_e32 v7, 31, v6
	v_lshl_add_u64 v[4:5], v[2:3], 0, v[170:171]
	v_lshlrev_b64 v[174:175], 12, v[6:7]
	v_lshl_add_u64 v[6:7], v[2:3], 0, v[174:175]
	global_load_dwordx4 v[28:31], v[4:5], off nt
	global_load_dwordx4 v[24:27], v[6:7], off nt
	v_or_b32_e32 v4, 26, v0
	v_ashrrev_i32_e32 v5, 31, v4
	v_or_b32_e32 v6, 27, v0
	v_lshlrev_b64 v[178:179], 12, v[4:5]
	v_ashrrev_i32_e32 v7, 31, v6
	v_lshl_add_u64 v[4:5], v[2:3], 0, v[178:179]
	v_lshlrev_b64 v[182:183], 12, v[6:7]
	v_lshl_add_u64 v[6:7], v[2:3], 0, v[182:183]
	global_load_dwordx4 v[20:23], v[4:5], off nt
	global_load_dwordx4 v[16:19], v[6:7], off nt
	v_or_b32_e32 v4, 28, v0
	v_ashrrev_i32_e32 v5, 31, v4
	v_or_b32_e32 v6, 29, v0
	v_lshlrev_b64 v[186:187], 12, v[4:5]
	v_ashrrev_i32_e32 v7, 31, v6
	v_lshl_add_u64 v[4:5], v[2:3], 0, v[186:187]
	v_lshlrev_b64 v[190:191], 12, v[6:7]
	v_lshl_add_u64 v[6:7], v[2:3], 0, v[190:191]
	global_load_dwordx4 v[12:15], v[4:5], off nt
	global_load_dwordx4 v[8:11], v[6:7], off nt
	v_or_b32_e32 v4, 30, v0
	v_or_b32_e32 v0, 31, v0
	v_ashrrev_i32_e32 v5, 31, v4
	v_ashrrev_i32_e32 v1, 31, v0
	v_lshlrev_b64 v[194:195], 12, v[4:5]
	v_lshlrev_b64 v[198:199], 12, v[0:1]
	v_lshl_add_u64 v[4:5], v[2:3], 0, v[194:195]
	v_lshl_add_u64 v[0:1], v[2:3], 0, v[198:199]
	global_load_dwordx4 v[4:7], v[4:5], off nt
	s_nop 0
	global_load_dwordx4 v[0:3], v[0:1], off nt
	s_waitcnt vmcnt(35)
	v_pk_add_f32 v[128:129], v[128:129], 0 op_sel_hi:[1,0]
	v_pk_add_f32 v[130:131], v[130:131], 0 op_sel_hi:[1,0]
	s_waitcnt vmcnt(34)
	v_pk_add_f32 v[128:129], v[128:129], v[132:133]
	v_pk_add_f32 v[130:131], v[130:131], v[134:135]
	s_waitcnt vmcnt(33)
	v_pk_add_f32 v[128:129], v[128:129], v[136:137]
	v_pk_add_f32 v[130:131], v[130:131], v[138:139]
	s_waitcnt vmcnt(32)
; DI void attn_sample_item(const Params& p, int item, ldsp lds, int tid_) {
;     ...
;   for (int t = 0; t < 4; ++t) { f32x4 a = {0.f, 0.f, 0.f, 0.f}; const float* pp = (const float*)(p.ws + B_PART) + (size_t)(b * 4 + t) * 1024 + h * 256 + lane * 4;
; #pragma unroll
;     for (int kp = 0; kp < 4; ++kp) a += *(const f32x4*)(pp + (size_t)kp * 512 * 1024);
;     q[t][0] = a[0] * 0.0625f; q[t][1] = a[1] * 0.0625f; q[t][2] = a[2] * 0.0625f; q[t][3] = a[3] * 0.0625f; }
;   const bool b0 = lane & 1, b1 = lane & 2;
;   f32x4 kvA[16], kvB[16];
; #pragma unroll
;   for (int j = 0; j < 16; ++j) kvA[j] = __builtin_nontemporal_load((const f32x4*)(ck + (size_t)(wid * 32 + j) * 1024 + lane * 4));
; #pragma unroll
;   for (int j = 0; j < 16; ++j) kvB[j] = __builtin_nontemporal_load((const f32x4*)(ck + (size_t)(wid * 32 + 16 + j) * 1024 + lane * 4));
;     ...
;   SC_SCORE(kvA, 0)
;   SC_SCORE(kvB, 1)
	v_pk_add_f32 v[128:129], v[128:129], v[140:141]
	v_pk_add_f32 v[130:131], v[130:131], v[142:143]
	v_mul_f32_e32 v138, 0x3d800000, v129
	v_mul_f32_e32 v135, 0x3d800000, v128
	v_mul_f32_e32 v134, 0x3d800000, v131
	v_mul_f32_e32 v137, 0x3d800000, v130
	v_lshlrev_b32_e32 v128, 2, v215
	v_lshlrev_b32_e32 v129, 2, v217
	v_lshlrev_b32_e32 v130, 2, v218
	v_lshlrev_b32_e32 v131, 2, v219
	v_lshlrev_b32_e32 v132, 2, v220
	v_lshlrev_b32_e32 v133, 2, v221
	v_lshl_add_u32 v136, v210, 7, 16
	v_and_b32_e32 v139, 3, v223
	v_bfrev_b32_e32 v139, v139
	v_lshrrev_b32_e32 v139, 20, v139
	v_and_b32_e32 v235, -4, v223
	v_add3_u32 v235, v136, v139, v235
	v_mov_b32_e32 v236, v228
	v_mov_b32_e32 v237, v226
	v_mov_b32_e32 v238, v231
	v_mov_b32_e32 v239, v230
	v_mov_b32_e32 v240, v229
	v_mov_b32_e32 v241, v227
	v_mov_b32_e32 v242, v225
	v_mov_b32_e32 v243, v224
	v_mov_b32_e32 v244, v232
	v_mov_b32_e32 v245, v135
	v_mov_b32_e32 v246, v234
	v_mov_b32_e32 v247, v138
	v_mov_b32_e32 v248, v233
	v_mov_b32_e32 v249, v137
	v_mov_b32_e32 v250, v211
	v_mov_b32_e32 v251, v134
	s_mov_b32 vcc_lo, 0x55555555
	s_mov_b32 vcc_hi, 0x55555555
	s_mov_b32 s4, 0x33333333
	s_mov_b32 s5, 0x33333333
	s_mov_b32 s6, 0x0f0f0f0f
	s_mov_b32 s7, 0x0f0f0f0f
	s_mov_b32 s64, 0x00ff00ff
	s_mov_b32 s65, 0x00ff00ff
	s_waitcnt vmcnt(31)
	v_pk_mul_f32 v[252:253], v[236:237], v[124:125] op_sel_hi:[1,0]
	v_pk_mul_f32 v[254:255], v[244:245], v[124:125] op_sel_hi:[1,0]
	v_pk_fma_f32 v[252:253], v[238:239], v[124:125], v[252:253] op_sel:[0,1,0]
	v_pk_fma_f32 v[254:255], v[246:247], v[124:125], v[254:255] op_sel:[0,1,0]
	v_pk_fma_f32 v[252:253], v[240:241], v[126:127], v[252:253] op_sel_hi:[1,0,1]
	v_pk_fma_f32 v[254:255], v[248:249], v[126:127], v[254:255] op_sel_hi:[1,0,1]
	v_pk_fma_f32 v[252:253], v[242:243], v[126:127], v[252:253] op_sel:[0,1,0]
	v_pk_fma_f32 v[254:255], v[250:251], v[126:127], v[254:255] op_sel:[0,1,0]
	s_waitcnt vmcnt(30)
	v_pk_mul_f32 v[140:141], v[236:237], v[120:121] op_sel_hi:[1,0]
	v_pk_mul_f32 v[142:143], v[244:245], v[120:121] op_sel_hi:[1,0]
	v_pk_fma_f32 v[140:141], v[238:239], v[120:121], v[140:141] op_sel:[0,1,0]
	v_pk_fma_f32 v[142:143], v[246:247], v[120:121], v[142:143] op_sel:[0,1,0]
	v_pk_fma_f32 v[140:141], v[240:241], v[122:123], v[140:141] op_sel_hi:[1,0,1]
	v_pk_fma_f32 v[142:143], v[248:249], v[122:123], v[142:143] op_sel_hi:[1,0,1]
	v_pk_fma_f32 v[140:141], v[242:243], v[122:123], v[140:141] op_sel:[0,1,0]
	v_pk_fma_f32 v[142:143], v[250:251], v[122:123], v[142:143] op_sel:[0,1,0]
	v_add_f32_dpp v124, v252, v252 quad_perm:[1,0,3,2] row_mask:0xf bank_mask:0xf
	v_add_f32_dpp v125, v253, v253 quad_perm:[1,0,3,2] row_mask:0xf bank_mask:0xf
	v_add_f32_dpp v126, v254, v254 quad_perm:[1,0,3,2] row_mask:0xf bank_mask:0xf
	v_add_f32_dpp v127, v255, v255 quad_perm:[1,0,3,2] row_mask:0xf bank_mask:0xf
	v_cndmask_b32_e32 v124, v126, v124, vcc
	v_cndmask_b32_e32 v125, v127, v125, vcc
	s_waitcnt vmcnt(29)
	v_pk_mul_f32 v[252:253], v[236:237], v[116:117] op_sel_hi:[1,0]
	v_pk_mul_f32 v[254:255], v[244:245], v[116:117] op_sel_hi:[1,0]
	v_pk_fma_f32 v[252:253], v[238:239], v[116:117], v[252:253] op_sel:[0,1,0]
	v_pk_fma_f32 v[254:255], v[246:247], v[116:117], v[254:255] op_sel:[0,1,0]
	v_pk_fma_f32 v[252:253], v[240:241], v[118:119], v[252:253] op_sel_hi:[1,0,1]
	v_pk_fma_f32 v[254:255], v[248:249], v[118:119], v[254:255] op_sel_hi:[1,0,1]
	v_pk_fma_f32 v[252:253], v[242:243], v[118:119], v[252:253] op_sel:[0,1,0]
	v_pk_fma_f32 v[254:255], v[250:251], v[118:119], v[254:255] op_sel:[0,1,0]
	v_add_f32_dpp v120, v140, v140 quad_perm:[1,0,3,2] row_mask:0xf bank_mask:0xf
	v_add_f32_dpp v121, v141, v141 quad_perm:[1,0,3,2] row_mask:0xf bank_mask:0xf
	v_add_f32_dpp v122, v142, v142 quad_perm:[1,0,3,2] row_mask:0xf bank_mask:0xf
	v_add_f32_dpp v123, v143, v143 quad_perm:[1,0,3,2] row_mask:0xf bank_mask:0xf
	v_cndmask_b32_e32 v120, v122, v120, vcc
	v_cndmask_b32_e32 v121, v123, v121, vcc
	v_add_f32_dpp v126, v124, v124 quad_perm:[2,3,0,1] row_mask:0xf bank_mask:0xf
	v_add_f32_dpp v127, v125, v125 quad_perm:[2,3,0,1] row_mask:0xf bank_mask:0xf
	v_cndmask_b32_e64 v124, v127, v126, s[4:5]
	s_waitcnt vmcnt(28)
	v_pk_mul_f32 v[140:141], v[236:237], v[112:113] op_sel_hi:[1,0]
	v_pk_mul_f32 v[142:143], v[244:245], v[112:113] op_sel_hi:[1,0]
	v_pk_fma_f32 v[140:141], v[238:239], v[112:113], v[140:141] op_sel:[0,1,0]
	v_pk_fma_f32 v[142:143], v[246:247], v[112:113], v[142:143] op_sel:[0,1,0]
	v_pk_fma_f32 v[140:141], v[240:241], v[114:115], v[140:141] op_sel_hi:[1,0,1]
	v_pk_fma_f32 v[142:143], v[248:249], v[114:115], v[142:143] op_sel_hi:[1,0,1]
	v_pk_fma_f32 v[140:141], v[242:243], v[114:115], v[140:141] op_sel:[0,1,0]
	v_pk_fma_f32 v[142:143], v[250:251], v[114:115], v[142:143] op_sel:[0,1,0]
	v_add_f32_dpp v116, v252, v252 quad_perm:[1,0,3,2] row_mask:0xf bank_mask:0xf
	v_add_f32_dpp v117, v253, v253 quad_perm:[1,0,3,2] row_mask:0xf bank_mask:0xf
	v_add_f32_dpp v118, v254, v254 quad_perm:[1,0,3,2] row_mask:0xf bank_mask:0xf
	v_add_f32_dpp v119, v255, v255 quad_perm:[1,0,3,2] row_mask:0xf bank_mask:0xf
	v_cndmask_b32_e32 v116, v118, v116, vcc
	v_cndmask_b32_e32 v117, v119, v117, vcc
	v_add_f32_dpp v122, v120, v120 quad_perm:[2,3,0,1] row_mask:0xf bank_mask:0xf
	v_add_f32_dpp v123, v121, v121 quad_perm:[2,3,0,1] row_mask:0xf bank_mask:0xf
	v_cndmask_b32_e64 v120, v123, v122, s[4:5]
	s_waitcnt vmcnt(27)
; DI void attn_sample_item(const Params& p, int item, ldsp lds, int tid_) {
;     ...
;   SC_SCORE(kvA, 0)
;   SC_SCORE(kvB, 1)
	v_pk_mul_f32 v[252:253], v[236:237], v[108:109] op_sel_hi:[1,0]
	v_pk_mul_f32 v[254:255], v[244:245], v[108:109] op_sel_hi:[1,0]
	v_pk_fma_f32 v[252:253], v[238:239], v[108:109], v[252:253] op_sel:[0,1,0]
	v_pk_fma_f32 v[254:255], v[246:247], v[108:109], v[254:255] op_sel:[0,1,0]
	v_pk_fma_f32 v[252:253], v[240:241], v[110:111], v[252:253] op_sel_hi:[1,0,1]
	v_pk_fma_f32 v[254:255], v[248:249], v[110:111], v[254:255] op_sel_hi:[1,0,1]
	v_pk_fma_f32 v[252:253], v[242:243], v[110:111], v[252:253] op_sel:[0,1,0]
	v_pk_fma_f32 v[254:255], v[250:251], v[110:111], v[254:255] op_sel:[0,1,0]
	v_add_f32_dpp v124, v124, v124 row_ror:4 row_mask:0xf bank_mask:0x5
	v_add_f32_dpp v124, v120, v120 row_ror:4 row_mask:0xf bank_mask:0xa
	v_add_f32_dpp v112, v140, v140 quad_perm:[1,0,3,2] row_mask:0xf bank_mask:0xf
	v_add_f32_dpp v113, v141, v141 quad_perm:[1,0,3,2] row_mask:0xf bank_mask:0xf
	v_add_f32_dpp v114, v142, v142 quad_perm:[1,0,3,2] row_mask:0xf bank_mask:0xf
	v_add_f32_dpp v115, v143, v143 quad_perm:[1,0,3,2] row_mask:0xf bank_mask:0xf
	v_cndmask_b32_e32 v112, v114, v112, vcc
	v_cndmask_b32_e32 v113, v115, v113, vcc
	v_add_f32_dpp v118, v116, v116 quad_perm:[2,3,0,1] row_mask:0xf bank_mask:0xf
	v_add_f32_dpp v119, v117, v117 quad_perm:[2,3,0,1] row_mask:0xf bank_mask:0xf
	v_cndmask_b32_e64 v116, v119, v118, s[4:5]
	s_waitcnt vmcnt(26)
	v_pk_mul_f32 v[140:141], v[236:237], v[104:105] op_sel_hi:[1,0]
	v_pk_mul_f32 v[142:143], v[244:245], v[104:105] op_sel_hi:[1,0]
	v_pk_fma_f32 v[140:141], v[238:239], v[104:105], v[140:141] op_sel:[0,1,0]
	v_pk_fma_f32 v[142:143], v[246:247], v[104:105], v[142:143] op_sel:[0,1,0]
	v_pk_fma_f32 v[140:141], v[240:241], v[106:107], v[140:141] op_sel_hi:[1,0,1]
	v_pk_fma_f32 v[142:143], v[248:249], v[106:107], v[142:143] op_sel_hi:[1,0,1]
	v_pk_fma_f32 v[140:141], v[242:243], v[106:107], v[140:141] op_sel:[0,1,0]
	v_pk_fma_f32 v[142:143], v[250:251], v[106:107], v[142:143] op_sel:[0,1,0]
	v_add_f32_dpp v108, v252, v252 quad_perm:[1,0,3,2] row_mask:0xf bank_mask:0xf
	v_add_f32_dpp v109, v253, v253 quad_perm:[1,0,3,2] row_mask:0xf bank_mask:0xf
	v_add_f32_dpp v110, v254, v254 quad_perm:[1,0,3,2] row_mask:0xf bank_mask:0xf
	v_add_f32_dpp v111, v255, v255 quad_perm:[1,0,3,2] row_mask:0xf bank_mask:0xf
	v_cndmask_b32_e32 v108, v110, v108, vcc
	v_cndmask_b32_e32 v109, v111, v109, vcc
	v_add_f32_dpp v114, v112, v112 quad_perm:[2,3,0,1] row_mask:0xf bank_mask:0xf
	v_add_f32_dpp v115, v113, v113 quad_perm:[2,3,0,1] row_mask:0xf bank_mask:0xf
	v_cndmask_b32_e64 v112, v115, v114, s[4:5]
	s_waitcnt vmcnt(25)
	v_pk_mul_f32 v[252:253], v[236:237], v[100:101] op_sel_hi:[1,0]
	v_pk_mul_f32 v[254:255], v[244:245], v[100:101] op_sel_hi:[1,0]
	v_pk_fma_f32 v[252:253], v[238:239], v[100:101], v[252:253] op_sel:[0,1,0]
	v_pk_fma_f32 v[254:255], v[246:247], v[100:101], v[254:255] op_sel:[0,1,0]
	v_pk_fma_f32 v[252:253], v[240:241], v[102:103], v[252:253] op_sel_hi:[1,0,1]
	v_pk_fma_f32 v[254:255], v[248:249], v[102:103], v[254:255] op_sel_hi:[1,0,1]
	v_pk_fma_f32 v[252:253], v[242:243], v[102:103], v[252:253] op_sel:[0,1,0]
	v_pk_fma_f32 v[254:255], v[250:251], v[102:103], v[254:255] op_sel:[0,1,0]
	v_add_f32_dpp v116, v116, v116 row_ror:4 row_mask:0xf bank_mask:0x5
	v_add_f32_dpp v116, v112, v112 row_ror:4 row_mask:0xf bank_mask:0xa
	v_add_f32_dpp v104, v140, v140 quad_perm:[1,0,3,2] row_mask:0xf bank_mask:0xf
	v_add_f32_dpp v105, v141, v141 quad_perm:[1,0,3,2] row_mask:0xf bank_mask:0xf
	v_add_f32_dpp v106, v142, v142 quad_perm:[1,0,3,2] row_mask:0xf bank_mask:0xf
	v_add_f32_dpp v107, v143, v143 quad_perm:[1,0,3,2] row_mask:0xf bank_mask:0xf
	v_cndmask_b32_e32 v104, v106, v104, vcc
	v_cndmask_b32_e32 v105, v107, v105, vcc
	v_add_f32_dpp v110, v108, v108 quad_perm:[2,3,0,1] row_mask:0xf bank_mask:0xf
	v_add_f32_dpp v111, v109, v109 quad_perm:[2,3,0,1] row_mask:0xf bank_mask:0xf
	v_cndmask_b32_e64 v108, v111, v110, s[4:5]
	s_waitcnt vmcnt(24)
	v_pk_mul_f32 v[140:141], v[236:237], v[96:97] op_sel_hi:[1,0]
	v_pk_mul_f32 v[142:143], v[244:245], v[96:97] op_sel_hi:[1,0]
	v_pk_fma_f32 v[140:141], v[238:239], v[96:97], v[140:141] op_sel:[0,1,0]
	v_pk_fma_f32 v[142:143], v[246:247], v[96:97], v[142:143] op_sel:[0,1,0]
	v_pk_fma_f32 v[140:141], v[240:241], v[98:99], v[140:141] op_sel_hi:[1,0,1]
	v_pk_fma_f32 v[142:143], v[248:249], v[98:99], v[142:143] op_sel_hi:[1,0,1]
	v_pk_fma_f32 v[140:141], v[242:243], v[98:99], v[140:141] op_sel:[0,1,0]
	v_pk_fma_f32 v[142:143], v[250:251], v[98:99], v[142:143] op_sel:[0,1,0]
	v_add_f32_dpp v124, v124, v124 row_ror:8 row_mask:0xf bank_mask:0x3
	v_add_f32_dpp v124, v116, v116 row_ror:8 row_mask:0xf bank_mask:0xc
	v_add_f32_dpp v100, v252, v252 quad_perm:[1,0,3,2] row_mask:0xf bank_mask:0xf
	v_add_f32_dpp v101, v253, v253 quad_perm:[1,0,3,2] row_mask:0xf bank_mask:0xf
	v_add_f32_dpp v102, v254, v254 quad_perm:[1,0,3,2] row_mask:0xf bank_mask:0xf
	v_add_f32_dpp v103, v255, v255 quad_perm:[1,0,3,2] row_mask:0xf bank_mask:0xf
	v_cndmask_b32_e32 v100, v102, v100, vcc
	v_cndmask_b32_e32 v101, v103, v101, vcc
	v_add_f32_dpp v106, v104, v104 quad_perm:[2,3,0,1] row_mask:0xf bank_mask:0xf
	v_add_f32_dpp v107, v105, v105 quad_perm:[2,3,0,1] row_mask:0xf bank_mask:0xf
	v_cndmask_b32_e64 v104, v107, v106, s[4:5]
	s_waitcnt vmcnt(23)
; DI void attn_sample_item(const Params& p, int item, ldsp lds, int tid_) {
;     ...
;   SC_SCORE(kvA, 0)
;   SC_SCORE(kvB, 1)
	v_pk_mul_f32 v[252:253], v[236:237], v[92:93] op_sel_hi:[1,0]
	v_pk_mul_f32 v[254:255], v[244:245], v[92:93] op_sel_hi:[1,0]
	v_pk_fma_f32 v[252:253], v[238:239], v[92:93], v[252:253] op_sel:[0,1,0]
	v_pk_fma_f32 v[254:255], v[246:247], v[92:93], v[254:255] op_sel:[0,1,0]
	v_pk_fma_f32 v[252:253], v[240:241], v[94:95], v[252:253] op_sel_hi:[1,0,1]
	v_pk_fma_f32 v[254:255], v[248:249], v[94:95], v[254:255] op_sel_hi:[1,0,1]
	v_pk_fma_f32 v[252:253], v[242:243], v[94:95], v[252:253] op_sel:[0,1,0]
	v_pk_fma_f32 v[254:255], v[250:251], v[94:95], v[254:255] op_sel:[0,1,0]
	v_add_f32_dpp v108, v108, v108 row_ror:4 row_mask:0xf bank_mask:0x5
	v_add_f32_dpp v108, v104, v104 row_ror:4 row_mask:0xf bank_mask:0xa
	v_add_f32_dpp v96, v140, v140 quad_perm:[1,0,3,2] row_mask:0xf bank_mask:0xf
	v_add_f32_dpp v97, v141, v141 quad_perm:[1,0,3,2] row_mask:0xf bank_mask:0xf
	v_add_f32_dpp v98, v142, v142 quad_perm:[1,0,3,2] row_mask:0xf bank_mask:0xf
	v_add_f32_dpp v99, v143, v143 quad_perm:[1,0,3,2] row_mask:0xf bank_mask:0xf
	v_cndmask_b32_e32 v96, v98, v96, vcc
	v_cndmask_b32_e32 v97, v99, v97, vcc
	v_add_f32_dpp v102, v100, v100 quad_perm:[2,3,0,1] row_mask:0xf bank_mask:0xf
	v_add_f32_dpp v103, v101, v101 quad_perm:[2,3,0,1] row_mask:0xf bank_mask:0xf
	v_cndmask_b32_e64 v100, v103, v102, s[4:5]
	s_waitcnt vmcnt(22)
	v_pk_mul_f32 v[140:141], v[236:237], v[88:89] op_sel_hi:[1,0]
	v_pk_mul_f32 v[142:143], v[244:245], v[88:89] op_sel_hi:[1,0]
	v_pk_fma_f32 v[140:141], v[238:239], v[88:89], v[140:141] op_sel:[0,1,0]
	v_pk_fma_f32 v[142:143], v[246:247], v[88:89], v[142:143] op_sel:[0,1,0]
	v_pk_fma_f32 v[140:141], v[240:241], v[90:91], v[140:141] op_sel_hi:[1,0,1]
	v_pk_fma_f32 v[142:143], v[248:249], v[90:91], v[142:143] op_sel_hi:[1,0,1]
	v_pk_fma_f32 v[140:141], v[242:243], v[90:91], v[140:141] op_sel:[0,1,0]
	v_pk_fma_f32 v[142:143], v[250:251], v[90:91], v[142:143] op_sel:[0,1,0]
	v_add_f32_dpp v92, v252, v252 quad_perm:[1,0,3,2] row_mask:0xf bank_mask:0xf
	v_add_f32_dpp v93, v253, v253 quad_perm:[1,0,3,2] row_mask:0xf bank_mask:0xf
	v_add_f32_dpp v94, v254, v254 quad_perm:[1,0,3,2] row_mask:0xf bank_mask:0xf
	v_add_f32_dpp v95, v255, v255 quad_perm:[1,0,3,2] row_mask:0xf bank_mask:0xf
	v_cndmask_b32_e32 v92, v94, v92, vcc
	v_cndmask_b32_e32 v93, v95, v93, vcc
	v_add_f32_dpp v98, v96, v96 quad_perm:[2,3,0,1] row_mask:0xf bank_mask:0xf
	v_add_f32_dpp v99, v97, v97 quad_perm:[2,3,0,1] row_mask:0xf bank_mask:0xf
	v_cndmask_b32_e64 v96, v99, v98, s[4:5]
	s_waitcnt vmcnt(21)
	v_pk_mul_f32 v[252:253], v[236:237], v[84:85] op_sel_hi:[1,0]
	v_pk_mul_f32 v[254:255], v[244:245], v[84:85] op_sel_hi:[1,0]
	v_pk_fma_f32 v[252:253], v[238:239], v[84:85], v[252:253] op_sel:[0,1,0]
	v_pk_fma_f32 v[254:255], v[246:247], v[84:85], v[254:255] op_sel:[0,1,0]
	v_pk_fma_f32 v[252:253], v[240:241], v[86:87], v[252:253] op_sel_hi:[1,0,1]
	v_pk_fma_f32 v[254:255], v[248:249], v[86:87], v[254:255] op_sel_hi:[1,0,1]
	v_pk_fma_f32 v[252:253], v[242:243], v[86:87], v[252:253] op_sel:[0,1,0]
	v_pk_fma_f32 v[254:255], v[250:251], v[86:87], v[254:255] op_sel:[0,1,0]
	v_add_f32_dpp v100, v100, v100 row_ror:4 row_mask:0xf bank_mask:0x5
	v_add_f32_dpp v100, v96, v96 row_ror:4 row_mask:0xf bank_mask:0xa
	v_add_f32_dpp v88, v140, v140 quad_perm:[1,0,3,2] row_mask:0xf bank_mask:0xf
	v_add_f32_dpp v89, v141, v141 quad_perm:[1,0,3,2] row_mask:0xf bank_mask:0xf
	v_add_f32_dpp v90, v142, v142 quad_perm:[1,0,3,2] row_mask:0xf bank_mask:0xf
	v_add_f32_dpp v91, v143, v143 quad_perm:[1,0,3,2] row_mask:0xf bank_mask:0xf
	v_cndmask_b32_e32 v88, v90, v88, vcc
	v_cndmask_b32_e32 v89, v91, v89, vcc
	v_add_f32_dpp v94, v92, v92 quad_perm:[2,3,0,1] row_mask:0xf bank_mask:0xf
	v_add_f32_dpp v95, v93, v93 quad_perm:[2,3,0,1] row_mask:0xf bank_mask:0xf
	v_cndmask_b32_e64 v92, v95, v94, s[4:5]
	s_waitcnt vmcnt(20)
	v_pk_mul_f32 v[140:141], v[236:237], v[80:81] op_sel_hi:[1,0]
	v_pk_mul_f32 v[142:143], v[244:245], v[80:81] op_sel_hi:[1,0]
	v_pk_fma_f32 v[140:141], v[238:239], v[80:81], v[140:141] op_sel:[0,1,0]
	v_pk_fma_f32 v[142:143], v[246:247], v[80:81], v[142:143] op_sel:[0,1,0]
	v_pk_fma_f32 v[140:141], v[240:241], v[82:83], v[140:141] op_sel_hi:[1,0,1]
	v_pk_fma_f32 v[142:143], v[248:249], v[82:83], v[142:143] op_sel_hi:[1,0,1]
	v_pk_fma_f32 v[140:141], v[242:243], v[82:83], v[140:141] op_sel:[0,1,0]
	v_pk_fma_f32 v[142:143], v[250:251], v[82:83], v[142:143] op_sel:[0,1,0]
	v_add_f32_dpp v108, v108, v108 row_ror:8 row_mask:0xf bank_mask:0x3
	v_add_f32_dpp v108, v100, v100 row_ror:8 row_mask:0xf bank_mask:0xc
	v_add_f32_dpp v84, v252, v252 quad_perm:[1,0,3,2] row_mask:0xf bank_mask:0xf
	v_add_f32_dpp v85, v253, v253 quad_perm:[1,0,3,2] row_mask:0xf bank_mask:0xf
	v_add_f32_dpp v86, v254, v254 quad_perm:[1,0,3,2] row_mask:0xf bank_mask:0xf
	v_add_f32_dpp v87, v255, v255 quad_perm:[1,0,3,2] row_mask:0xf bank_mask:0xf
	v_cndmask_b32_e32 v84, v86, v84, vcc
	v_cndmask_b32_e32 v85, v87, v85, vcc
	v_add_f32_dpp v90, v88, v88 quad_perm:[2,3,0,1] row_mask:0xf bank_mask:0xf
	v_add_f32_dpp v91, v89, v89 quad_perm:[2,3,0,1] row_mask:0xf bank_mask:0xf
	v_cndmask_b32_e64 v88, v91, v90, s[4:5]
	s_waitcnt vmcnt(19)
; DI void attn_sample_item(const Params& p, int item, ldsp lds, int tid_) {
;     ...
;   SC_SCORE(kvA, 0)
;   SC_SCORE(kvB, 1)
	v_pk_mul_f32 v[252:253], v[236:237], v[76:77] op_sel_hi:[1,0]
	v_pk_mul_f32 v[254:255], v[244:245], v[76:77] op_sel_hi:[1,0]
	v_pk_fma_f32 v[252:253], v[238:239], v[76:77], v[252:253] op_sel:[0,1,0]
	v_pk_fma_f32 v[254:255], v[246:247], v[76:77], v[254:255] op_sel:[0,1,0]
	v_pk_fma_f32 v[252:253], v[240:241], v[78:79], v[252:253] op_sel_hi:[1,0,1]
	v_pk_fma_f32 v[254:255], v[248:249], v[78:79], v[254:255] op_sel_hi:[1,0,1]
	v_pk_fma_f32 v[252:253], v[242:243], v[78:79], v[252:253] op_sel:[0,1,0]
	v_pk_fma_f32 v[254:255], v[250:251], v[78:79], v[254:255] op_sel:[0,1,0]
	v_permlane16_swap_b32_e32 v124, v108
	v_add_f32_e32 v124, v124, v108
	v_add_f32_dpp v92, v92, v92 row_ror:4 row_mask:0xf bank_mask:0x5
	v_add_f32_dpp v92, v88, v88 row_ror:4 row_mask:0xf bank_mask:0xa
	v_add_f32_dpp v80, v140, v140 quad_perm:[1,0,3,2] row_mask:0xf bank_mask:0xf
	v_add_f32_dpp v81, v141, v141 quad_perm:[1,0,3,2] row_mask:0xf bank_mask:0xf
	v_add_f32_dpp v82, v142, v142 quad_perm:[1,0,3,2] row_mask:0xf bank_mask:0xf
	v_add_f32_dpp v83, v143, v143 quad_perm:[1,0,3,2] row_mask:0xf bank_mask:0xf
	v_cndmask_b32_e32 v80, v82, v80, vcc
	v_cndmask_b32_e32 v81, v83, v81, vcc
	v_add_f32_dpp v86, v84, v84 quad_perm:[2,3,0,1] row_mask:0xf bank_mask:0xf
	v_add_f32_dpp v87, v85, v85 quad_perm:[2,3,0,1] row_mask:0xf bank_mask:0xf
	v_cndmask_b32_e64 v84, v87, v86, s[4:5]
	s_waitcnt vmcnt(18)
	v_pk_mul_f32 v[140:141], v[236:237], v[72:73] op_sel_hi:[1,0]
	v_pk_mul_f32 v[142:143], v[244:245], v[72:73] op_sel_hi:[1,0]
	v_pk_fma_f32 v[140:141], v[238:239], v[72:73], v[140:141] op_sel:[0,1,0]
	v_pk_fma_f32 v[142:143], v[246:247], v[72:73], v[142:143] op_sel:[0,1,0]
	v_pk_fma_f32 v[140:141], v[240:241], v[74:75], v[140:141] op_sel_hi:[1,0,1]
	v_pk_fma_f32 v[142:143], v[248:249], v[74:75], v[142:143] op_sel_hi:[1,0,1]
	v_pk_fma_f32 v[140:141], v[242:243], v[74:75], v[140:141] op_sel:[0,1,0]
	v_pk_fma_f32 v[142:143], v[250:251], v[74:75], v[142:143] op_sel:[0,1,0]
	v_add_f32_dpp v76, v252, v252 quad_perm:[1,0,3,2] row_mask:0xf bank_mask:0xf
	v_add_f32_dpp v77, v253, v253 quad_perm:[1,0,3,2] row_mask:0xf bank_mask:0xf
	v_add_f32_dpp v78, v254, v254 quad_perm:[1,0,3,2] row_mask:0xf bank_mask:0xf
	v_add_f32_dpp v79, v255, v255 quad_perm:[1,0,3,2] row_mask:0xf bank_mask:0xf
	v_cndmask_b32_e32 v76, v78, v76, vcc
	v_cndmask_b32_e32 v77, v79, v77, vcc
	v_add_f32_dpp v82, v80, v80 quad_perm:[2,3,0,1] row_mask:0xf bank_mask:0xf
	v_add_f32_dpp v83, v81, v81 quad_perm:[2,3,0,1] row_mask:0xf bank_mask:0xf
	v_cndmask_b32_e64 v80, v83, v82, s[4:5]
	s_waitcnt vmcnt(17)
	v_pk_mul_f32 v[252:253], v[236:237], v[68:69] op_sel_hi:[1,0]
	v_pk_mul_f32 v[254:255], v[244:245], v[68:69] op_sel_hi:[1,0]
	v_pk_fma_f32 v[252:253], v[238:239], v[68:69], v[252:253] op_sel:[0,1,0]
	v_pk_fma_f32 v[254:255], v[246:247], v[68:69], v[254:255] op_sel:[0,1,0]
	v_pk_fma_f32 v[252:253], v[240:241], v[70:71], v[252:253] op_sel_hi:[1,0,1]
	v_pk_fma_f32 v[254:255], v[248:249], v[70:71], v[254:255] op_sel_hi:[1,0,1]
	v_pk_fma_f32 v[252:253], v[242:243], v[70:71], v[252:253] op_sel:[0,1,0]
	v_pk_fma_f32 v[254:255], v[250:251], v[70:71], v[254:255] op_sel:[0,1,0]
	v_add_f32_dpp v84, v84, v84 row_ror:4 row_mask:0xf bank_mask:0x5
	v_add_f32_dpp v84, v80, v80 row_ror:4 row_mask:0xf bank_mask:0xa
	v_add_f32_dpp v72, v140, v140 quad_perm:[1,0,3,2] row_mask:0xf bank_mask:0xf
	v_add_f32_dpp v73, v141, v141 quad_perm:[1,0,3,2] row_mask:0xf bank_mask:0xf
	v_add_f32_dpp v74, v142, v142 quad_perm:[1,0,3,2] row_mask:0xf bank_mask:0xf
	v_add_f32_dpp v75, v143, v143 quad_perm:[1,0,3,2] row_mask:0xf bank_mask:0xf
	v_cndmask_b32_e32 v72, v74, v72, vcc
	v_cndmask_b32_e32 v73, v75, v73, vcc
	v_add_f32_dpp v78, v76, v76 quad_perm:[2,3,0,1] row_mask:0xf bank_mask:0xf
	v_add_f32_dpp v79, v77, v77 quad_perm:[2,3,0,1] row_mask:0xf bank_mask:0xf
	v_cndmask_b32_e64 v76, v79, v78, s[4:5]
	s_waitcnt vmcnt(16)
	v_pk_mul_f32 v[140:141], v[236:237], v[64:65] op_sel_hi:[1,0]
	v_pk_mul_f32 v[142:143], v[244:245], v[64:65] op_sel_hi:[1,0]
	v_pk_fma_f32 v[140:141], v[238:239], v[64:65], v[140:141] op_sel:[0,1,0]
	v_pk_fma_f32 v[142:143], v[246:247], v[64:65], v[142:143] op_sel:[0,1,0]
	v_pk_fma_f32 v[140:141], v[240:241], v[66:67], v[140:141] op_sel_hi:[1,0,1]
	v_pk_fma_f32 v[142:143], v[248:249], v[66:67], v[142:143] op_sel_hi:[1,0,1]
	v_pk_fma_f32 v[140:141], v[242:243], v[66:67], v[140:141] op_sel:[0,1,0]
	v_pk_fma_f32 v[142:143], v[250:251], v[66:67], v[142:143] op_sel:[0,1,0]
	v_add_f32_dpp v92, v92, v92 row_ror:8 row_mask:0xf bank_mask:0x3
	v_add_f32_dpp v92, v84, v84 row_ror:8 row_mask:0xf bank_mask:0xc
	v_add_f32_dpp v68, v252, v252 quad_perm:[1,0,3,2] row_mask:0xf bank_mask:0xf
	v_add_f32_dpp v69, v253, v253 quad_perm:[1,0,3,2] row_mask:0xf bank_mask:0xf
	v_add_f32_dpp v70, v254, v254 quad_perm:[1,0,3,2] row_mask:0xf bank_mask:0xf
	v_add_f32_dpp v71, v255, v255 quad_perm:[1,0,3,2] row_mask:0xf bank_mask:0xf
	v_cndmask_b32_e32 v68, v70, v68, vcc
	v_cndmask_b32_e32 v69, v71, v69, vcc
	v_add_f32_dpp v74, v72, v72 quad_perm:[2,3,0,1] row_mask:0xf bank_mask:0xf
	v_add_f32_dpp v75, v73, v73 quad_perm:[2,3,0,1] row_mask:0xf bank_mask:0xf
	v_cndmask_b32_e64 v72, v75, v74, s[4:5]
	s_waitcnt vmcnt(15)
; DI void attn_sample_item(const Params& p, int item, ldsp lds, int tid_) {
;     ...
;   SC_SCORE(kvA, 0)
;   SC_SCORE(kvB, 1)
	v_pk_mul_f32 v[252:253], v[236:237], v[60:61] op_sel_hi:[1,0]
	v_pk_mul_f32 v[254:255], v[244:245], v[60:61] op_sel_hi:[1,0]
	v_pk_fma_f32 v[252:253], v[238:239], v[60:61], v[252:253] op_sel:[0,1,0]
	v_pk_fma_f32 v[254:255], v[246:247], v[60:61], v[254:255] op_sel:[0,1,0]
	v_pk_fma_f32 v[252:253], v[240:241], v[62:63], v[252:253] op_sel_hi:[1,0,1]
	v_pk_fma_f32 v[254:255], v[248:249], v[62:63], v[254:255] op_sel_hi:[1,0,1]
	v_pk_fma_f32 v[252:253], v[242:243], v[62:63], v[252:253] op_sel:[0,1,0]
	v_pk_fma_f32 v[254:255], v[250:251], v[62:63], v[254:255] op_sel:[0,1,0]
	v_add_f32_dpp v76, v76, v76 row_ror:4 row_mask:0xf bank_mask:0x5
	v_add_f32_dpp v76, v72, v72 row_ror:4 row_mask:0xf bank_mask:0xa
	v_add_f32_dpp v64, v140, v140 quad_perm:[1,0,3,2] row_mask:0xf bank_mask:0xf
	v_add_f32_dpp v65, v141, v141 quad_perm:[1,0,3,2] row_mask:0xf bank_mask:0xf
	v_add_f32_dpp v66, v142, v142 quad_perm:[1,0,3,2] row_mask:0xf bank_mask:0xf
	v_add_f32_dpp v67, v143, v143 quad_perm:[1,0,3,2] row_mask:0xf bank_mask:0xf
	v_cndmask_b32_e32 v64, v66, v64, vcc
	v_cndmask_b32_e32 v65, v67, v65, vcc
	v_add_f32_dpp v70, v68, v68 quad_perm:[2,3,0,1] row_mask:0xf bank_mask:0xf
	v_add_f32_dpp v71, v69, v69 quad_perm:[2,3,0,1] row_mask:0xf bank_mask:0xf
	v_cndmask_b32_e64 v68, v71, v70, s[4:5]
	s_waitcnt vmcnt(14)
	v_pk_mul_f32 v[140:141], v[236:237], v[56:57] op_sel_hi:[1,0]
	v_pk_mul_f32 v[142:143], v[244:245], v[56:57] op_sel_hi:[1,0]
	v_pk_fma_f32 v[140:141], v[238:239], v[56:57], v[140:141] op_sel:[0,1,0]
	v_pk_fma_f32 v[142:143], v[246:247], v[56:57], v[142:143] op_sel:[0,1,0]
	v_pk_fma_f32 v[140:141], v[240:241], v[58:59], v[140:141] op_sel_hi:[1,0,1]
	v_pk_fma_f32 v[142:143], v[248:249], v[58:59], v[142:143] op_sel_hi:[1,0,1]
	v_pk_fma_f32 v[140:141], v[242:243], v[58:59], v[140:141] op_sel:[0,1,0]
	v_pk_fma_f32 v[142:143], v[250:251], v[58:59], v[142:143] op_sel:[0,1,0]
	v_add_f32_dpp v60, v252, v252 quad_perm:[1,0,3,2] row_mask:0xf bank_mask:0xf
	v_add_f32_dpp v61, v253, v253 quad_perm:[1,0,3,2] row_mask:0xf bank_mask:0xf
	v_add_f32_dpp v62, v254, v254 quad_perm:[1,0,3,2] row_mask:0xf bank_mask:0xf
	v_add_f32_dpp v63, v255, v255 quad_perm:[1,0,3,2] row_mask:0xf bank_mask:0xf
	v_cndmask_b32_e32 v60, v62, v60, vcc
	v_cndmask_b32_e32 v61, v63, v61, vcc
	v_add_f32_dpp v66, v64, v64 quad_perm:[2,3,0,1] row_mask:0xf bank_mask:0xf
	v_add_f32_dpp v67, v65, v65 quad_perm:[2,3,0,1] row_mask:0xf bank_mask:0xf
	v_cndmask_b32_e64 v64, v67, v66, s[4:5]
	s_waitcnt vmcnt(13)
	v_pk_mul_f32 v[252:253], v[236:237], v[52:53] op_sel_hi:[1,0]
	v_pk_mul_f32 v[254:255], v[244:245], v[52:53] op_sel_hi:[1,0]
	v_pk_fma_f32 v[252:253], v[238:239], v[52:53], v[252:253] op_sel:[0,1,0]
	v_pk_fma_f32 v[254:255], v[246:247], v[52:53], v[254:255] op_sel:[0,1,0]
	v_pk_fma_f32 v[252:253], v[240:241], v[54:55], v[252:253] op_sel_hi:[1,0,1]
	v_pk_fma_f32 v[254:255], v[248:249], v[54:55], v[254:255] op_sel_hi:[1,0,1]
	v_pk_fma_f32 v[252:253], v[242:243], v[54:55], v[252:253] op_sel:[0,1,0]
	v_pk_fma_f32 v[254:255], v[250:251], v[54:55], v[254:255] op_sel:[0,1,0]
	v_add_f32_dpp v68, v68, v68 row_ror:4 row_mask:0xf bank_mask:0x5
	v_add_f32_dpp v68, v64, v64 row_ror:4 row_mask:0xf bank_mask:0xa
	v_add_f32_dpp v56, v140, v140 quad_perm:[1,0,3,2] row_mask:0xf bank_mask:0xf
	v_add_f32_dpp v57, v141, v141 quad_perm:[1,0,3,2] row_mask:0xf bank_mask:0xf
	v_add_f32_dpp v58, v142, v142 quad_perm:[1,0,3,2] row_mask:0xf bank_mask:0xf
	v_add_f32_dpp v59, v143, v143 quad_perm:[1,0,3,2] row_mask:0xf bank_mask:0xf
	v_cndmask_b32_e32 v56, v58, v56, vcc
	v_cndmask_b32_e32 v57, v59, v57, vcc
	v_add_f32_dpp v62, v60, v60 quad_perm:[2,3,0,1] row_mask:0xf bank_mask:0xf
	v_add_f32_dpp v63, v61, v61 quad_perm:[2,3,0,1] row_mask:0xf bank_mask:0xf
	v_cndmask_b32_e64 v60, v63, v62, s[4:5]
	s_waitcnt vmcnt(12)
	v_pk_mul_f32 v[140:141], v[236:237], v[48:49] op_sel_hi:[1,0]
	v_pk_mul_f32 v[142:143], v[244:245], v[48:49] op_sel_hi:[1,0]
	v_pk_fma_f32 v[140:141], v[238:239], v[48:49], v[140:141] op_sel:[0,1,0]
	v_pk_fma_f32 v[142:143], v[246:247], v[48:49], v[142:143] op_sel:[0,1,0]
	v_pk_fma_f32 v[140:141], v[240:241], v[50:51], v[140:141] op_sel_hi:[1,0,1]
	v_pk_fma_f32 v[142:143], v[248:249], v[50:51], v[142:143] op_sel_hi:[1,0,1]
	v_pk_fma_f32 v[140:141], v[242:243], v[50:51], v[140:141] op_sel:[0,1,0]
	v_pk_fma_f32 v[142:143], v[250:251], v[50:51], v[142:143] op_sel:[0,1,0]
	v_add_f32_dpp v76, v76, v76 row_ror:8 row_mask:0xf bank_mask:0x3
	v_add_f32_dpp v76, v68, v68 row_ror:8 row_mask:0xf bank_mask:0xc
	v_add_f32_dpp v52, v252, v252 quad_perm:[1,0,3,2] row_mask:0xf bank_mask:0xf
	v_add_f32_dpp v53, v253, v253 quad_perm:[1,0,3,2] row_mask:0xf bank_mask:0xf
	v_add_f32_dpp v54, v254, v254 quad_perm:[1,0,3,2] row_mask:0xf bank_mask:0xf
	v_add_f32_dpp v55, v255, v255 quad_perm:[1,0,3,2] row_mask:0xf bank_mask:0xf
	v_cndmask_b32_e32 v52, v54, v52, vcc
	v_cndmask_b32_e32 v53, v55, v53, vcc
	v_add_f32_dpp v58, v56, v56 quad_perm:[2,3,0,1] row_mask:0xf bank_mask:0xf
	v_add_f32_dpp v59, v57, v57 quad_perm:[2,3,0,1] row_mask:0xf bank_mask:0xf
	v_cndmask_b32_e64 v56, v59, v58, s[4:5]
	s_waitcnt vmcnt(11)
; DI void attn_sample_item(const Params& p, int item, ldsp lds, int tid_) {
;     ...
;   SC_SCORE(kvA, 0)
;   SC_SCORE(kvB, 1)
	v_pk_mul_f32 v[252:253], v[236:237], v[44:45] op_sel_hi:[1,0]
	v_pk_mul_f32 v[254:255], v[244:245], v[44:45] op_sel_hi:[1,0]
	v_pk_fma_f32 v[252:253], v[238:239], v[44:45], v[252:253] op_sel:[0,1,0]
	v_pk_fma_f32 v[254:255], v[246:247], v[44:45], v[254:255] op_sel:[0,1,0]
	v_pk_fma_f32 v[252:253], v[240:241], v[46:47], v[252:253] op_sel_hi:[1,0,1]
	v_pk_fma_f32 v[254:255], v[248:249], v[46:47], v[254:255] op_sel_hi:[1,0,1]
	v_pk_fma_f32 v[252:253], v[242:243], v[46:47], v[252:253] op_sel:[0,1,0]
	v_pk_fma_f32 v[254:255], v[250:251], v[46:47], v[254:255] op_sel:[0,1,0]
	v_permlane16_swap_b32_e32 v92, v76
	v_add_f32_e32 v92, v92, v76
	v_add_f32_dpp v60, v60, v60 row_ror:4 row_mask:0xf bank_mask:0x5
	v_add_f32_dpp v60, v56, v56 row_ror:4 row_mask:0xf bank_mask:0xa
	v_add_f32_dpp v48, v140, v140 quad_perm:[1,0,3,2] row_mask:0xf bank_mask:0xf
	v_add_f32_dpp v49, v141, v141 quad_perm:[1,0,3,2] row_mask:0xf bank_mask:0xf
	v_add_f32_dpp v50, v142, v142 quad_perm:[1,0,3,2] row_mask:0xf bank_mask:0xf
	v_add_f32_dpp v51, v143, v143 quad_perm:[1,0,3,2] row_mask:0xf bank_mask:0xf
	v_cndmask_b32_e32 v48, v50, v48, vcc
	v_cndmask_b32_e32 v49, v51, v49, vcc
	v_add_f32_dpp v54, v52, v52 quad_perm:[2,3,0,1] row_mask:0xf bank_mask:0xf
	v_add_f32_dpp v55, v53, v53 quad_perm:[2,3,0,1] row_mask:0xf bank_mask:0xf
	v_cndmask_b32_e64 v52, v55, v54, s[4:5]
	s_waitcnt vmcnt(10)
	v_pk_mul_f32 v[140:141], v[236:237], v[40:41] op_sel_hi:[1,0]
	v_pk_mul_f32 v[142:143], v[244:245], v[40:41] op_sel_hi:[1,0]
	v_pk_fma_f32 v[140:141], v[238:239], v[40:41], v[140:141] op_sel:[0,1,0]
	v_pk_fma_f32 v[142:143], v[246:247], v[40:41], v[142:143] op_sel:[0,1,0]
	v_pk_fma_f32 v[140:141], v[240:241], v[42:43], v[140:141] op_sel_hi:[1,0,1]
	v_pk_fma_f32 v[142:143], v[248:249], v[42:43], v[142:143] op_sel_hi:[1,0,1]
	v_pk_fma_f32 v[140:141], v[242:243], v[42:43], v[140:141] op_sel:[0,1,0]
	v_pk_fma_f32 v[142:143], v[250:251], v[42:43], v[142:143] op_sel:[0,1,0]
	v_permlane32_swap_b32_e32 v124, v92
	v_add_f32_e32 v124, v124, v92
	ds_write_b32 v235, v124
	v_add_f32_dpp v44, v252, v252 quad_perm:[1,0,3,2] row_mask:0xf bank_mask:0xf
	v_add_f32_dpp v45, v253, v253 quad_perm:[1,0,3,2] row_mask:0xf bank_mask:0xf
	v_add_f32_dpp v46, v254, v254 quad_perm:[1,0,3,2] row_mask:0xf bank_mask:0xf
	v_add_f32_dpp v47, v255, v255 quad_perm:[1,0,3,2] row_mask:0xf bank_mask:0xf
	v_cndmask_b32_e32 v44, v46, v44, vcc
	v_cndmask_b32_e32 v45, v47, v45, vcc
	v_add_f32_dpp v50, v48, v48 quad_perm:[2,3,0,1] row_mask:0xf bank_mask:0xf
	v_add_f32_dpp v51, v49, v49 quad_perm:[2,3,0,1] row_mask:0xf bank_mask:0xf
	v_cndmask_b32_e64 v48, v51, v50, s[4:5]
	s_waitcnt vmcnt(9)
	v_pk_mul_f32 v[252:253], v[236:237], v[36:37] op_sel_hi:[1,0]
	v_pk_mul_f32 v[254:255], v[244:245], v[36:37] op_sel_hi:[1,0]
	v_pk_fma_f32 v[252:253], v[238:239], v[36:37], v[252:253] op_sel:[0,1,0]
	v_pk_fma_f32 v[254:255], v[246:247], v[36:37], v[254:255] op_sel:[0,1,0]
	v_pk_fma_f32 v[252:253], v[240:241], v[38:39], v[252:253] op_sel_hi:[1,0,1]
	v_pk_fma_f32 v[254:255], v[248:249], v[38:39], v[254:255] op_sel_hi:[1,0,1]
	v_pk_fma_f32 v[252:253], v[242:243], v[38:39], v[252:253] op_sel:[0,1,0]
	v_pk_fma_f32 v[254:255], v[250:251], v[38:39], v[254:255] op_sel:[0,1,0]
	v_add_f32_dpp v52, v52, v52 row_ror:4 row_mask:0xf bank_mask:0x5
	v_add_f32_dpp v52, v48, v48 row_ror:4 row_mask:0xf bank_mask:0xa
	v_add_f32_dpp v40, v140, v140 quad_perm:[1,0,3,2] row_mask:0xf bank_mask:0xf
	v_add_f32_dpp v41, v141, v141 quad_perm:[1,0,3,2] row_mask:0xf bank_mask:0xf
	v_add_f32_dpp v42, v142, v142 quad_perm:[1,0,3,2] row_mask:0xf bank_mask:0xf
	v_add_f32_dpp v43, v143, v143 quad_perm:[1,0,3,2] row_mask:0xf bank_mask:0xf
	v_cndmask_b32_e32 v40, v42, v40, vcc
	v_cndmask_b32_e32 v41, v43, v41, vcc
	v_add_f32_dpp v46, v44, v44 quad_perm:[2,3,0,1] row_mask:0xf bank_mask:0xf
	v_add_f32_dpp v47, v45, v45 quad_perm:[2,3,0,1] row_mask:0xf bank_mask:0xf
	v_cndmask_b32_e64 v44, v47, v46, s[4:5]
	s_waitcnt vmcnt(8)
	v_pk_mul_f32 v[140:141], v[236:237], v[32:33] op_sel_hi:[1,0]
	v_pk_mul_f32 v[142:143], v[244:245], v[32:33] op_sel_hi:[1,0]
	v_pk_fma_f32 v[140:141], v[238:239], v[32:33], v[140:141] op_sel:[0,1,0]
	v_pk_fma_f32 v[142:143], v[246:247], v[32:33], v[142:143] op_sel:[0,1,0]
	v_pk_fma_f32 v[140:141], v[240:241], v[34:35], v[140:141] op_sel_hi:[1,0,1]
	v_pk_fma_f32 v[142:143], v[248:249], v[34:35], v[142:143] op_sel_hi:[1,0,1]
	v_pk_fma_f32 v[140:141], v[242:243], v[34:35], v[140:141] op_sel:[0,1,0]
	v_pk_fma_f32 v[142:143], v[250:251], v[34:35], v[142:143] op_sel:[0,1,0]
	v_add_f32_dpp v60, v60, v60 row_ror:8 row_mask:0xf bank_mask:0x3
	v_add_f32_dpp v60, v52, v52 row_ror:8 row_mask:0xf bank_mask:0xc
	v_add_f32_dpp v36, v252, v252 quad_perm:[1,0,3,2] row_mask:0xf bank_mask:0xf
	v_add_f32_dpp v37, v253, v253 quad_perm:[1,0,3,2] row_mask:0xf bank_mask:0xf
	v_add_f32_dpp v38, v254, v254 quad_perm:[1,0,3,2] row_mask:0xf bank_mask:0xf
	v_add_f32_dpp v39, v255, v255 quad_perm:[1,0,3,2] row_mask:0xf bank_mask:0xf
	v_cndmask_b32_e32 v36, v38, v36, vcc
	v_cndmask_b32_e32 v37, v39, v37, vcc
	v_add_f32_dpp v42, v40, v40 quad_perm:[2,3,0,1] row_mask:0xf bank_mask:0xf
	v_add_f32_dpp v43, v41, v41 quad_perm:[2,3,0,1] row_mask:0xf bank_mask:0xf
	v_cndmask_b32_e64 v40, v43, v42, s[4:5]
	s_waitcnt vmcnt(7)
; DI void attn_sample_item(const Params& p, int item, ldsp lds, int tid_) {
;     ...
;   SC_SCORE(kvA, 0)
;   SC_SCORE(kvB, 1)
	v_pk_mul_f32 v[252:253], v[236:237], v[28:29] op_sel_hi:[1,0]
	v_pk_mul_f32 v[254:255], v[244:245], v[28:29] op_sel_hi:[1,0]
	v_pk_fma_f32 v[252:253], v[238:239], v[28:29], v[252:253] op_sel:[0,1,0]
	v_pk_fma_f32 v[254:255], v[246:247], v[28:29], v[254:255] op_sel:[0,1,0]
	v_pk_fma_f32 v[252:253], v[240:241], v[30:31], v[252:253] op_sel_hi:[1,0,1]
	v_pk_fma_f32 v[254:255], v[248:249], v[30:31], v[254:255] op_sel_hi:[1,0,1]
	v_pk_fma_f32 v[252:253], v[242:243], v[30:31], v[252:253] op_sel:[0,1,0]
	v_pk_fma_f32 v[254:255], v[250:251], v[30:31], v[254:255] op_sel:[0,1,0]
	v_add_f32_dpp v44, v44, v44 row_ror:4 row_mask:0xf bank_mask:0x5
	v_add_f32_dpp v44, v40, v40 row_ror:4 row_mask:0xf bank_mask:0xa
	v_add_f32_dpp v32, v140, v140 quad_perm:[1,0,3,2] row_mask:0xf bank_mask:0xf
	v_add_f32_dpp v33, v141, v141 quad_perm:[1,0,3,2] row_mask:0xf bank_mask:0xf
	v_add_f32_dpp v34, v142, v142 quad_perm:[1,0,3,2] row_mask:0xf bank_mask:0xf
	v_add_f32_dpp v35, v143, v143 quad_perm:[1,0,3,2] row_mask:0xf bank_mask:0xf
	v_cndmask_b32_e32 v32, v34, v32, vcc
	v_cndmask_b32_e32 v33, v35, v33, vcc
	v_add_f32_dpp v38, v36, v36 quad_perm:[2,3,0,1] row_mask:0xf bank_mask:0xf
	v_add_f32_dpp v39, v37, v37 quad_perm:[2,3,0,1] row_mask:0xf bank_mask:0xf
	v_cndmask_b32_e64 v36, v39, v38, s[4:5]
	s_waitcnt vmcnt(6)
	v_pk_mul_f32 v[140:141], v[236:237], v[24:25] op_sel_hi:[1,0]
	v_pk_mul_f32 v[142:143], v[244:245], v[24:25] op_sel_hi:[1,0]
	v_pk_fma_f32 v[140:141], v[238:239], v[24:25], v[140:141] op_sel:[0,1,0]
	v_pk_fma_f32 v[142:143], v[246:247], v[24:25], v[142:143] op_sel:[0,1,0]
	v_pk_fma_f32 v[140:141], v[240:241], v[26:27], v[140:141] op_sel_hi:[1,0,1]
	v_pk_fma_f32 v[142:143], v[248:249], v[26:27], v[142:143] op_sel_hi:[1,0,1]
	v_pk_fma_f32 v[140:141], v[242:243], v[26:27], v[140:141] op_sel:[0,1,0]
	v_pk_fma_f32 v[142:143], v[250:251], v[26:27], v[142:143] op_sel:[0,1,0]
	v_add_f32_dpp v28, v252, v252 quad_perm:[1,0,3,2] row_mask:0xf bank_mask:0xf
	v_add_f32_dpp v29, v253, v253 quad_perm:[1,0,3,2] row_mask:0xf bank_mask:0xf
	v_add_f32_dpp v30, v254, v254 quad_perm:[1,0,3,2] row_mask:0xf bank_mask:0xf
	v_add_f32_dpp v31, v255, v255 quad_perm:[1,0,3,2] row_mask:0xf bank_mask:0xf
	v_cndmask_b32_e32 v28, v30, v28, vcc
	v_cndmask_b32_e32 v29, v31, v29, vcc
	v_add_f32_dpp v34, v32, v32 quad_perm:[2,3,0,1] row_mask:0xf bank_mask:0xf
	v_add_f32_dpp v35, v33, v33 quad_perm:[2,3,0,1] row_mask:0xf bank_mask:0xf
	v_cndmask_b32_e64 v32, v35, v34, s[4:5]
	s_waitcnt vmcnt(5)
	v_pk_mul_f32 v[252:253], v[236:237], v[20:21] op_sel_hi:[1,0]
	v_pk_mul_f32 v[254:255], v[244:245], v[20:21] op_sel_hi:[1,0]
	v_pk_fma_f32 v[252:253], v[238:239], v[20:21], v[252:253] op_sel:[0,1,0]
	v_pk_fma_f32 v[254:255], v[246:247], v[20:21], v[254:255] op_sel:[0,1,0]
	v_pk_fma_f32 v[252:253], v[240:241], v[22:23], v[252:253] op_sel_hi:[1,0,1]
	v_pk_fma_f32 v[254:255], v[248:249], v[22:23], v[254:255] op_sel_hi:[1,0,1]
	v_pk_fma_f32 v[252:253], v[242:243], v[22:23], v[252:253] op_sel:[0,1,0]
	v_pk_fma_f32 v[254:255], v[250:251], v[22:23], v[254:255] op_sel:[0,1,0]
	v_add_f32_dpp v36, v36, v36 row_ror:4 row_mask:0xf bank_mask:0x5
	v_add_f32_dpp v36, v32, v32 row_ror:4 row_mask:0xf bank_mask:0xa
	v_add_f32_dpp v24, v140, v140 quad_perm:[1,0,3,2] row_mask:0xf bank_mask:0xf
	v_add_f32_dpp v25, v141, v141 quad_perm:[1,0,3,2] row_mask:0xf bank_mask:0xf
	v_add_f32_dpp v26, v142, v142 quad_perm:[1,0,3,2] row_mask:0xf bank_mask:0xf
	v_add_f32_dpp v27, v143, v143 quad_perm:[1,0,3,2] row_mask:0xf bank_mask:0xf
	v_cndmask_b32_e32 v24, v26, v24, vcc
	v_cndmask_b32_e32 v25, v27, v25, vcc
	v_add_f32_dpp v30, v28, v28 quad_perm:[2,3,0,1] row_mask:0xf bank_mask:0xf
	v_add_f32_dpp v31, v29, v29 quad_perm:[2,3,0,1] row_mask:0xf bank_mask:0xf
	v_cndmask_b32_e64 v28, v31, v30, s[4:5]
	s_waitcnt vmcnt(4)
	v_pk_mul_f32 v[140:141], v[236:237], v[16:17] op_sel_hi:[1,0]
	v_pk_mul_f32 v[142:143], v[244:245], v[16:17] op_sel_hi:[1,0]
	v_pk_fma_f32 v[140:141], v[238:239], v[16:17], v[140:141] op_sel:[0,1,0]
	v_pk_fma_f32 v[142:143], v[246:247], v[16:17], v[142:143] op_sel:[0,1,0]
	v_pk_fma_f32 v[140:141], v[240:241], v[18:19], v[140:141] op_sel_hi:[1,0,1]
	v_pk_fma_f32 v[142:143], v[248:249], v[18:19], v[142:143] op_sel_hi:[1,0,1]
	v_pk_fma_f32 v[140:141], v[242:243], v[18:19], v[140:141] op_sel:[0,1,0]
	v_pk_fma_f32 v[142:143], v[250:251], v[18:19], v[142:143] op_sel:[0,1,0]
	v_add_f32_dpp v44, v44, v44 row_ror:8 row_mask:0xf bank_mask:0x3
	v_add_f32_dpp v44, v36, v36 row_ror:8 row_mask:0xf bank_mask:0xc
	v_add_f32_dpp v20, v252, v252 quad_perm:[1,0,3,2] row_mask:0xf bank_mask:0xf
	v_add_f32_dpp v21, v253, v253 quad_perm:[1,0,3,2] row_mask:0xf bank_mask:0xf
	v_add_f32_dpp v22, v254, v254 quad_perm:[1,0,3,2] row_mask:0xf bank_mask:0xf
	v_add_f32_dpp v23, v255, v255 quad_perm:[1,0,3,2] row_mask:0xf bank_mask:0xf
	v_cndmask_b32_e32 v20, v22, v20, vcc
	v_cndmask_b32_e32 v21, v23, v21, vcc
	v_add_f32_dpp v26, v24, v24 quad_perm:[2,3,0,1] row_mask:0xf bank_mask:0xf
	v_add_f32_dpp v27, v25, v25 quad_perm:[2,3,0,1] row_mask:0xf bank_mask:0xf
	v_cndmask_b32_e64 v24, v27, v26, s[4:5]
	s_waitcnt vmcnt(3)
; DI void attn_sample_item(const Params& p, int item, ldsp lds, int tid_) {
;     ...
;   SC_SCORE(kvA, 0)
;   SC_SCORE(kvB, 1)
	v_pk_mul_f32 v[252:253], v[236:237], v[12:13] op_sel_hi:[1,0]
	v_pk_mul_f32 v[254:255], v[244:245], v[12:13] op_sel_hi:[1,0]
	v_pk_fma_f32 v[252:253], v[238:239], v[12:13], v[252:253] op_sel:[0,1,0]
	v_pk_fma_f32 v[254:255], v[246:247], v[12:13], v[254:255] op_sel:[0,1,0]
	v_pk_fma_f32 v[252:253], v[240:241], v[14:15], v[252:253] op_sel_hi:[1,0,1]
	v_pk_fma_f32 v[254:255], v[248:249], v[14:15], v[254:255] op_sel_hi:[1,0,1]
	v_pk_fma_f32 v[252:253], v[242:243], v[14:15], v[252:253] op_sel:[0,1,0]
	v_pk_fma_f32 v[254:255], v[250:251], v[14:15], v[254:255] op_sel:[0,1,0]
	v_permlane16_swap_b32_e32 v60, v44
	v_add_f32_e32 v60, v60, v44
	v_add_f32_dpp v28, v28, v28 row_ror:4 row_mask:0xf bank_mask:0x5
	v_add_f32_dpp v28, v24, v24 row_ror:4 row_mask:0xf bank_mask:0xa
	v_add_f32_dpp v16, v140, v140 quad_perm:[1,0,3,2] row_mask:0xf bank_mask:0xf
	v_add_f32_dpp v17, v141, v141 quad_perm:[1,0,3,2] row_mask:0xf bank_mask:0xf
	v_add_f32_dpp v18, v142, v142 quad_perm:[1,0,3,2] row_mask:0xf bank_mask:0xf
	v_add_f32_dpp v19, v143, v143 quad_perm:[1,0,3,2] row_mask:0xf bank_mask:0xf
	v_cndmask_b32_e32 v16, v18, v16, vcc
	v_cndmask_b32_e32 v17, v19, v17, vcc
	v_add_f32_dpp v22, v20, v20 quad_perm:[2,3,0,1] row_mask:0xf bank_mask:0xf
	v_add_f32_dpp v23, v21, v21 quad_perm:[2,3,0,1] row_mask:0xf bank_mask:0xf
	v_cndmask_b32_e64 v20, v23, v22, s[4:5]
	s_waitcnt vmcnt(2)
	v_pk_mul_f32 v[140:141], v[236:237], v[8:9] op_sel_hi:[1,0]
	v_pk_mul_f32 v[142:143], v[244:245], v[8:9] op_sel_hi:[1,0]
	v_pk_fma_f32 v[140:141], v[238:239], v[8:9], v[140:141] op_sel:[0,1,0]
	v_pk_fma_f32 v[142:143], v[246:247], v[8:9], v[142:143] op_sel:[0,1,0]
	v_pk_fma_f32 v[140:141], v[240:241], v[10:11], v[140:141] op_sel_hi:[1,0,1]
	v_pk_fma_f32 v[142:143], v[248:249], v[10:11], v[142:143] op_sel_hi:[1,0,1]
	v_pk_fma_f32 v[140:141], v[242:243], v[10:11], v[140:141] op_sel:[0,1,0]
	v_pk_fma_f32 v[142:143], v[250:251], v[10:11], v[142:143] op_sel:[0,1,0]
	v_add_f32_dpp v12, v252, v252 quad_perm:[1,0,3,2] row_mask:0xf bank_mask:0xf
	v_add_f32_dpp v13, v253, v253 quad_perm:[1,0,3,2] row_mask:0xf bank_mask:0xf
	v_add_f32_dpp v14, v254, v254 quad_perm:[1,0,3,2] row_mask:0xf bank_mask:0xf
	v_add_f32_dpp v15, v255, v255 quad_perm:[1,0,3,2] row_mask:0xf bank_mask:0xf
	v_cndmask_b32_e32 v12, v14, v12, vcc
	v_cndmask_b32_e32 v13, v15, v13, vcc
	v_add_f32_dpp v18, v16, v16 quad_perm:[2,3,0,1] row_mask:0xf bank_mask:0xf
	v_add_f32_dpp v19, v17, v17 quad_perm:[2,3,0,1] row_mask:0xf bank_mask:0xf
	v_cndmask_b32_e64 v16, v19, v18, s[4:5]
	s_waitcnt vmcnt(1)
	v_pk_mul_f32 v[252:253], v[236:237], v[4:5] op_sel_hi:[1,0]
	v_pk_mul_f32 v[254:255], v[244:245], v[4:5] op_sel_hi:[1,0]
	v_pk_fma_f32 v[252:253], v[238:239], v[4:5], v[252:253] op_sel:[0,1,0]
	v_pk_fma_f32 v[254:255], v[246:247], v[4:5], v[254:255] op_sel:[0,1,0]
	v_pk_fma_f32 v[252:253], v[240:241], v[6:7], v[252:253] op_sel_hi:[1,0,1]
	v_pk_fma_f32 v[254:255], v[248:249], v[6:7], v[254:255] op_sel_hi:[1,0,1]
	v_pk_fma_f32 v[252:253], v[242:243], v[6:7], v[252:253] op_sel:[0,1,0]
	v_pk_fma_f32 v[254:255], v[250:251], v[6:7], v[254:255] op_sel:[0,1,0]
	v_add_f32_dpp v20, v20, v20 row_ror:4 row_mask:0xf bank_mask:0x5
	v_add_f32_dpp v20, v16, v16 row_ror:4 row_mask:0xf bank_mask:0xa
	v_add_f32_dpp v8, v140, v140 quad_perm:[1,0,3,2] row_mask:0xf bank_mask:0xf
	v_add_f32_dpp v9, v141, v141 quad_perm:[1,0,3,2] row_mask:0xf bank_mask:0xf
	v_add_f32_dpp v10, v142, v142 quad_perm:[1,0,3,2] row_mask:0xf bank_mask:0xf
	v_add_f32_dpp v11, v143, v143 quad_perm:[1,0,3,2] row_mask:0xf bank_mask:0xf
	v_cndmask_b32_e32 v8, v10, v8, vcc
	v_cndmask_b32_e32 v9, v11, v9, vcc
	v_add_f32_dpp v14, v12, v12 quad_perm:[2,3,0,1] row_mask:0xf bank_mask:0xf
	v_add_f32_dpp v15, v13, v13 quad_perm:[2,3,0,1] row_mask:0xf bank_mask:0xf
	v_cndmask_b32_e64 v12, v15, v14, s[4:5]
	s_waitcnt vmcnt(0)
	v_pk_mul_f32 v[140:141], v[236:237], v[0:1] op_sel_hi:[1,0]
	v_pk_mul_f32 v[142:143], v[244:245], v[0:1] op_sel_hi:[1,0]
	v_pk_fma_f32 v[140:141], v[238:239], v[0:1], v[140:141] op_sel:[0,1,0]
	v_pk_fma_f32 v[142:143], v[246:247], v[0:1], v[142:143] op_sel:[0,1,0]
	v_pk_fma_f32 v[140:141], v[240:241], v[2:3], v[140:141] op_sel_hi:[1,0,1]
	v_pk_fma_f32 v[142:143], v[248:249], v[2:3], v[142:143] op_sel_hi:[1,0,1]
	v_pk_fma_f32 v[140:141], v[242:243], v[2:3], v[140:141] op_sel:[0,1,0]
	v_pk_fma_f32 v[142:143], v[250:251], v[2:3], v[142:143] op_sel:[0,1,0]
	v_add_f32_dpp v28, v28, v28 row_ror:8 row_mask:0xf bank_mask:0x3
	v_add_f32_dpp v28, v20, v20 row_ror:8 row_mask:0xf bank_mask:0xc
	v_add_f32_dpp v4, v252, v252 quad_perm:[1,0,3,2] row_mask:0xf bank_mask:0xf
	v_add_f32_dpp v5, v253, v253 quad_perm:[1,0,3,2] row_mask:0xf bank_mask:0xf
	v_add_f32_dpp v6, v254, v254 quad_perm:[1,0,3,2] row_mask:0xf bank_mask:0xf
	v_add_f32_dpp v7, v255, v255 quad_perm:[1,0,3,2] row_mask:0xf bank_mask:0xf
	v_cndmask_b32_e32 v4, v6, v4, vcc
	v_cndmask_b32_e32 v5, v7, v5, vcc
	v_add_f32_dpp v10, v8, v8 quad_perm:[2,3,0,1] row_mask:0xf bank_mask:0xf
	v_add_f32_dpp v11, v9, v9 quad_perm:[2,3,0,1] row_mask:0xf bank_mask:0xf
	v_cndmask_b32_e64 v8, v11, v10, s[4:5]
	v_add_f32_dpp v12, v12, v12 row_ror:4 row_mask:0xf bank_mask:0x5
	s_nop 0
	v_add_f32_dpp v12, v8, v8 row_ror:4 row_mask:0xf bank_mask:0xa
	v_add_f32_dpp v0, v140, v140 quad_perm:[1,0,3,2] row_mask:0xf bank_mask:0xf
	v_add_f32_dpp v1, v141, v141 quad_perm:[1,0,3,2] row_mask:0xf bank_mask:0xf
	v_add_f32_dpp v2, v142, v142 quad_perm:[1,0,3,2] row_mask:0xf bank_mask:0xf
	v_add_f32_dpp v3, v143, v143 quad_perm:[1,0,3,2] row_mask:0xf bank_mask:0xf
	v_cndmask_b32_e32 v0, v2, v0, vcc
	v_cndmask_b32_e32 v1, v3, v1, vcc
	v_add_f32_dpp v6, v4, v4 quad_perm:[2,3,0,1] row_mask:0xf bank_mask:0xf
	v_add_f32_dpp v7, v5, v5 quad_perm:[2,3,0,1] row_mask:0xf bank_mask:0xf
	v_cndmask_b32_e64 v4, v7, v6, s[4:5]
	v_add_f32_dpp v2, v0, v0 quad_perm:[2,3,0,1] row_mask:0xf bank_mask:0xf
	v_add_f32_dpp v3, v1, v1 quad_perm:[2,3,0,1] row_mask:0xf bank_mask:0xf
	v_cndmask_b32_e64 v0, v3, v2, s[4:5]
	v_add_f32_dpp v4, v4, v4 row_ror:4 row_mask:0xf bank_mask:0x5
	s_nop 0
	v_add_f32_dpp v4, v0, v0 row_ror:4 row_mask:0xf bank_mask:0xa
	v_add_f32_dpp v12, v12, v12 row_ror:8 row_mask:0xf bank_mask:0x3
	s_nop 0
	v_add_f32_dpp v12, v4, v4 row_ror:8 row_mask:0xf bank_mask:0xc
	s_nop 1
	v_permlane16_swap_b32_e32 v28, v12
	v_add_f32_e32 v28, v28, v12
	s_nop 1
	v_permlane32_swap_b32_e32 v60, v28
	v_add_f32_e32 v60, v60, v28
	ds_write_b32 v235, v60 offset:64
	v_lshlrev_b32_e32 v2, 2, v223
	s_add_u32 s4, s14, s28
	s_addc_u32 s5, s15, s29
	v_lshlrev_b32_e32 v0, 2, v2
	s_waitcnt lgkmcnt(0)
; DI void lbar() { asm volatile("s_waitcnt lgkmcnt(0)" ::: "memory"); __builtin_amdgcn_s_barrier(); asm volatile("" ::: "memory"); }
; DI float wave_sum(float v) { for (int o = 32; o >= 1; o >>= 1) v += __shfl_xor(v, o); return v; }
; DI void attn_sample_item(const Params& p, int item, ldsp lds, int tid_) {
;     ...
;   for (int j = 0; j < 16; ++j) vvA[j] = __builtin_nontemporal_load((const f32x4*)(cv + (size_t)(wid * 32 + j) * 1024 + lane * 4));
;   lbar();
;   if (wid < 4) {
;     float v[4]; float mx = -1e30f;
; #pragma unroll
;     for (int j = 0; j < 4; ++j) { v[j] = SC[wid * 256 + j * 64 + lane]; mx = fmaxf(mx, v[j]); }
;     for (int o = 32; o >= 1; o >>= 1) mx = fmaxf(mx, __shfl_xor(mx, o));
;     float s = 0.f;
; #pragma unroll
;     for (int j = 0; j < 4; ++j) { v[j] = __expf(v[j] - mx); s += v[j]; }
;     s = wave_sum(s); const float inv = 1.f / s;
; #pragma unroll
;     for (int j = 0; j < 4; ++j) SC[wid * 256 + j * 64 + lane] = v[j] * inv;
	v_mov_b32_e32 v1, v145
	v_lshl_add_u64 v[0:1], s[4:5], 0, v[0:1]
	v_lshl_add_u64 v[4:5], v[0:1], 0, v[158:159]
	v_lshl_add_u64 v[6:7], v[0:1], 0, v[162:163]
	global_load_dwordx4 v[100:103], v[4:5], off nt
	global_load_dwordx4 v[92:95], v[6:7], off nt
	v_lshl_add_u64 v[4:5], v[0:1], 0, v[164:165]
	v_lshl_add_u64 v[6:7], v[0:1], 0, v[168:169]
	global_load_dwordx4 v[112:115], v[4:5], off nt
	global_load_dwordx4 v[108:111], v[6:7], off nt
	v_lshl_add_u64 v[4:5], v[0:1], 0, v[172:173]
	v_lshl_add_u64 v[6:7], v[0:1], 0, v[176:177]
	global_load_dwordx4 v[120:123], v[4:5], off nt
	global_load_dwordx4 v[116:119], v[6:7], off nt
	v_lshl_add_u64 v[4:5], v[0:1], 0, v[180:181]
	v_lshl_add_u64 v[6:7], v[0:1], 0, v[184:185]
	global_load_dwordx4 v[124:127], v[4:5], off nt
	global_load_dwordx4 v[104:107], v[6:7], off nt
	v_lshl_add_u64 v[4:5], v[0:1], 0, v[188:189]
	v_lshl_add_u64 v[6:7], v[0:1], 0, v[192:193]
	global_load_dwordx4 v[68:71], v[4:5], off nt
	global_load_dwordx4 v[64:67], v[6:7], off nt
	v_lshl_add_u64 v[4:5], v[0:1], 0, v[196:197]
	v_lshl_add_u64 v[6:7], v[0:1], 0, v[200:201]
	global_load_dwordx4 v[80:83], v[4:5], off nt
	global_load_dwordx4 v[76:79], v[6:7], off nt
	v_lshl_add_u64 v[4:5], v[0:1], 0, v[202:203]
	v_lshl_add_u64 v[6:7], v[0:1], 0, v[204:205]
	global_load_dwordx4 v[88:91], v[4:5], off nt
	global_load_dwordx4 v[84:87], v[6:7], off nt
	v_lshl_add_u64 v[4:5], v[0:1], 0, v[206:207]
	v_lshl_add_u64 v[6:7], v[0:1], 0, v[208:209]
	global_load_dwordx4 v[96:99], v[4:5], off nt
	global_load_dwordx4 v[72:75], v[6:7], off nt
	s_waitcnt lgkmcnt(0)
	s_barrier
	v_cmp_gt_i32_e32 vcc, 4, v210
	s_and_saveexec_b64 s[4:5], vcc
	s_cbranch_execz .LBB0_1675
	v_lshlrev_b32_e32 v3, 10, v210
	v_add3_u32 v6, 16, v3, v2
	ds_read2st64_b32 v[2:3], v6 offset1:1
	ds_read2st64_b32 v[4:5], v6 offset0:2 offset1:3
	s_waitcnt lgkmcnt(1)
	v_max3_f32 v7, v2, s35, v3
	s_waitcnt lgkmcnt(0)
	v_max3_f32 v7, v7, v4, v5
	ds_bpermute_b32 v8, v133, v7
	s_waitcnt lgkmcnt(0)
	v_max_f32_e32 v8, v8, v8
	v_max_f32_e32 v7, v7, v8
	ds_bpermute_b32 v8, v132, v7
	s_waitcnt lgkmcnt(0)
	v_max_f32_e32 v8, v8, v8
	v_max_f32_e32 v7, v7, v8
	ds_bpermute_b32 v8, v131, v7
	s_waitcnt lgkmcnt(0)
	v_max_f32_e32 v8, v8, v8
	v_max_f32_e32 v7, v7, v8
	ds_bpermute_b32 v8, v130, v7
	s_waitcnt lgkmcnt(0)
	v_max_f32_e32 v8, v8, v8
	v_max_f32_e32 v7, v7, v8
	ds_bpermute_b32 v8, v129, v7
	s_waitcnt lgkmcnt(0)
	v_max_f32_e32 v8, v8, v8
	v_max_f32_e32 v7, v7, v8
	ds_bpermute_b32 v8, v128, v7
	s_waitcnt lgkmcnt(0)
	v_max_f32_e32 v8, v8, v8
	v_max_f32_e32 v7, v7, v8
	v_sub_f32_e32 v2, v2, v7
	v_sub_f32_e32 v3, v3, v7
	v_mul_f32_e32 v2, 0x3fb8aa3b, v2
	v_sub_f32_e32 v4, v4, v7
	v_mul_f32_e32 v3, 0x3fb8aa3b, v3
	v_exp_f32_e32 v2, v2
	v_sub_f32_e32 v5, v5, v7
	v_mul_f32_e32 v4, 0x3fb8aa3b, v4
	v_exp_f32_e32 v3, v3
	v_mul_f32_e32 v5, 0x3fb8aa3b, v5
	v_exp_f32_e32 v4, v4
	v_exp_f32_e32 v5, v5
	v_add_f32_e32 v7, 0, v2
	v_add_f32_e32 v7, v3, v7
	v_add_f32_e32 v7, v4, v7
	v_add_f32_e32 v7, v5, v7
	ds_bpermute_b32 v8, v133, v7
	s_waitcnt lgkmcnt(0)
	v_add_f32_e32 v7, v7, v8
	ds_bpermute_b32 v8, v132, v7
	s_waitcnt lgkmcnt(0)
	v_add_f32_e32 v7, v7, v8
	ds_bpermute_b32 v8, v131, v7
	s_waitcnt lgkmcnt(0)
	v_add_f32_e32 v7, v7, v8
	ds_bpermute_b32 v8, v130, v7
	s_waitcnt lgkmcnt(0)
	v_add_f32_e32 v7, v7, v8
	ds_bpermute_b32 v8, v129, v7
	s_waitcnt lgkmcnt(0)
	v_add_f32_e32 v7, v7, v8
	ds_bpermute_b32 v8, v128, v7
	s_waitcnt lgkmcnt(0)
	v_add_f32_e32 v7, v7, v8
	v_div_scale_f32 v8, s[6:7], v7, v7, 1.0
	v_rcp_f32_e32 v9, v8
	v_div_scale_f32 v10, vcc, 1.0, v7, 1.0
	v_fma_f32 v11, -v8, v9, 1.0
	v_fmac_f32_e32 v9, v11, v9
	v_mul_f32_e32 v11, v10, v9
	v_fma_f32 v12, -v8, v11, v10
	v_fmac_f32_e32 v11, v12, v9
	v_fma_f32 v8, -v8, v11, v10
	v_div_fmas_f32 v8, v8, v9, v11
	v_div_fixup_f32 v7, v8, v7, 1.0
	v_mul_f32_e32 v2, v2, v7
	v_mul_f32_e32 v3, v3, v7
	v_mul_f32_e32 v4, v4, v7
	v_mul_f32_e32 v5, v5, v7
	ds_write2st64_b32 v6, v2, v3 offset1:1
	ds_write2st64_b32 v6, v4, v5 offset0:2 offset1:3
	s_branch .LBB0_1675
